# LN rewrite + 16B H stores (lane-pair exchange), 16B MERGED write-through stores (permlane16_swap), conv pass rewritten: taps hoisted, 2-deep counted prefetch
# speedup vs baseline: 1.0319x; 1.0280x over previous
.LBB0_77:
	s_mov_b64 s[10:11], 0
	s_mov_b64 s[18:19], -1
	s_mov_b64 s[16:17], 0
	s_cmp_lt_i32 s2, 1
	s_mov_b64 s[0:1], 0
	s_cbranch_scc1 .LBB0_86
	s_cmp_eq_u32 s2, 1
	s_mov_b64 s[0:1], -1
	s_cbranch_scc0 .LBB0_85
	s_waitcnt vmcnt(0)
	v_readlane_b32 s2, v254, 38
	v_lshrrev_b32_e32 v146, 6, v221
	v_and_b32_e32 v112, 63, v221
	v_mov_b32_e32 v152, 0x800000
	v_mov_b32_e32 v153, 0
	v_mov_b32_e32 v154, 0x400000
	v_mov_b32_e32 v155, 0
	v_mov_b32_e32 v156, 0x3000
	v_mov_b32_e32 v157, 0
	v_add_u32_e32 v146, s2, v146
	v_lshlrev_b32_e32 v148, 4, v112
	v_mov_b32_e32 v149, 0
	v_lshlrev_b32_e32 v150, 3, v112
	v_mov_b32_e32 v151, 0
	v_lshl_add_u32 v140, v146, 12, v148
	v_mov_b32_e32 v141, 0
	v_mov_b32_e32 v142, 0xba800000
	s_mov_b32 s0, 0
	v_add_u32_e32 v114, 0x1000, v148
	v_mov_b32_e32 v115, 0
	v_lshl_add_u64 v[134:135], s[60:61], 0, v[114:115]
	v_and_b32_e32 v116, 1, v112
	v_cmp_eq_u32_e64 s[40:41], 1, v116
	v_lshlrev_b32_e32 v114, 3, v112
	v_mov_b32_e32 v117, 0x1f8
	v_cndmask_b32_e64 v117, 0, v117, s[40:41]
	v_add_u32_e32 v114, v114, v117
	v_lshl_add_u32 v114, v146, 11, v114
	s_add_u32 s18, s60, 0x3100000
	s_addc_u32 s19, s61, 0
	v_lshl_add_u64 v[132:133], s[18:19], 0, v[114:115]
	v_lshl_add_u64 v[128:129], s[68:69], 0, v[140:141]
	global_load_dwordx4 v[0:3], v[128:129], off nt
	global_load_dwordx4 v[4:7], v[128:129], off offset:1024 nt
	global_load_dwordx4 v[8:11], v[128:129], off offset:2048 nt
	global_load_dwordx4 v[12:15], v[128:129], off offset:3072 nt
	v_lshl_add_u64 v[128:129], v[128:129], 0, v[152:153]
	global_load_dword v158, v[134:135], off
	global_load_dword v158, v[134:135], off
	global_load_dwordx4 v[16:19], v[128:129], off nt
	global_load_dwordx4 v[20:23], v[128:129], off offset:1024 nt
	global_load_dwordx4 v[24:27], v[128:129], off offset:2048 nt
	global_load_dwordx4 v[28:31], v[128:129], off offset:3072 nt
	v_lshl_add_u64 v[128:129], s[70:71], 0, v[140:141]
	global_load_dword v158, v[134:135], off
	global_load_dword v158, v[134:135], off
.Lln0_loop:
	global_load_dwordx4 v[48:51], v[134:135], off offset:-4096
	global_load_dwordx4 v[52:55], v[134:135], off offset:-3072
	global_load_dwordx4 v[56:59], v[134:135], off offset:-2048
	global_load_dwordx4 v[60:63], v[134:135], off offset:-1024
	global_load_dwordx4 v[64:67], v[134:135], off
	global_load_dwordx4 v[68:71], v[134:135], off offset:1024
	global_load_dwordx4 v[72:75], v[134:135], off offset:2048
	global_load_dwordx4 v[76:79], v[134:135], off offset:3072
	v_lshl_add_u64 v[134:135], v[134:135], 0, v[156:157]
	global_load_dwordx4 v[32:35], v[128:129], off nt
	global_load_dwordx4 v[36:39], v[128:129], off offset:1024 nt
	global_load_dwordx4 v[40:43], v[128:129], off offset:2048 nt
	global_load_dwordx4 v[44:47], v[128:129], off offset:3072 nt
	v_lshl_add_u64 v[128:129], v[128:129], 0, v[152:153]
	s_waitcnt vmcnt(20)
	v_add_f32_e32 v112, v0, v1
	v_add_f32_e32 v113, v2, v3
	v_add_f32_e32 v114, v4, v5
	v_add_f32_e32 v115, v6, v7
	v_add_f32_e32 v116, v8, v9
	v_add_f32_e32 v117, v10, v11
	v_add_f32_e32 v118, v12, v13
	v_add_f32_e32 v119, v14, v15
	v_add_f32_e32 v112, v112, v116
	v_add_f32_e32 v113, v113, v117
	v_add_f32_e32 v114, v114, v118
	v_add_f32_e32 v115, v115, v119
	v_add_f32_e32 v112, v112, v113
	v_add_f32_e32 v114, v114, v115
	v_add_f32_e32 v112, v112, v114
	s_nop 1
	v_add_f32_dpp v112, v112, v112 quad_perm:[1,0,3,2] row_mask:0xf bank_mask:0xf
	s_nop 1
	v_add_f32_dpp v112, v112, v112 quad_perm:[2,3,0,1] row_mask:0xf bank_mask:0xf
	s_nop 1
	v_add_f32_dpp v112, v112, v112 row_half_mirror row_mask:0xf bank_mask:0xf
	s_nop 1
	v_add_f32_dpp v112, v112, v112 row_mirror row_mask:0xf bank_mask:0xf
	s_nop 1
	v_add_f32_dpp v112, v112, v112 row_bcast:15 row_mask:0xa bank_mask:0xf
	s_nop 1
	v_add_f32_dpp v112, v112, v112 row_bcast:31 row_mask:0xc bank_mask:0xf
	s_nop 1
	v_readlane_b32 s2, v112, 63
	s_nop 1
	v_fmac_f32_e32 v0, s2, v142
	v_fmac_f32_e32 v1, s2, v142
	v_fmac_f32_e32 v2, s2, v142
	v_fmac_f32_e32 v3, s2, v142
	v_fmac_f32_e32 v4, s2, v142
	v_fmac_f32_e32 v5, s2, v142
	v_fmac_f32_e32 v6, s2, v142
	v_fmac_f32_e32 v7, s2, v142
	v_fmac_f32_e32 v8, s2, v142
	v_fmac_f32_e32 v9, s2, v142
	v_fmac_f32_e32 v10, s2, v142
	v_fmac_f32_e32 v11, s2, v142
	v_fmac_f32_e32 v12, s2, v142
	v_fmac_f32_e32 v13, s2, v142
	v_fmac_f32_e32 v14, s2, v142
	v_fmac_f32_e32 v15, s2, v142
	v_mul_f32_e32 v112, v0, v0
	v_mul_f32_e32 v113, v1, v1
	v_mul_f32_e32 v114, v2, v2
	v_mul_f32_e32 v115, v3, v3
	v_fmac_f32_e32 v112, v4, v4
	v_fmac_f32_e32 v113, v5, v5
	v_fmac_f32_e32 v114, v6, v6
	v_fmac_f32_e32 v115, v7, v7
	v_fmac_f32_e32 v112, v8, v8
	v_fmac_f32_e32 v113, v9, v9
	v_fmac_f32_e32 v114, v10, v10
	v_fmac_f32_e32 v115, v11, v11
	v_fmac_f32_e32 v112, v12, v12
	v_fmac_f32_e32 v113, v13, v13
	v_fmac_f32_e32 v114, v14, v14
	v_fmac_f32_e32 v115, v15, v15
	v_add_f32_e32 v112, v112, v113
	v_add_f32_e32 v114, v114, v115
	v_add_f32_e32 v112, v112, v114
	s_nop 1
	v_add_f32_dpp v112, v112, v112 quad_perm:[1,0,3,2] row_mask:0xf bank_mask:0xf
	s_nop 1
	v_add_f32_dpp v112, v112, v112 quad_perm:[2,3,0,1] row_mask:0xf bank_mask:0xf
	s_nop 1
	v_add_f32_dpp v112, v112, v112 row_half_mirror row_mask:0xf bank_mask:0xf
	s_nop 1
	v_add_f32_dpp v112, v112, v112 row_mirror row_mask:0xf bank_mask:0xf
	s_nop 1
	v_add_f32_dpp v112, v112, v112 row_bcast:15 row_mask:0xa bank_mask:0xf
	s_nop 1
	v_add_f32_dpp v112, v112, v112 row_bcast:31 row_mask:0xc bank_mask:0xf
	s_nop 1
	v_readlane_b32 s2, v112, 63
	s_nop 1
	v_mov_b32_e32 v113, 0x358637bd
	v_mov_b32_e32 v114, 0x3a800000
	v_fmac_f32_e32 v113, s2, v114
	v_rsq_f32_e32 v115, v113
	v_mul_f32_e32 v113, 0.5, v113
	v_mul_f32_e32 v116, v115, v115
	v_mov_b32_e32 v117, 0x3fc00000
	v_fma_f32 v116, -v113, v116, v117
	v_mul_f32_e32 v144, v115, v116
	v_pk_mul_f32 v[0:1], v[0:1], v[144:145] op_sel_hi:[1,0]
	v_pk_mul_f32 v[2:3], v[2:3], v[144:145] op_sel_hi:[1,0]
	v_pk_mul_f32 v[4:5], v[4:5], v[144:145] op_sel_hi:[1,0]
	v_pk_mul_f32 v[6:7], v[6:7], v[144:145] op_sel_hi:[1,0]
	v_pk_mul_f32 v[8:9], v[8:9], v[144:145] op_sel_hi:[1,0]
	v_pk_mul_f32 v[10:11], v[10:11], v[144:145] op_sel_hi:[1,0]
	v_pk_mul_f32 v[12:13], v[12:13], v[144:145] op_sel_hi:[1,0]
	v_pk_mul_f32 v[14:15], v[14:15], v[144:145] op_sel_hi:[1,0]
	s_waitcnt vmcnt(4)
	v_pk_add_f32 v[64:65], v[64:65], 1.0 op_sel_hi:[1,0]
	v_pk_add_f32 v[66:67], v[66:67], 1.0 op_sel_hi:[1,0]
	v_pk_add_f32 v[68:69], v[68:69], 1.0 op_sel_hi:[1,0]
	v_pk_add_f32 v[70:71], v[70:71], 1.0 op_sel_hi:[1,0]
	v_pk_add_f32 v[72:73], v[72:73], 1.0 op_sel_hi:[1,0]
	v_pk_add_f32 v[74:75], v[74:75], 1.0 op_sel_hi:[1,0]
	v_pk_add_f32 v[76:77], v[76:77], 1.0 op_sel_hi:[1,0]
	v_pk_add_f32 v[78:79], v[78:79], 1.0 op_sel_hi:[1,0]
	v_pk_fma_f32 v[0:1], v[64:65], v[0:1], v[48:49]
	v_pk_fma_f32 v[2:3], v[66:67], v[2:3], v[50:51]
	v_pk_fma_f32 v[4:5], v[68:69], v[4:5], v[52:53]
	v_pk_fma_f32 v[6:7], v[70:71], v[6:7], v[54:55]
	v_pk_fma_f32 v[8:9], v[72:73], v[8:9], v[56:57]
	v_pk_fma_f32 v[10:11], v[74:75], v[10:11], v[58:59]
	v_pk_fma_f32 v[12:13], v[76:77], v[12:13], v[60:61]
	v_pk_fma_f32 v[14:15], v[78:79], v[14:15], v[62:63]
	v_cvt_pk_bf16_f32 v120, v0, v1
	v_cvt_pk_bf16_f32 v121, v2, v3
	v_cvt_pk_bf16_f32 v122, v4, v5
	v_cvt_pk_bf16_f32 v123, v6, v7
	v_cvt_pk_bf16_f32 v124, v8, v9
	v_cvt_pk_bf16_f32 v125, v10, v11
	v_cvt_pk_bf16_f32 v126, v12, v13
	v_cvt_pk_bf16_f32 v127, v14, v15
	v_cndmask_b32_e64 v112, v122, v120, s[40:41]
	v_cndmask_b32_e64 v113, v123, v121, s[40:41]
	v_cndmask_b32_e64 v114, v126, v124, s[40:41]
	v_cndmask_b32_e64 v115, v127, v125, s[40:41]
	v_mov_b32_dpp v116, v112 quad_perm:[1,0,3,2] row_mask:0xf bank_mask:0xf
	v_mov_b32_dpp v117, v113 quad_perm:[1,0,3,2] row_mask:0xf bank_mask:0xf
	v_mov_b32_dpp v118, v114 quad_perm:[1,0,3,2] row_mask:0xf bank_mask:0xf
	v_mov_b32_dpp v119, v115 quad_perm:[1,0,3,2] row_mask:0xf bank_mask:0xf
	s_nop 0
	v_cndmask_b32_e64 v160, v120, v116, s[40:41]
	v_cndmask_b32_e64 v161, v121, v117, s[40:41]
	v_cndmask_b32_e64 v162, v116, v122, s[40:41]
	v_cndmask_b32_e64 v163, v117, v123, s[40:41]
	v_cndmask_b32_e64 v164, v124, v118, s[40:41]
	v_cndmask_b32_e64 v165, v125, v119, s[40:41]
	v_cndmask_b32_e64 v166, v118, v126, s[40:41]
	v_cndmask_b32_e64 v167, v119, v127, s[40:41]
	global_store_dwordx4 v[132:133], v[160:163], off
	global_store_dwordx4 v[132:133], v[164:167], off offset:1024
	v_lshl_add_u64 v[132:133], v[132:133], 0, v[154:155]
	global_load_dwordx4 v[0:3], v[128:129], off nt
	global_load_dwordx4 v[4:7], v[128:129], off offset:1024 nt
	global_load_dwordx4 v[8:11], v[128:129], off offset:2048 nt
	global_load_dwordx4 v[12:15], v[128:129], off offset:3072 nt
	v_lshl_add_u64 v[128:129], v[128:129], 0, v[152:153]
	v_add_f32_e32 v112, v16, v17
	v_add_f32_e32 v113, v18, v19
	v_add_f32_e32 v114, v20, v21
	v_add_f32_e32 v115, v22, v23
	v_add_f32_e32 v116, v24, v25
	v_add_f32_e32 v117, v26, v27
	v_add_f32_e32 v118, v28, v29
	v_add_f32_e32 v119, v30, v31
	v_add_f32_e32 v112, v112, v116
	v_add_f32_e32 v113, v113, v117
	v_add_f32_e32 v114, v114, v118
	v_add_f32_e32 v115, v115, v119
	v_add_f32_e32 v112, v112, v113
	v_add_f32_e32 v114, v114, v115
	v_add_f32_e32 v112, v112, v114
	s_nop 1
	v_add_f32_dpp v112, v112, v112 quad_perm:[1,0,3,2] row_mask:0xf bank_mask:0xf
	s_nop 1
	v_add_f32_dpp v112, v112, v112 quad_perm:[2,3,0,1] row_mask:0xf bank_mask:0xf
	s_nop 1
	v_add_f32_dpp v112, v112, v112 row_half_mirror row_mask:0xf bank_mask:0xf
	s_nop 1
	v_add_f32_dpp v112, v112, v112 row_mirror row_mask:0xf bank_mask:0xf
	s_nop 1
	v_add_f32_dpp v112, v112, v112 row_bcast:15 row_mask:0xa bank_mask:0xf
	s_nop 1
	v_add_f32_dpp v112, v112, v112 row_bcast:31 row_mask:0xc bank_mask:0xf
	s_nop 1
	v_readlane_b32 s2, v112, 63
	s_nop 1
	v_fmac_f32_e32 v16, s2, v142
	v_fmac_f32_e32 v17, s2, v142
	v_fmac_f32_e32 v18, s2, v142
	v_fmac_f32_e32 v19, s2, v142
	v_fmac_f32_e32 v20, s2, v142
	v_fmac_f32_e32 v21, s2, v142
	v_fmac_f32_e32 v22, s2, v142
	v_fmac_f32_e32 v23, s2, v142
	v_fmac_f32_e32 v24, s2, v142
	v_fmac_f32_e32 v25, s2, v142
	v_fmac_f32_e32 v26, s2, v142
	v_fmac_f32_e32 v27, s2, v142
	v_fmac_f32_e32 v28, s2, v142
	v_fmac_f32_e32 v29, s2, v142
	v_fmac_f32_e32 v30, s2, v142
	v_fmac_f32_e32 v31, s2, v142
	v_mul_f32_e32 v112, v16, v16
	v_mul_f32_e32 v113, v17, v17
	v_mul_f32_e32 v114, v18, v18
	v_mul_f32_e32 v115, v19, v19
	v_fmac_f32_e32 v112, v20, v20
	v_fmac_f32_e32 v113, v21, v21
	v_fmac_f32_e32 v114, v22, v22
	v_fmac_f32_e32 v115, v23, v23
	v_fmac_f32_e32 v112, v24, v24
	v_fmac_f32_e32 v113, v25, v25
	v_fmac_f32_e32 v114, v26, v26
	v_fmac_f32_e32 v115, v27, v27
	v_fmac_f32_e32 v112, v28, v28
	v_fmac_f32_e32 v113, v29, v29
	v_fmac_f32_e32 v114, v30, v30
	v_fmac_f32_e32 v115, v31, v31
	v_add_f32_e32 v112, v112, v113
	v_add_f32_e32 v114, v114, v115
	v_add_f32_e32 v112, v112, v114
	s_nop 1
	v_add_f32_dpp v112, v112, v112 quad_perm:[1,0,3,2] row_mask:0xf bank_mask:0xf
	s_nop 1
	v_add_f32_dpp v112, v112, v112 quad_perm:[2,3,0,1] row_mask:0xf bank_mask:0xf
	s_nop 1
	v_add_f32_dpp v112, v112, v112 row_half_mirror row_mask:0xf bank_mask:0xf
	s_nop 1
	v_add_f32_dpp v112, v112, v112 row_mirror row_mask:0xf bank_mask:0xf
	s_nop 1
	v_add_f32_dpp v112, v112, v112 row_bcast:15 row_mask:0xa bank_mask:0xf
	s_nop 1
	v_add_f32_dpp v112, v112, v112 row_bcast:31 row_mask:0xc bank_mask:0xf
	s_nop 1
	v_readlane_b32 s2, v112, 63
	s_nop 1
	v_mov_b32_e32 v113, 0x358637bd
	v_mov_b32_e32 v114, 0x3a800000
	v_fmac_f32_e32 v113, s2, v114
	v_rsq_f32_e32 v115, v113
	v_mul_f32_e32 v113, 0.5, v113
	v_mul_f32_e32 v116, v115, v115
	v_mov_b32_e32 v117, 0x3fc00000
	v_fma_f32 v116, -v113, v116, v117
	v_mul_f32_e32 v144, v115, v116
	v_pk_mul_f32 v[16:17], v[16:17], v[144:145] op_sel_hi:[1,0]
	v_pk_mul_f32 v[18:19], v[18:19], v[144:145] op_sel_hi:[1,0]
	v_pk_mul_f32 v[20:21], v[20:21], v[144:145] op_sel_hi:[1,0]
	v_pk_mul_f32 v[22:23], v[22:23], v[144:145] op_sel_hi:[1,0]
	v_pk_mul_f32 v[24:25], v[24:25], v[144:145] op_sel_hi:[1,0]
	v_pk_mul_f32 v[26:27], v[26:27], v[144:145] op_sel_hi:[1,0]
	v_pk_mul_f32 v[28:29], v[28:29], v[144:145] op_sel_hi:[1,0]
	v_pk_mul_f32 v[30:31], v[30:31], v[144:145] op_sel_hi:[1,0]
	v_pk_fma_f32 v[16:17], v[64:65], v[16:17], v[48:49]
	v_pk_fma_f32 v[18:19], v[66:67], v[18:19], v[50:51]
	v_pk_fma_f32 v[20:21], v[68:69], v[20:21], v[52:53]
	v_pk_fma_f32 v[22:23], v[70:71], v[22:23], v[54:55]
	v_pk_fma_f32 v[24:25], v[72:73], v[24:25], v[56:57]
	v_pk_fma_f32 v[26:27], v[74:75], v[26:27], v[58:59]
	v_pk_fma_f32 v[28:29], v[76:77], v[28:29], v[60:61]
	v_pk_fma_f32 v[30:31], v[78:79], v[30:31], v[62:63]
	v_cvt_pk_bf16_f32 v120, v16, v17
	v_cvt_pk_bf16_f32 v121, v18, v19
	v_cvt_pk_bf16_f32 v122, v20, v21
	v_cvt_pk_bf16_f32 v123, v22, v23
	v_cvt_pk_bf16_f32 v124, v24, v25
	v_cvt_pk_bf16_f32 v125, v26, v27
	v_cvt_pk_bf16_f32 v126, v28, v29
	v_cvt_pk_bf16_f32 v127, v30, v31
	v_cndmask_b32_e64 v112, v122, v120, s[40:41]
	v_cndmask_b32_e64 v113, v123, v121, s[40:41]
	v_cndmask_b32_e64 v114, v126, v124, s[40:41]
	v_cndmask_b32_e64 v115, v127, v125, s[40:41]
	v_mov_b32_dpp v116, v112 quad_perm:[1,0,3,2] row_mask:0xf bank_mask:0xf
	v_mov_b32_dpp v117, v113 quad_perm:[1,0,3,2] row_mask:0xf bank_mask:0xf
	v_mov_b32_dpp v118, v114 quad_perm:[1,0,3,2] row_mask:0xf bank_mask:0xf
	v_mov_b32_dpp v119, v115 quad_perm:[1,0,3,2] row_mask:0xf bank_mask:0xf
	s_nop 0
	v_cndmask_b32_e64 v160, v120, v116, s[40:41]
	v_cndmask_b32_e64 v161, v121, v117, s[40:41]
	v_cndmask_b32_e64 v162, v116, v122, s[40:41]
	v_cndmask_b32_e64 v163, v117, v123, s[40:41]
	v_cndmask_b32_e64 v164, v124, v118, s[40:41]
	v_cndmask_b32_e64 v165, v125, v119, s[40:41]
	v_cndmask_b32_e64 v166, v118, v126, s[40:41]
	v_cndmask_b32_e64 v167, v119, v127, s[40:41]
	global_store_dwordx4 v[132:133], v[160:163], off
	global_store_dwordx4 v[132:133], v[164:167], off offset:1024
	v_lshl_add_u64 v[132:133], v[132:133], 0, v[154:155]
	global_load_dwordx4 v[48:51], v[134:135], off offset:-4096
	global_load_dwordx4 v[52:55], v[134:135], off offset:-3072
	global_load_dwordx4 v[56:59], v[134:135], off offset:-2048
	global_load_dwordx4 v[60:63], v[134:135], off offset:-1024
	global_load_dwordx4 v[64:67], v[134:135], off
	global_load_dwordx4 v[68:71], v[134:135], off offset:1024
	global_load_dwordx4 v[72:75], v[134:135], off offset:2048
	global_load_dwordx4 v[76:79], v[134:135], off offset:3072
	v_lshl_add_u64 v[134:135], v[134:135], 0, v[156:157]
	global_load_dwordx4 v[16:19], v[128:129], off nt
	global_load_dwordx4 v[20:23], v[128:129], off offset:1024 nt
	global_load_dwordx4 v[24:27], v[128:129], off offset:2048 nt
	global_load_dwordx4 v[28:31], v[128:129], off offset:3072 nt
	v_lshl_add_u64 v[128:129], v[128:129], 0, v[152:153]
	s_waitcnt vmcnt(20)
	v_add_f32_e32 v112, v32, v33
	v_add_f32_e32 v113, v34, v35
	v_add_f32_e32 v114, v36, v37
	v_add_f32_e32 v115, v38, v39
	v_add_f32_e32 v116, v40, v41
	v_add_f32_e32 v117, v42, v43
	v_add_f32_e32 v118, v44, v45
	v_add_f32_e32 v119, v46, v47
	v_add_f32_e32 v112, v112, v116
	v_add_f32_e32 v113, v113, v117
	v_add_f32_e32 v114, v114, v118
	v_add_f32_e32 v115, v115, v119
	v_add_f32_e32 v112, v112, v113
	v_add_f32_e32 v114, v114, v115
	v_add_f32_e32 v112, v112, v114
	s_nop 1
	v_add_f32_dpp v112, v112, v112 quad_perm:[1,0,3,2] row_mask:0xf bank_mask:0xf
	s_nop 1
	v_add_f32_dpp v112, v112, v112 quad_perm:[2,3,0,1] row_mask:0xf bank_mask:0xf
	s_nop 1
	v_add_f32_dpp v112, v112, v112 row_half_mirror row_mask:0xf bank_mask:0xf
	s_nop 1
	v_add_f32_dpp v112, v112, v112 row_mirror row_mask:0xf bank_mask:0xf
	s_nop 1
	v_add_f32_dpp v112, v112, v112 row_bcast:15 row_mask:0xa bank_mask:0xf
	s_nop 1
	v_add_f32_dpp v112, v112, v112 row_bcast:31 row_mask:0xc bank_mask:0xf
	s_nop 1
	v_readlane_b32 s2, v112, 63
	s_nop 1
	v_fmac_f32_e32 v32, s2, v142
	v_fmac_f32_e32 v33, s2, v142
	v_fmac_f32_e32 v34, s2, v142
	v_fmac_f32_e32 v35, s2, v142
	v_fmac_f32_e32 v36, s2, v142
	v_fmac_f32_e32 v37, s2, v142
	v_fmac_f32_e32 v38, s2, v142
	v_fmac_f32_e32 v39, s2, v142
	v_fmac_f32_e32 v40, s2, v142
	v_fmac_f32_e32 v41, s2, v142
	v_fmac_f32_e32 v42, s2, v142
	v_fmac_f32_e32 v43, s2, v142
	v_fmac_f32_e32 v44, s2, v142
	v_fmac_f32_e32 v45, s2, v142
	v_fmac_f32_e32 v46, s2, v142
	v_fmac_f32_e32 v47, s2, v142
	v_mul_f32_e32 v112, v32, v32
	v_mul_f32_e32 v113, v33, v33
	v_mul_f32_e32 v114, v34, v34
	v_mul_f32_e32 v115, v35, v35
	v_fmac_f32_e32 v112, v36, v36
	v_fmac_f32_e32 v113, v37, v37
	v_fmac_f32_e32 v114, v38, v38
	v_fmac_f32_e32 v115, v39, v39
	v_fmac_f32_e32 v112, v40, v40
	v_fmac_f32_e32 v113, v41, v41
	v_fmac_f32_e32 v114, v42, v42
	v_fmac_f32_e32 v115, v43, v43
	v_fmac_f32_e32 v112, v44, v44
	v_fmac_f32_e32 v113, v45, v45
	v_fmac_f32_e32 v114, v46, v46
	v_fmac_f32_e32 v115, v47, v47
	v_add_f32_e32 v112, v112, v113
	v_add_f32_e32 v114, v114, v115
	v_add_f32_e32 v112, v112, v114
	s_nop 1
	v_add_f32_dpp v112, v112, v112 quad_perm:[1,0,3,2] row_mask:0xf bank_mask:0xf
	s_nop 1
	v_add_f32_dpp v112, v112, v112 quad_perm:[2,3,0,1] row_mask:0xf bank_mask:0xf
	s_nop 1
	v_add_f32_dpp v112, v112, v112 row_half_mirror row_mask:0xf bank_mask:0xf
	s_nop 1
	v_add_f32_dpp v112, v112, v112 row_mirror row_mask:0xf bank_mask:0xf
	s_nop 1
	v_add_f32_dpp v112, v112, v112 row_bcast:15 row_mask:0xa bank_mask:0xf
	s_nop 1
	v_add_f32_dpp v112, v112, v112 row_bcast:31 row_mask:0xc bank_mask:0xf
	s_nop 1
	v_readlane_b32 s2, v112, 63
	s_nop 1
	v_mov_b32_e32 v113, 0x358637bd
	v_mov_b32_e32 v114, 0x3a800000
	v_fmac_f32_e32 v113, s2, v114
	v_rsq_f32_e32 v115, v113
	v_mul_f32_e32 v113, 0.5, v113
	v_mul_f32_e32 v116, v115, v115
	v_mov_b32_e32 v117, 0x3fc00000
	v_fma_f32 v116, -v113, v116, v117
	v_mul_f32_e32 v144, v115, v116
	v_pk_mul_f32 v[32:33], v[32:33], v[144:145] op_sel_hi:[1,0]
	v_pk_mul_f32 v[34:35], v[34:35], v[144:145] op_sel_hi:[1,0]
	v_pk_mul_f32 v[36:37], v[36:37], v[144:145] op_sel_hi:[1,0]
	v_pk_mul_f32 v[38:39], v[38:39], v[144:145] op_sel_hi:[1,0]
	v_pk_mul_f32 v[40:41], v[40:41], v[144:145] op_sel_hi:[1,0]
	v_pk_mul_f32 v[42:43], v[42:43], v[144:145] op_sel_hi:[1,0]
	v_pk_mul_f32 v[44:45], v[44:45], v[144:145] op_sel_hi:[1,0]
	v_pk_mul_f32 v[46:47], v[46:47], v[144:145] op_sel_hi:[1,0]
	s_waitcnt vmcnt(4)
	v_pk_add_f32 v[64:65], v[64:65], 1.0 op_sel_hi:[1,0]
	v_pk_add_f32 v[66:67], v[66:67], 1.0 op_sel_hi:[1,0]
	v_pk_add_f32 v[68:69], v[68:69], 1.0 op_sel_hi:[1,0]
	v_pk_add_f32 v[70:71], v[70:71], 1.0 op_sel_hi:[1,0]
	v_pk_add_f32 v[72:73], v[72:73], 1.0 op_sel_hi:[1,0]
	v_pk_add_f32 v[74:75], v[74:75], 1.0 op_sel_hi:[1,0]
	v_pk_add_f32 v[76:77], v[76:77], 1.0 op_sel_hi:[1,0]
	v_pk_add_f32 v[78:79], v[78:79], 1.0 op_sel_hi:[1,0]
	v_pk_fma_f32 v[32:33], v[64:65], v[32:33], v[48:49]
	v_pk_fma_f32 v[34:35], v[66:67], v[34:35], v[50:51]
	v_pk_fma_f32 v[36:37], v[68:69], v[36:37], v[52:53]
	v_pk_fma_f32 v[38:39], v[70:71], v[38:39], v[54:55]
	v_pk_fma_f32 v[40:41], v[72:73], v[40:41], v[56:57]
	v_pk_fma_f32 v[42:43], v[74:75], v[42:43], v[58:59]
	v_pk_fma_f32 v[44:45], v[76:77], v[44:45], v[60:61]
	v_pk_fma_f32 v[46:47], v[78:79], v[46:47], v[62:63]
	v_cvt_pk_bf16_f32 v120, v32, v33
	v_cvt_pk_bf16_f32 v121, v34, v35
	v_cvt_pk_bf16_f32 v122, v36, v37
	v_cvt_pk_bf16_f32 v123, v38, v39
	v_cvt_pk_bf16_f32 v124, v40, v41
	v_cvt_pk_bf16_f32 v125, v42, v43
	v_cvt_pk_bf16_f32 v126, v44, v45
	v_cvt_pk_bf16_f32 v127, v46, v47
	v_cndmask_b32_e64 v112, v122, v120, s[40:41]
	v_cndmask_b32_e64 v113, v123, v121, s[40:41]
	v_cndmask_b32_e64 v114, v126, v124, s[40:41]
	v_cndmask_b32_e64 v115, v127, v125, s[40:41]
	v_mov_b32_dpp v116, v112 quad_perm:[1,0,3,2] row_mask:0xf bank_mask:0xf
	v_mov_b32_dpp v117, v113 quad_perm:[1,0,3,2] row_mask:0xf bank_mask:0xf
	v_mov_b32_dpp v118, v114 quad_perm:[1,0,3,2] row_mask:0xf bank_mask:0xf
	v_mov_b32_dpp v119, v115 quad_perm:[1,0,3,2] row_mask:0xf bank_mask:0xf
	s_nop 0
	v_cndmask_b32_e64 v160, v120, v116, s[40:41]
	v_cndmask_b32_e64 v161, v121, v117, s[40:41]
	v_cndmask_b32_e64 v162, v116, v122, s[40:41]
	v_cndmask_b32_e64 v163, v117, v123, s[40:41]
	v_cndmask_b32_e64 v164, v124, v118, s[40:41]
	v_cndmask_b32_e64 v165, v125, v119, s[40:41]
	v_cndmask_b32_e64 v166, v118, v126, s[40:41]
	v_cndmask_b32_e64 v167, v119, v127, s[40:41]
	global_store_dwordx4 v[132:133], v[160:163], off
	global_store_dwordx4 v[132:133], v[164:167], off offset:1024
	v_lshl_add_u64 v[132:133], v[132:133], 0, v[154:155]
	global_load_dwordx4 v[32:35], v[128:129], off nt
	global_load_dwordx4 v[36:39], v[128:129], off offset:1024 nt
	global_load_dwordx4 v[40:43], v[128:129], off offset:2048 nt
	global_load_dwordx4 v[44:47], v[128:129], off offset:3072 nt
	v_lshl_add_u64 v[128:129], v[128:129], 0, v[152:153]
	s_cmp_lg_u32 s0, 2
	s_cbranch_scc1 .Lln0_nopark
	v_lshl_add_u64 v[128:129], s[60:61], 0, v[148:149]
.Lln0_nopark:
	v_add_f32_e32 v112, v0, v1
	v_add_f32_e32 v113, v2, v3
	v_add_f32_e32 v114, v4, v5
	v_add_f32_e32 v115, v6, v7
	v_add_f32_e32 v116, v8, v9
	v_add_f32_e32 v117, v10, v11
	v_add_f32_e32 v118, v12, v13
	v_add_f32_e32 v119, v14, v15
	v_add_f32_e32 v112, v112, v116
	v_add_f32_e32 v113, v113, v117
	v_add_f32_e32 v114, v114, v118
	v_add_f32_e32 v115, v115, v119
	v_add_f32_e32 v112, v112, v113
	v_add_f32_e32 v114, v114, v115
	v_add_f32_e32 v112, v112, v114
	s_nop 1
	v_add_f32_dpp v112, v112, v112 quad_perm:[1,0,3,2] row_mask:0xf bank_mask:0xf
	s_nop 1
	v_add_f32_dpp v112, v112, v112 quad_perm:[2,3,0,1] row_mask:0xf bank_mask:0xf
	s_nop 1
	v_add_f32_dpp v112, v112, v112 row_half_mirror row_mask:0xf bank_mask:0xf
	s_nop 1
	v_add_f32_dpp v112, v112, v112 row_mirror row_mask:0xf bank_mask:0xf
	s_nop 1
	v_add_f32_dpp v112, v112, v112 row_bcast:15 row_mask:0xa bank_mask:0xf
	s_nop 1
	v_add_f32_dpp v112, v112, v112 row_bcast:31 row_mask:0xc bank_mask:0xf
	s_nop 1
	v_readlane_b32 s2, v112, 63
	s_nop 1
	v_fmac_f32_e32 v0, s2, v142
	v_fmac_f32_e32 v1, s2, v142
	v_fmac_f32_e32 v2, s2, v142
	v_fmac_f32_e32 v3, s2, v142
	v_fmac_f32_e32 v4, s2, v142
	v_fmac_f32_e32 v5, s2, v142
	v_fmac_f32_e32 v6, s2, v142
	v_fmac_f32_e32 v7, s2, v142
	v_fmac_f32_e32 v8, s2, v142
	v_fmac_f32_e32 v9, s2, v142
	v_fmac_f32_e32 v10, s2, v142
	v_fmac_f32_e32 v11, s2, v142
	v_fmac_f32_e32 v12, s2, v142
	v_fmac_f32_e32 v13, s2, v142
	v_fmac_f32_e32 v14, s2, v142
	v_fmac_f32_e32 v15, s2, v142
	v_mul_f32_e32 v112, v0, v0
	v_mul_f32_e32 v113, v1, v1
	v_mul_f32_e32 v114, v2, v2
	v_mul_f32_e32 v115, v3, v3
	v_fmac_f32_e32 v112, v4, v4
	v_fmac_f32_e32 v113, v5, v5
	v_fmac_f32_e32 v114, v6, v6
	v_fmac_f32_e32 v115, v7, v7
	v_fmac_f32_e32 v112, v8, v8
	v_fmac_f32_e32 v113, v9, v9
	v_fmac_f32_e32 v114, v10, v10
	v_fmac_f32_e32 v115, v11, v11
	v_fmac_f32_e32 v112, v12, v12
	v_fmac_f32_e32 v113, v13, v13
	v_fmac_f32_e32 v114, v14, v14
	v_fmac_f32_e32 v115, v15, v15
	v_add_f32_e32 v112, v112, v113
	v_add_f32_e32 v114, v114, v115
	v_add_f32_e32 v112, v112, v114
	s_nop 1
	v_add_f32_dpp v112, v112, v112 quad_perm:[1,0,3,2] row_mask:0xf bank_mask:0xf
	s_nop 1
	v_add_f32_dpp v112, v112, v112 quad_perm:[2,3,0,1] row_mask:0xf bank_mask:0xf
	s_nop 1
	v_add_f32_dpp v112, v112, v112 row_half_mirror row_mask:0xf bank_mask:0xf
	s_nop 1
	v_add_f32_dpp v112, v112, v112 row_mirror row_mask:0xf bank_mask:0xf
	s_nop 1
	v_add_f32_dpp v112, v112, v112 row_bcast:15 row_mask:0xa bank_mask:0xf
	s_nop 1
	v_add_f32_dpp v112, v112, v112 row_bcast:31 row_mask:0xc bank_mask:0xf
	s_nop 1
	v_readlane_b32 s2, v112, 63
	s_nop 1
	v_mov_b32_e32 v113, 0x358637bd
	v_mov_b32_e32 v114, 0x3a800000
	v_fmac_f32_e32 v113, s2, v114
	v_rsq_f32_e32 v115, v113
	v_mul_f32_e32 v113, 0.5, v113
	v_mul_f32_e32 v116, v115, v115
	v_mov_b32_e32 v117, 0x3fc00000
	v_fma_f32 v116, -v113, v116, v117
	v_mul_f32_e32 v144, v115, v116
	v_pk_mul_f32 v[0:1], v[0:1], v[144:145] op_sel_hi:[1,0]
	v_pk_mul_f32 v[2:3], v[2:3], v[144:145] op_sel_hi:[1,0]
	v_pk_mul_f32 v[4:5], v[4:5], v[144:145] op_sel_hi:[1,0]
	v_pk_mul_f32 v[6:7], v[6:7], v[144:145] op_sel_hi:[1,0]
	v_pk_mul_f32 v[8:9], v[8:9], v[144:145] op_sel_hi:[1,0]
	v_pk_mul_f32 v[10:11], v[10:11], v[144:145] op_sel_hi:[1,0]
	v_pk_mul_f32 v[12:13], v[12:13], v[144:145] op_sel_hi:[1,0]
	v_pk_mul_f32 v[14:15], v[14:15], v[144:145] op_sel_hi:[1,0]
	v_pk_fma_f32 v[0:1], v[64:65], v[0:1], v[48:49]
	v_pk_fma_f32 v[2:3], v[66:67], v[2:3], v[50:51]
	v_pk_fma_f32 v[4:5], v[68:69], v[4:5], v[52:53]
	v_pk_fma_f32 v[6:7], v[70:71], v[6:7], v[54:55]
	v_pk_fma_f32 v[8:9], v[72:73], v[8:9], v[56:57]
	v_pk_fma_f32 v[10:11], v[74:75], v[10:11], v[58:59]
	v_pk_fma_f32 v[12:13], v[76:77], v[12:13], v[60:61]
	v_pk_fma_f32 v[14:15], v[78:79], v[14:15], v[62:63]
	v_cvt_pk_bf16_f32 v120, v0, v1
	v_cvt_pk_bf16_f32 v121, v2, v3
	v_cvt_pk_bf16_f32 v122, v4, v5
	v_cvt_pk_bf16_f32 v123, v6, v7
	v_cvt_pk_bf16_f32 v124, v8, v9
	v_cvt_pk_bf16_f32 v125, v10, v11
	v_cvt_pk_bf16_f32 v126, v12, v13
	v_cvt_pk_bf16_f32 v127, v14, v15
	v_cndmask_b32_e64 v112, v122, v120, s[40:41]
	v_cndmask_b32_e64 v113, v123, v121, s[40:41]
	v_cndmask_b32_e64 v114, v126, v124, s[40:41]
	v_cndmask_b32_e64 v115, v127, v125, s[40:41]
	v_mov_b32_dpp v116, v112 quad_perm:[1,0,3,2] row_mask:0xf bank_mask:0xf
	v_mov_b32_dpp v117, v113 quad_perm:[1,0,3,2] row_mask:0xf bank_mask:0xf
	v_mov_b32_dpp v118, v114 quad_perm:[1,0,3,2] row_mask:0xf bank_mask:0xf
	v_mov_b32_dpp v119, v115 quad_perm:[1,0,3,2] row_mask:0xf bank_mask:0xf
	s_nop 0
	v_cndmask_b32_e64 v160, v120, v116, s[40:41]
	v_cndmask_b32_e64 v161, v121, v117, s[40:41]
	v_cndmask_b32_e64 v162, v116, v122, s[40:41]
	v_cndmask_b32_e64 v163, v117, v123, s[40:41]
	v_cndmask_b32_e64 v164, v124, v118, s[40:41]
	v_cndmask_b32_e64 v165, v125, v119, s[40:41]
	v_cndmask_b32_e64 v166, v118, v126, s[40:41]
	v_cndmask_b32_e64 v167, v119, v127, s[40:41]
	global_store_dwordx4 v[132:133], v[160:163], off
	global_store_dwordx4 v[132:133], v[164:167], off offset:1024
	v_lshl_add_u64 v[132:133], v[132:133], 0, v[154:155]
	global_load_dwordx4 v[48:51], v[134:135], off offset:-4096
	global_load_dwordx4 v[52:55], v[134:135], off offset:-3072
	global_load_dwordx4 v[56:59], v[134:135], off offset:-2048
	global_load_dwordx4 v[60:63], v[134:135], off offset:-1024
	global_load_dwordx4 v[64:67], v[134:135], off
	global_load_dwordx4 v[68:71], v[134:135], off offset:1024
	global_load_dwordx4 v[72:75], v[134:135], off offset:2048
	global_load_dwordx4 v[76:79], v[134:135], off offset:3072
	v_lshl_add_u64 v[134:135], v[134:135], 0, v[156:157]
	global_load_dwordx4 v[0:3], v[128:129], off nt
	global_load_dwordx4 v[4:7], v[128:129], off offset:1024 nt
	global_load_dwordx4 v[8:11], v[128:129], off offset:2048 nt
	global_load_dwordx4 v[12:15], v[128:129], off offset:3072 nt
	v_lshl_add_u64 v[128:129], v[128:129], 0, v[152:153]
	s_waitcnt vmcnt(20)
	v_add_f32_e32 v112, v16, v17
	v_add_f32_e32 v113, v18, v19
	v_add_f32_e32 v114, v20, v21
	v_add_f32_e32 v115, v22, v23
	v_add_f32_e32 v116, v24, v25
	v_add_f32_e32 v117, v26, v27
	v_add_f32_e32 v118, v28, v29
	v_add_f32_e32 v119, v30, v31
	v_add_f32_e32 v112, v112, v116
	v_add_f32_e32 v113, v113, v117
	v_add_f32_e32 v114, v114, v118
	v_add_f32_e32 v115, v115, v119
	v_add_f32_e32 v112, v112, v113
	v_add_f32_e32 v114, v114, v115
	v_add_f32_e32 v112, v112, v114
	s_nop 1
	v_add_f32_dpp v112, v112, v112 quad_perm:[1,0,3,2] row_mask:0xf bank_mask:0xf
	s_nop 1
	v_add_f32_dpp v112, v112, v112 quad_perm:[2,3,0,1] row_mask:0xf bank_mask:0xf
	s_nop 1
	v_add_f32_dpp v112, v112, v112 row_half_mirror row_mask:0xf bank_mask:0xf
	s_nop 1
	v_add_f32_dpp v112, v112, v112 row_mirror row_mask:0xf bank_mask:0xf
	s_nop 1
	v_add_f32_dpp v112, v112, v112 row_bcast:15 row_mask:0xa bank_mask:0xf
	s_nop 1
	v_add_f32_dpp v112, v112, v112 row_bcast:31 row_mask:0xc bank_mask:0xf
	s_nop 1
	v_readlane_b32 s2, v112, 63
	s_nop 1
	v_fmac_f32_e32 v16, s2, v142
	v_fmac_f32_e32 v17, s2, v142
	v_fmac_f32_e32 v18, s2, v142
	v_fmac_f32_e32 v19, s2, v142
	v_fmac_f32_e32 v20, s2, v142
	v_fmac_f32_e32 v21, s2, v142
	v_fmac_f32_e32 v22, s2, v142
	v_fmac_f32_e32 v23, s2, v142
	v_fmac_f32_e32 v24, s2, v142
	v_fmac_f32_e32 v25, s2, v142
	v_fmac_f32_e32 v26, s2, v142
	v_fmac_f32_e32 v27, s2, v142
	v_fmac_f32_e32 v28, s2, v142
	v_fmac_f32_e32 v29, s2, v142
	v_fmac_f32_e32 v30, s2, v142
	v_fmac_f32_e32 v31, s2, v142
	v_mul_f32_e32 v112, v16, v16
	v_mul_f32_e32 v113, v17, v17
	v_mul_f32_e32 v114, v18, v18
	v_mul_f32_e32 v115, v19, v19
	v_fmac_f32_e32 v112, v20, v20
	v_fmac_f32_e32 v113, v21, v21
	v_fmac_f32_e32 v114, v22, v22
	v_fmac_f32_e32 v115, v23, v23
	v_fmac_f32_e32 v112, v24, v24
	v_fmac_f32_e32 v113, v25, v25
	v_fmac_f32_e32 v114, v26, v26
	v_fmac_f32_e32 v115, v27, v27
	v_fmac_f32_e32 v112, v28, v28
	v_fmac_f32_e32 v113, v29, v29
	v_fmac_f32_e32 v114, v30, v30
	v_fmac_f32_e32 v115, v31, v31
	v_add_f32_e32 v112, v112, v113
	v_add_f32_e32 v114, v114, v115
	v_add_f32_e32 v112, v112, v114
	s_nop 1
	v_add_f32_dpp v112, v112, v112 quad_perm:[1,0,3,2] row_mask:0xf bank_mask:0xf
	s_nop 1
	v_add_f32_dpp v112, v112, v112 quad_perm:[2,3,0,1] row_mask:0xf bank_mask:0xf
	s_nop 1
	v_add_f32_dpp v112, v112, v112 row_half_mirror row_mask:0xf bank_mask:0xf
	s_nop 1
	v_add_f32_dpp v112, v112, v112 row_mirror row_mask:0xf bank_mask:0xf
	s_nop 1
	v_add_f32_dpp v112, v112, v112 row_bcast:15 row_mask:0xa bank_mask:0xf
	s_nop 1
	v_add_f32_dpp v112, v112, v112 row_bcast:31 row_mask:0xc bank_mask:0xf
	s_nop 1
	v_readlane_b32 s2, v112, 63
	s_nop 1
	v_mov_b32_e32 v113, 0x358637bd
	v_mov_b32_e32 v114, 0x3a800000
	v_fmac_f32_e32 v113, s2, v114
	v_rsq_f32_e32 v115, v113
	v_mul_f32_e32 v113, 0.5, v113
	v_mul_f32_e32 v116, v115, v115
	v_mov_b32_e32 v117, 0x3fc00000
	v_fma_f32 v116, -v113, v116, v117
	v_mul_f32_e32 v144, v115, v116
	v_pk_mul_f32 v[16:17], v[16:17], v[144:145] op_sel_hi:[1,0]
	v_pk_mul_f32 v[18:19], v[18:19], v[144:145] op_sel_hi:[1,0]
	v_pk_mul_f32 v[20:21], v[20:21], v[144:145] op_sel_hi:[1,0]
	v_pk_mul_f32 v[22:23], v[22:23], v[144:145] op_sel_hi:[1,0]
	v_pk_mul_f32 v[24:25], v[24:25], v[144:145] op_sel_hi:[1,0]
	v_pk_mul_f32 v[26:27], v[26:27], v[144:145] op_sel_hi:[1,0]
	v_pk_mul_f32 v[28:29], v[28:29], v[144:145] op_sel_hi:[1,0]
	v_pk_mul_f32 v[30:31], v[30:31], v[144:145] op_sel_hi:[1,0]
	s_waitcnt vmcnt(4)
	v_pk_add_f32 v[64:65], v[64:65], 1.0 op_sel_hi:[1,0]
	v_pk_add_f32 v[66:67], v[66:67], 1.0 op_sel_hi:[1,0]
	v_pk_add_f32 v[68:69], v[68:69], 1.0 op_sel_hi:[1,0]
	v_pk_add_f32 v[70:71], v[70:71], 1.0 op_sel_hi:[1,0]
	v_pk_add_f32 v[72:73], v[72:73], 1.0 op_sel_hi:[1,0]
	v_pk_add_f32 v[74:75], v[74:75], 1.0 op_sel_hi:[1,0]
	v_pk_add_f32 v[76:77], v[76:77], 1.0 op_sel_hi:[1,0]
	v_pk_add_f32 v[78:79], v[78:79], 1.0 op_sel_hi:[1,0]
	v_pk_fma_f32 v[16:17], v[64:65], v[16:17], v[48:49]
	v_pk_fma_f32 v[18:19], v[66:67], v[18:19], v[50:51]
	v_pk_fma_f32 v[20:21], v[68:69], v[20:21], v[52:53]
	v_pk_fma_f32 v[22:23], v[70:71], v[22:23], v[54:55]
	v_pk_fma_f32 v[24:25], v[72:73], v[24:25], v[56:57]
	v_pk_fma_f32 v[26:27], v[74:75], v[26:27], v[58:59]
	v_pk_fma_f32 v[28:29], v[76:77], v[28:29], v[60:61]
	v_pk_fma_f32 v[30:31], v[78:79], v[30:31], v[62:63]
	v_cvt_pk_bf16_f32 v120, v16, v17
	v_cvt_pk_bf16_f32 v121, v18, v19
	v_cvt_pk_bf16_f32 v122, v20, v21
	v_cvt_pk_bf16_f32 v123, v22, v23
	v_cvt_pk_bf16_f32 v124, v24, v25
	v_cvt_pk_bf16_f32 v125, v26, v27
	v_cvt_pk_bf16_f32 v126, v28, v29
	v_cvt_pk_bf16_f32 v127, v30, v31
	v_cndmask_b32_e64 v112, v122, v120, s[40:41]
	v_cndmask_b32_e64 v113, v123, v121, s[40:41]
	v_cndmask_b32_e64 v114, v126, v124, s[40:41]
	v_cndmask_b32_e64 v115, v127, v125, s[40:41]
	v_mov_b32_dpp v116, v112 quad_perm:[1,0,3,2] row_mask:0xf bank_mask:0xf
	v_mov_b32_dpp v117, v113 quad_perm:[1,0,3,2] row_mask:0xf bank_mask:0xf
	v_mov_b32_dpp v118, v114 quad_perm:[1,0,3,2] row_mask:0xf bank_mask:0xf
	v_mov_b32_dpp v119, v115 quad_perm:[1,0,3,2] row_mask:0xf bank_mask:0xf
	s_nop 0
	v_cndmask_b32_e64 v160, v120, v116, s[40:41]
	v_cndmask_b32_e64 v161, v121, v117, s[40:41]
	v_cndmask_b32_e64 v162, v116, v122, s[40:41]
	v_cndmask_b32_e64 v163, v117, v123, s[40:41]
	v_cndmask_b32_e64 v164, v124, v118, s[40:41]
	v_cndmask_b32_e64 v165, v125, v119, s[40:41]
	v_cndmask_b32_e64 v166, v118, v126, s[40:41]
	v_cndmask_b32_e64 v167, v119, v127, s[40:41]
	global_store_dwordx4 v[132:133], v[160:163], off
	global_store_dwordx4 v[132:133], v[164:167], off offset:1024
	v_lshl_add_u64 v[132:133], v[132:133], 0, v[154:155]
	global_load_dwordx4 v[16:19], v[128:129], off nt
	global_load_dwordx4 v[20:23], v[128:129], off offset:1024 nt
	global_load_dwordx4 v[24:27], v[128:129], off offset:2048 nt
	global_load_dwordx4 v[28:31], v[128:129], off offset:3072 nt
	v_lshl_add_u64 v[128:129], v[128:129], 0, v[152:153]
	v_add_f32_e32 v112, v32, v33
	v_add_f32_e32 v113, v34, v35
	v_add_f32_e32 v114, v36, v37
	v_add_f32_e32 v115, v38, v39
	v_add_f32_e32 v116, v40, v41
	v_add_f32_e32 v117, v42, v43
	v_add_f32_e32 v118, v44, v45
	v_add_f32_e32 v119, v46, v47
	v_add_f32_e32 v112, v112, v116
	v_add_f32_e32 v113, v113, v117
	v_add_f32_e32 v114, v114, v118
	v_add_f32_e32 v115, v115, v119
	v_add_f32_e32 v112, v112, v113
	v_add_f32_e32 v114, v114, v115
	v_add_f32_e32 v112, v112, v114
	s_nop 1
	v_add_f32_dpp v112, v112, v112 quad_perm:[1,0,3,2] row_mask:0xf bank_mask:0xf
	s_nop 1
	v_add_f32_dpp v112, v112, v112 quad_perm:[2,3,0,1] row_mask:0xf bank_mask:0xf
	s_nop 1
	v_add_f32_dpp v112, v112, v112 row_half_mirror row_mask:0xf bank_mask:0xf
	s_nop 1
	v_add_f32_dpp v112, v112, v112 row_mirror row_mask:0xf bank_mask:0xf
	s_nop 1
	v_add_f32_dpp v112, v112, v112 row_bcast:15 row_mask:0xa bank_mask:0xf
	s_nop 1
	v_add_f32_dpp v112, v112, v112 row_bcast:31 row_mask:0xc bank_mask:0xf
	s_nop 1
	v_readlane_b32 s2, v112, 63
	s_nop 1
	v_fmac_f32_e32 v32, s2, v142
	v_fmac_f32_e32 v33, s2, v142
	v_fmac_f32_e32 v34, s2, v142
	v_fmac_f32_e32 v35, s2, v142
	v_fmac_f32_e32 v36, s2, v142
	v_fmac_f32_e32 v37, s2, v142
	v_fmac_f32_e32 v38, s2, v142
	v_fmac_f32_e32 v39, s2, v142
	v_fmac_f32_e32 v40, s2, v142
	v_fmac_f32_e32 v41, s2, v142
	v_fmac_f32_e32 v42, s2, v142
	v_fmac_f32_e32 v43, s2, v142
	v_fmac_f32_e32 v44, s2, v142
	v_fmac_f32_e32 v45, s2, v142
	v_fmac_f32_e32 v46, s2, v142
	v_fmac_f32_e32 v47, s2, v142
	v_mul_f32_e32 v112, v32, v32
	v_mul_f32_e32 v113, v33, v33
	v_mul_f32_e32 v114, v34, v34
	v_mul_f32_e32 v115, v35, v35
	v_fmac_f32_e32 v112, v36, v36
	v_fmac_f32_e32 v113, v37, v37
	v_fmac_f32_e32 v114, v38, v38
	v_fmac_f32_e32 v115, v39, v39
	v_fmac_f32_e32 v112, v40, v40
	v_fmac_f32_e32 v113, v41, v41
	v_fmac_f32_e32 v114, v42, v42
	v_fmac_f32_e32 v115, v43, v43
	v_fmac_f32_e32 v112, v44, v44
	v_fmac_f32_e32 v113, v45, v45
	v_fmac_f32_e32 v114, v46, v46
	v_fmac_f32_e32 v115, v47, v47
	v_add_f32_e32 v112, v112, v113
	v_add_f32_e32 v114, v114, v115
	v_add_f32_e32 v112, v112, v114
	s_nop 1
	v_add_f32_dpp v112, v112, v112 quad_perm:[1,0,3,2] row_mask:0xf bank_mask:0xf
	s_nop 1
	v_add_f32_dpp v112, v112, v112 quad_perm:[2,3,0,1] row_mask:0xf bank_mask:0xf
	s_nop 1
	v_add_f32_dpp v112, v112, v112 row_half_mirror row_mask:0xf bank_mask:0xf
	s_nop 1
	v_add_f32_dpp v112, v112, v112 row_mirror row_mask:0xf bank_mask:0xf
	s_nop 1
	v_add_f32_dpp v112, v112, v112 row_bcast:15 row_mask:0xa bank_mask:0xf
	s_nop 1
	v_add_f32_dpp v112, v112, v112 row_bcast:31 row_mask:0xc bank_mask:0xf
	s_nop 1
	v_readlane_b32 s2, v112, 63
	s_nop 1
	v_mov_b32_e32 v113, 0x358637bd
	v_mov_b32_e32 v114, 0x3a800000
	v_fmac_f32_e32 v113, s2, v114
	v_rsq_f32_e32 v115, v113
	v_mul_f32_e32 v113, 0.5, v113
	v_mul_f32_e32 v116, v115, v115
	v_mov_b32_e32 v117, 0x3fc00000
	v_fma_f32 v116, -v113, v116, v117
	v_mul_f32_e32 v144, v115, v116
	v_pk_mul_f32 v[32:33], v[32:33], v[144:145] op_sel_hi:[1,0]
	v_pk_mul_f32 v[34:35], v[34:35], v[144:145] op_sel_hi:[1,0]
	v_pk_mul_f32 v[36:37], v[36:37], v[144:145] op_sel_hi:[1,0]
	v_pk_mul_f32 v[38:39], v[38:39], v[144:145] op_sel_hi:[1,0]
	v_pk_mul_f32 v[40:41], v[40:41], v[144:145] op_sel_hi:[1,0]
	v_pk_mul_f32 v[42:43], v[42:43], v[144:145] op_sel_hi:[1,0]
	v_pk_mul_f32 v[44:45], v[44:45], v[144:145] op_sel_hi:[1,0]
	v_pk_mul_f32 v[46:47], v[46:47], v[144:145] op_sel_hi:[1,0]
	v_pk_fma_f32 v[32:33], v[64:65], v[32:33], v[48:49]
	v_pk_fma_f32 v[34:35], v[66:67], v[34:35], v[50:51]
	v_pk_fma_f32 v[36:37], v[68:69], v[36:37], v[52:53]
	v_pk_fma_f32 v[38:39], v[70:71], v[38:39], v[54:55]
	v_pk_fma_f32 v[40:41], v[72:73], v[40:41], v[56:57]
	v_pk_fma_f32 v[42:43], v[74:75], v[42:43], v[58:59]
	v_pk_fma_f32 v[44:45], v[76:77], v[44:45], v[60:61]
	v_pk_fma_f32 v[46:47], v[78:79], v[46:47], v[62:63]
	v_cvt_pk_bf16_f32 v120, v32, v33
	v_cvt_pk_bf16_f32 v121, v34, v35
	v_cvt_pk_bf16_f32 v122, v36, v37
	v_cvt_pk_bf16_f32 v123, v38, v39
	v_cvt_pk_bf16_f32 v124, v40, v41
	v_cvt_pk_bf16_f32 v125, v42, v43
	v_cvt_pk_bf16_f32 v126, v44, v45
	v_cvt_pk_bf16_f32 v127, v46, v47
	v_cndmask_b32_e64 v112, v122, v120, s[40:41]
	v_cndmask_b32_e64 v113, v123, v121, s[40:41]
	v_cndmask_b32_e64 v114, v126, v124, s[40:41]
	v_cndmask_b32_e64 v115, v127, v125, s[40:41]
	v_mov_b32_dpp v116, v112 quad_perm:[1,0,3,2] row_mask:0xf bank_mask:0xf
	v_mov_b32_dpp v117, v113 quad_perm:[1,0,3,2] row_mask:0xf bank_mask:0xf
	v_mov_b32_dpp v118, v114 quad_perm:[1,0,3,2] row_mask:0xf bank_mask:0xf
	v_mov_b32_dpp v119, v115 quad_perm:[1,0,3,2] row_mask:0xf bank_mask:0xf
	s_nop 0
	v_cndmask_b32_e64 v160, v120, v116, s[40:41]
	v_cndmask_b32_e64 v161, v121, v117, s[40:41]
	v_cndmask_b32_e64 v162, v116, v122, s[40:41]
	v_cndmask_b32_e64 v163, v117, v123, s[40:41]
	v_cndmask_b32_e64 v164, v124, v118, s[40:41]
	v_cndmask_b32_e64 v165, v125, v119, s[40:41]
	v_cndmask_b32_e64 v166, v118, v126, s[40:41]
	v_cndmask_b32_e64 v167, v119, v127, s[40:41]
	global_store_dwordx4 v[132:133], v[160:163], off
	global_store_dwordx4 v[132:133], v[164:167], off offset:1024
	v_lshl_add_u64 v[132:133], v[132:133], 0, v[154:155]
	s_add_i32 s0, s0, 1
	s_cmp_lt_i32 s0, 3
	s_cbranch_scc1 .Lln0_loop

.LBB0_199:
	v_lshl_add_u32 v160, s46, 8, v250
	v_ashrrev_i32_e32 v161, 31, v160
	v_readlane_b32 s4, v255, 21
	v_lshlrev_b64 v[160:161], 11, v[160:161]
	v_readlane_b32 s5, v255, 22
	s_lshl_b32 s47, s10, 8
	s_andn2_b64 vcc, exec, s[30:31]
	v_lshl_add_u64 v[194:195], s[4:5], 0, v[160:161]
	v_lshlrev_b32_e32 v208, 1, v220
	v_and_b32_e32 v160, 4, v220
	v_mad_u32_u24 v208, v160, 6, v208
	s_cbranch_vccnz .LBB0_201
	s_lshl_b32 s36, s47, 1
	v_lshl_add_u64 v[160:161], v[194:195], 0, s[36:37]
	s_lshl_b32 s36, s2, 1
	v_lshl_add_u64 v[160:161], v[160:161], 0, s[36:37]
	v_lshl_add_u64 v[160:161], v[160:161], 0, v[208:209]
	s_nop 1
	v_permlane16_swap_b32_e32 v152, v154
	v_permlane16_swap_b32_e32 v153, v155
	global_store_dwordx4 v[160:161], v[152:155], off sc1
	s_nop 1

.LBB0_203:
	s_andn2_b64 vcc, exec, s[30:31]
	s_cbranch_vccnz .LBB0_205
	s_lshl_b32 s36, s47, 1
	v_lshl_add_u64 v[132:133], v[194:195], 0, s[36:37]
	s_lshl_b32 s36, s2, 1
	v_lshl_add_u64 v[132:133], v[132:133], 0, s[36:37]
	v_lshl_add_u64 v[132:133], v[132:133], 0, v[208:209]
	s_nop 1
	v_permlane16_swap_b32_e32 v128, v130
	v_permlane16_swap_b32_e32 v129, v131
	global_store_dwordx4 v[132:133], v[128:131], off offset:256 sc1
	s_nop 1

.LBB0_211:
	s_andn2_b64 vcc, exec, s[18:19]
	s_cbranch_vccnz .LBB0_213
	s_lshl_b32 s36, s47, 1
	v_lshl_add_u64 v[176:177], v[194:195], 0, s[36:37]
	s_lshl_b32 s36, s2, 1
	v_lshl_add_u64 v[176:177], v[176:177], 0, s[36:37]
	v_lshl_add_u64 v[176:177], v[176:177], 0, v[208:209]
	v_add_co_u32_e32 v176, vcc, 0x8000, v176
	s_nop 1
	v_addc_co_u32_e32 v177, vcc, 0, v177, vcc
	s_nop 1
	v_permlane16_swap_b32_e32 v172, v174
	v_permlane16_swap_b32_e32 v173, v175
	global_store_dwordx4 v[176:177], v[172:175], off sc1
	s_nop 1

.LBB0_215:
	s_andn2_b64 vcc, exec, s[18:19]
	s_cbranch_vccnz .LBB0_217
	s_lshl_b32 s36, s47, 1
	v_lshl_add_u64 v[164:165], v[194:195], 0, s[36:37]
	s_lshl_b32 s36, s2, 1
	v_lshl_add_u64 v[164:165], v[164:165], 0, s[36:37]
	v_lshl_add_u64 v[164:165], v[164:165], 0, v[208:209]
	v_add_co_u32_e32 v164, vcc, 0x8000, v164
	s_nop 1
	v_addc_co_u32_e32 v165, vcc, 0, v165, vcc
	s_nop 1
	v_permlane16_swap_b32_e32 v148, v150
	v_permlane16_swap_b32_e32 v149, v151
	global_store_dwordx4 v[164:165], v[148:151], off offset:256 sc1
	s_nop 1

.LBB0_223:
	s_andn2_b64 vcc, exec, s[18:19]
	s_cbranch_vccnz .LBB0_225
	s_lshl_b32 s36, s47, 1
	v_lshl_add_u64 v[188:189], v[194:195], 0, s[36:37]
	s_lshl_b32 s36, s2, 1
	v_lshl_add_u64 v[188:189], v[188:189], 0, s[36:37]
	v_lshl_add_u64 v[188:189], v[188:189], 0, v[208:209]
	v_add_co_u32_e32 v188, vcc, 0x10000, v188
	s_nop 1
	v_addc_co_u32_e32 v189, vcc, 0, v189, vcc
	s_nop 1
	v_permlane16_swap_b32_e32 v184, v186
	v_permlane16_swap_b32_e32 v185, v187
	global_store_dwordx4 v[188:189], v[184:187], off sc1
	s_nop 1

.LBB0_227:
	s_andn2_b64 vcc, exec, s[18:19]
	s_cbranch_vccnz .LBB0_229
	s_lshl_b32 s36, s47, 1
	v_lshl_add_u64 v[180:181], v[194:195], 0, s[36:37]
	s_lshl_b32 s36, s2, 1
	v_lshl_add_u64 v[180:181], v[180:181], 0, s[36:37]
	v_lshl_add_u64 v[180:181], v[180:181], 0, v[208:209]
	v_add_co_u32_e32 v180, vcc, 0x10000, v180
	s_nop 1
	v_addc_co_u32_e32 v181, vcc, 0, v181, vcc
	s_nop 1
	v_permlane16_swap_b32_e32 v168, v170
	v_permlane16_swap_b32_e32 v169, v171
	global_store_dwordx4 v[180:181], v[168:171], off offset:256 sc1
	s_nop 1

.LBB0_235:
	s_andn2_b64 vcc, exec, s[18:19]
	s_cbranch_vccnz .LBB0_237
	s_lshl_b32 s36, s47, 1
	v_lshl_add_u64 v[156:157], v[194:195], 0, s[36:37]
	s_lshl_b32 s36, s2, 1
	v_lshl_add_u64 v[156:157], v[156:157], 0, s[36:37]
	v_lshl_add_u64 v[156:157], v[156:157], 0, v[208:209]
	v_add_co_u32_e32 v156, vcc, 0x18000, v156
	s_nop 1
	v_addc_co_u32_e32 v157, vcc, 0, v157, vcc
	s_nop 1
	v_permlane16_swap_b32_e32 v144, v146
	v_permlane16_swap_b32_e32 v145, v147
	global_store_dwordx4 v[156:157], v[144:147], off sc1
	s_nop 1

.LBB0_239:
	s_andn2_b64 vcc, exec, s[18:19]
	s_cbranch_vccnz .LBB0_241
	s_lshl_b32 s36, s47, 1
	v_lshl_add_u64 v[140:141], v[194:195], 0, s[36:37]
	s_lshl_b32 s36, s2, 1
	v_lshl_add_u64 v[140:141], v[140:141], 0, s[36:37]
	v_lshl_add_u64 v[140:141], v[140:141], 0, v[208:209]
	v_add_co_u32_e32 v140, vcc, 0x18000, v140
	s_nop 1
	v_addc_co_u32_e32 v141, vcc, 0, v141, vcc
	s_nop 1
	v_permlane16_swap_b32_e32 v136, v138
	v_permlane16_swap_b32_e32 v137, v139
	global_store_dwordx4 v[140:141], v[136:139], off offset:256 sc1
	s_nop 1

.LBB0_247:
	s_andn2_b64 vcc, exec, s[18:19]
	s_cbranch_vccnz .LBB0_249
	s_lshl_b32 s36, s47, 1
	v_lshl_add_u64 v[160:161], v[194:195], 0, s[36:37]
	s_lshl_b32 s36, s2, 1
	v_lshl_add_u64 v[160:161], v[160:161], 0, s[36:37]
	v_lshl_add_u64 v[160:161], v[160:161], 0, v[208:209]
	v_add_co_u32_e32 v160, vcc, 0x40000, v160
	s_nop 1
	v_addc_co_u32_e32 v161, vcc, 0, v161, vcc
	s_nop 1
	v_permlane16_swap_b32_e32 v152, v154
	v_permlane16_swap_b32_e32 v153, v155
	global_store_dwordx4 v[160:161], v[152:155], off sc1
	s_nop 1

.LBB0_251:
	s_andn2_b64 vcc, exec, s[18:19]
	s_cbranch_vccnz .LBB0_253
	s_lshl_b32 s36, s47, 1
	v_lshl_add_u64 v[132:133], v[194:195], 0, s[36:37]
	s_lshl_b32 s36, s2, 1
	v_lshl_add_u64 v[132:133], v[132:133], 0, s[36:37]
	v_lshl_add_u64 v[132:133], v[132:133], 0, v[208:209]
	v_add_co_u32_e32 v132, vcc, 0x40000, v132
	s_nop 1
	v_addc_co_u32_e32 v133, vcc, 0, v133, vcc
	s_nop 1
	v_permlane16_swap_b32_e32 v128, v130
	v_permlane16_swap_b32_e32 v129, v131
	global_store_dwordx4 v[132:133], v[128:131], off offset:256 sc1
	s_nop 1

.LBB0_255:
	s_andn2_b64 vcc, exec, s[18:19]
	s_cbranch_vccnz .LBB0_257
	s_lshl_b32 s36, s47, 1
	v_lshl_add_u64 v[132:133], v[194:195], 0, s[36:37]
	s_lshl_b32 s36, s2, 1
	v_lshl_add_u64 v[132:133], v[132:133], 0, s[36:37]
	v_lshl_add_u64 v[132:133], v[132:133], 0, v[208:209]
	v_add_co_u32_e32 v132, vcc, 0x48000, v132
	s_nop 1
	v_addc_co_u32_e32 v133, vcc, 0, v133, vcc
	s_nop 1
	v_permlane16_swap_b32_e32 v128, v130
	v_permlane16_swap_b32_e32 v129, v131
	global_store_dwordx4 v[132:133], v[128:131], off sc1
	s_nop 1

.LBB0_259:
	s_andn2_b64 vcc, exec, s[18:19]
	s_cbranch_vccnz .LBB0_261
	s_lshl_b32 s36, s47, 1
	v_lshl_add_u64 v[132:133], v[194:195], 0, s[36:37]
	s_lshl_b32 s36, s2, 1
	v_lshl_add_u64 v[132:133], v[132:133], 0, s[36:37]
	v_lshl_add_u64 v[132:133], v[132:133], 0, v[208:209]
	v_add_co_u32_e32 v132, vcc, 0x48000, v132
	s_nop 1
	v_addc_co_u32_e32 v133, vcc, 0, v133, vcc
	s_nop 1
	v_permlane16_swap_b32_e32 v128, v130
	v_permlane16_swap_b32_e32 v129, v131
	global_store_dwordx4 v[132:133], v[128:131], off offset:256 sc1
	s_nop 1

.LBB0_263:
	s_andn2_b64 vcc, exec, s[18:19]
	s_cbranch_vccnz .LBB0_265
	s_lshl_b32 s36, s47, 1
	v_lshl_add_u64 v[132:133], v[194:195], 0, s[36:37]
	s_lshl_b32 s36, s2, 1
	v_lshl_add_u64 v[132:133], v[132:133], 0, s[36:37]
	v_lshl_add_u64 v[132:133], v[132:133], 0, v[208:209]
	v_add_co_u32_e32 v132, vcc, 0x50000, v132
	s_nop 1
	v_addc_co_u32_e32 v133, vcc, 0, v133, vcc
	s_nop 1
	v_permlane16_swap_b32_e32 v128, v130
	v_permlane16_swap_b32_e32 v129, v131
	global_store_dwordx4 v[132:133], v[128:131], off sc1
	s_nop 1

.LBB0_267:
	s_andn2_b64 vcc, exec, s[18:19]
	s_cbranch_vccnz .LBB0_269
	s_lshl_b32 s36, s47, 1
	v_lshl_add_u64 v[132:133], v[194:195], 0, s[36:37]
	s_lshl_b32 s36, s2, 1
	v_lshl_add_u64 v[132:133], v[132:133], 0, s[36:37]
	v_lshl_add_u64 v[132:133], v[132:133], 0, v[208:209]
	v_add_co_u32_e32 v132, vcc, 0x50000, v132
	s_nop 1
	v_addc_co_u32_e32 v133, vcc, 0, v133, vcc
	s_nop 1
	v_permlane16_swap_b32_e32 v128, v130
	v_permlane16_swap_b32_e32 v129, v131
	global_store_dwordx4 v[132:133], v[128:131], off offset:256 sc1
	s_nop 1

.LBB0_271:
	s_andn2_b64 vcc, exec, s[18:19]
	s_cbranch_vccnz .LBB0_273
	s_lshl_b32 s36, s47, 1
	v_lshl_add_u64 v[132:133], v[194:195], 0, s[36:37]
	s_lshl_b32 s36, s2, 1
	v_lshl_add_u64 v[132:133], v[132:133], 0, s[36:37]
	v_lshl_add_u64 v[132:133], v[132:133], 0, v[208:209]
	v_add_co_u32_e32 v132, vcc, 0x58000, v132
	s_nop 1
	v_addc_co_u32_e32 v133, vcc, 0, v133, vcc
	s_nop 1
	v_permlane16_swap_b32_e32 v128, v130
	v_permlane16_swap_b32_e32 v129, v131
	global_store_dwordx4 v[132:133], v[128:131], off sc1
	s_nop 1

.LBB0_277:
	s_lshl_b32 s36, s47, 1
	v_lshl_add_u64 v[132:133], v[194:195], 0, s[36:37]
	s_lshl_b32 s36, s2, 1
	v_lshl_add_u64 v[132:133], v[132:133], 0, s[36:37]
	v_lshl_add_u64 v[132:133], v[132:133], 0, v[208:209]
	v_add_co_u32_e32 v132, vcc, 0x58000, v132
	s_nop 1
	v_addc_co_u32_e32 v133, vcc, 0, v133, vcc
	s_nop 1
	v_permlane16_swap_b32_e32 v128, v130
	v_permlane16_swap_b32_e32 v129, v131
	global_store_dwordx4 v[132:133], v[128:131], off offset:256 sc1
	s_nop 1
	s_andn2_b64 vcc, exec, s[0:1]
	s_cbranch_vccnz .LBB0_282

.LBB0_313:
	v_mov_b32_e32 v0, v221
	v_readlane_b32 s0, v253, 16
	s_nop 1
	v_add_u32_e32 v2, s0, v0
	s_mov_b32 s0, 0x240000
	v_cmp_gt_i32_e32 vcc, s0, v2
	s_and_saveexec_b64 s[10:11], vcc
	s_cbranch_execz .LBB0_326
	v_readlane_b32 s43, v254, 38
	v_lshrrev_b32_e32 v124, 6, v221
	v_and_b32_e32 v125, 63, v221
	v_mov_b32_e32 v120, 0x400000
	v_mov_b32_e32 v121, 0
	v_add_u32_e32 v124, s43, v124
	v_lshlrev_b32_e32 v122, 4, v125
	v_mov_b32_e32 v123, 0
	v_readfirstlane_b32 s0, v124
	v_lshl_add_u32 v126, v124, 11, v122
	v_mov_b32_e32 v127, 0
	s_add_u32 s44, s60, 0x10900400
	s_addc_u32 s45, s61, 0
	v_lshl_add_u64 v[116:117], s[44:45], 0, v[126:127]
	v_mov_b32_e32 v118, v116
	v_mov_b32_e32 v119, v117
	s_mov_b32 s1, s0
	s_mov_b32 s2, 0
	v_readlane_b32 s43, v255, 6
	s_mul_i32 s43, s43, 0x1800
	s_addk_i32 s43, 0x800
	s_add_u32 s44, s88, s43
	s_addc_u32 s45, s89, 0
	v_lshlrev_b32_e32 v126, 5, v125
	v_lshl_add_u64 v[126:127], s[44:45], 0, v[126:127]
	global_load_dwordx4 v[48:51], v[126:127], off offset:-2048
	global_load_dwordx4 v[52:55], v[126:127], off offset:-2032
	global_load_dwordx4 v[56:59], v[126:127], off offset:0
	global_load_dwordx4 v[60:63], v[126:127], off offset:16
	global_load_dwordx4 v[64:67], v[126:127], off offset:2048
	global_load_dwordx4 v[68:71], v[126:127], off offset:2064
	s_cmpk_lt_u32 s0, 0x1000
	s_cselect_b32 s19, 4, 0
	s_cselect_b32 s42, 0, 0x1000
	s_lshr_b32 s19, 0xfff, s19
	s_sub_u32 s18, s0, s42
	s_and_b32 s18, s18, s19
	global_load_dwordx4 v[4:7], v[116:117], off
	s_cmp_eq_u32 s18, 0
	s_cbranch_scc1 .Lconv_f6
	global_load_dwordx4 v[0:3], v[116:117], off offset:-2048
	s_branch .Lconv_g6
.Lconv_f6:
	global_load_dwordx4 v[0:3], v[116:117], off
.Lconv_g6:
	s_cmp_eq_u32 s18, s19
	s_cbranch_scc1 .Lconv_h6
	global_load_dwordx4 v[8:11], v[116:117], off offset:2048
	s_branch .Lconv_i6
.Lconv_h6:
	global_load_dwordx4 v[8:11], v[116:117], off
.Lconv_i6:
	global_load_dwordx4 v[12:15], v[116:117], off offset:-1024 nt
	v_lshl_add_u64 v[116:117], v[116:117], 0, v[120:121]
	s_addk_i32 s0, 0x800
	global_load_dword v128, v[126:127], off
	s_cmpk_lt_u32 s0, 0x1000
	s_cselect_b32 s19, 4, 0
	s_cselect_b32 s42, 0, 0x1000
	s_lshr_b32 s19, 0xfff, s19
	s_sub_u32 s18, s0, s42
	s_and_b32 s18, s18, s19
	global_load_dwordx4 v[20:23], v[116:117], off
	s_cmp_eq_u32 s18, 0
	s_cbranch_scc1 .Lconv_f7
	global_load_dwordx4 v[16:19], v[116:117], off offset:-2048
	s_branch .Lconv_g7
.Lconv_f7:
	global_load_dwordx4 v[16:19], v[116:117], off
.Lconv_g7:
	s_cmp_eq_u32 s18, s19
	s_cbranch_scc1 .Lconv_h7
	global_load_dwordx4 v[24:27], v[116:117], off offset:2048
	s_branch .Lconv_i7
.Lconv_h7:
	global_load_dwordx4 v[24:27], v[116:117], off
.Lconv_i7:
	global_load_dwordx4 v[28:31], v[116:117], off offset:-1024 nt
	v_lshl_add_u64 v[116:117], v[116:117], 0, v[120:121]
	s_addk_i32 s0, 0x800
	global_load_dword v128, v[126:127], off
.Lconv_loop:
	s_cmpk_lt_u32 s0, 0x1000
	s_cselect_b32 s19, 4, 0
	s_cselect_b32 s42, 0, 0x1000
	s_lshr_b32 s19, 0xfff, s19
	s_sub_u32 s18, s0, s42
	s_and_b32 s18, s18, s19
	global_load_dwordx4 v[36:39], v[116:117], off
	s_cmp_eq_u32 s18, 0
	s_cbranch_scc1 .Lconv_f0
	global_load_dwordx4 v[32:35], v[116:117], off offset:-2048
	s_branch .Lconv_g0
.Lconv_f0:
	global_load_dwordx4 v[32:35], v[116:117], off
.Lconv_g0:
	s_cmp_eq_u32 s18, s19
	s_cbranch_scc1 .Lconv_h0
	global_load_dwordx4 v[40:43], v[116:117], off offset:2048
	s_branch .Lconv_i0
.Lconv_h0:
	global_load_dwordx4 v[40:43], v[116:117], off
.Lconv_i0:
	global_load_dwordx4 v[44:47], v[116:117], off offset:-1024 nt
	v_lshl_add_u64 v[116:117], v[116:117], 0, v[120:121]
	s_addk_i32 s0, 0x800
	s_waitcnt vmcnt(10)
	s_cmpk_lt_u32 s1, 0x1000
	s_cselect_b32 s19, 4, 0
	s_cselect_b32 s42, 0, 0x1000
	s_lshr_b32 s19, 0xfff, s19
	s_sub_u32 s18, s1, s42
	s_and_b32 s18, s18, s19
	s_cmp_lg_u32 s18, 0
	s_cbranch_scc1 .Lconv_j0
	v_mov_b32_e32 v0, 0
	v_mov_b32_e32 v1, 0
	v_mov_b32_e32 v2, 0
	v_mov_b32_e32 v3, 0
.Lconv_j0:
	s_cmp_lg_u32 s18, s19
	s_cbranch_scc1 .Lconv_k0
	v_mov_b32_e32 v8, 0
	v_mov_b32_e32 v9, 0
	v_mov_b32_e32 v10, 0
	v_mov_b32_e32 v11, 0
.Lconv_k0:
	v_lshlrev_b32_e32 v80, 16, v4
	v_and_b32_e32 v81, 0xffff0000, v4
	v_lshlrev_b32_e32 v82, 16, v5
	v_and_b32_e32 v83, 0xffff0000, v5
	v_lshlrev_b32_e32 v84, 16, v6
	v_and_b32_e32 v85, 0xffff0000, v6
	v_lshlrev_b32_e32 v86, 16, v7
	v_and_b32_e32 v87, 0xffff0000, v7
	v_pk_mul_f32 v[104:105], v[56:57], v[80:81]
	v_pk_mul_f32 v[106:107], v[58:59], v[82:83]
	v_pk_mul_f32 v[108:109], v[60:61], v[84:85]
	v_pk_mul_f32 v[110:111], v[62:63], v[86:87]
	v_lshlrev_b32_e32 v72, 16, v0
	v_and_b32_e32 v73, 0xffff0000, v0
	v_lshlrev_b32_e32 v74, 16, v1
	v_and_b32_e32 v75, 0xffff0000, v1
	v_lshlrev_b32_e32 v76, 16, v2
	v_and_b32_e32 v77, 0xffff0000, v2
	v_lshlrev_b32_e32 v78, 16, v3
	v_and_b32_e32 v79, 0xffff0000, v3
	v_pk_fma_f32 v[104:105], v[48:49], v[72:73], v[104:105]
	v_pk_fma_f32 v[106:107], v[50:51], v[74:75], v[106:107]
	v_pk_fma_f32 v[108:109], v[52:53], v[76:77], v[108:109]
	v_pk_fma_f32 v[110:111], v[54:55], v[78:79], v[110:111]
	v_lshlrev_b32_e32 v88, 16, v8
	v_and_b32_e32 v89, 0xffff0000, v8
	v_lshlrev_b32_e32 v90, 16, v9
	v_and_b32_e32 v91, 0xffff0000, v9
	v_lshlrev_b32_e32 v92, 16, v10
	v_and_b32_e32 v93, 0xffff0000, v10
	v_lshlrev_b32_e32 v94, 16, v11
	v_and_b32_e32 v95, 0xffff0000, v11
	v_pk_fma_f32 v[104:105], v[64:65], v[88:89], v[104:105]
	v_pk_fma_f32 v[106:107], v[66:67], v[90:91], v[106:107]
	v_pk_fma_f32 v[108:109], v[68:69], v[92:93], v[108:109]
	v_pk_fma_f32 v[110:111], v[70:71], v[94:95], v[110:111]
	v_lshlrev_b32_e32 v96, 16, v12
	v_and_b32_e32 v97, 0xffff0000, v12
	v_lshlrev_b32_e32 v98, 16, v13
	v_and_b32_e32 v99, 0xffff0000, v13
	v_lshlrev_b32_e32 v100, 16, v14
	v_and_b32_e32 v101, 0xffff0000, v14
	v_lshlrev_b32_e32 v102, 16, v15
	v_and_b32_e32 v103, 0xffff0000, v15
	v_pk_mul_f32 v[104:105], v[104:105], v[96:97]
	v_pk_mul_f32 v[106:107], v[106:107], v[98:99]
	v_pk_mul_f32 v[108:109], v[108:109], v[100:101]
	v_pk_mul_f32 v[110:111], v[110:111], v[102:103]
	v_cvt_pk_bf16_f32 v112, v104, v105
	v_cvt_pk_bf16_f32 v113, v106, v107
	v_cvt_pk_bf16_f32 v114, v108, v109
	v_cvt_pk_bf16_f32 v115, v110, v111
	global_store_dwordx4 v[118:119], v[112:115], off offset:-1024
	v_lshl_add_u64 v[118:119], v[118:119], 0, v[120:121]
	s_addk_i32 s1, 0x800
	s_cmpk_lt_u32 s0, 0x1000
	s_cselect_b32 s19, 4, 0
	s_cselect_b32 s42, 0, 0x1000
	s_lshr_b32 s19, 0xfff, s19
	s_sub_u32 s18, s0, s42
	s_and_b32 s18, s18, s19
	global_load_dwordx4 v[4:7], v[116:117], off
	s_cmp_eq_u32 s18, 0
	s_cbranch_scc1 .Lconv_f1
	global_load_dwordx4 v[0:3], v[116:117], off offset:-2048
	s_branch .Lconv_g1

.Lconv_i1:
	global_load_dwordx4 v[12:15], v[116:117], off offset:-1024 nt
	v_lshl_add_u64 v[116:117], v[116:117], 0, v[120:121]
	s_addk_i32 s0, 0x800
	s_waitcnt vmcnt(10)
	s_cmpk_lt_u32 s1, 0x1000
	s_cselect_b32 s19, 4, 0
	s_cselect_b32 s42, 0, 0x1000
	s_lshr_b32 s19, 0xfff, s19
	s_sub_u32 s18, s1, s42
	s_and_b32 s18, s18, s19
	s_cmp_lg_u32 s18, 0
	s_cbranch_scc1 .Lconv_j1
	v_mov_b32_e32 v16, 0
	v_mov_b32_e32 v17, 0
	v_mov_b32_e32 v18, 0
	v_mov_b32_e32 v19, 0
.Lconv_j1:
	s_cmp_lg_u32 s18, s19
	s_cbranch_scc1 .Lconv_k1
	v_mov_b32_e32 v24, 0
	v_mov_b32_e32 v25, 0
	v_mov_b32_e32 v26, 0
	v_mov_b32_e32 v27, 0
.Lconv_k1:
	v_lshlrev_b32_e32 v80, 16, v20
	v_and_b32_e32 v81, 0xffff0000, v20
	v_lshlrev_b32_e32 v82, 16, v21
	v_and_b32_e32 v83, 0xffff0000, v21
	v_lshlrev_b32_e32 v84, 16, v22
	v_and_b32_e32 v85, 0xffff0000, v22
	v_lshlrev_b32_e32 v86, 16, v23
	v_and_b32_e32 v87, 0xffff0000, v23
	v_pk_mul_f32 v[104:105], v[56:57], v[80:81]
	v_pk_mul_f32 v[106:107], v[58:59], v[82:83]
	v_pk_mul_f32 v[108:109], v[60:61], v[84:85]
	v_pk_mul_f32 v[110:111], v[62:63], v[86:87]
	v_lshlrev_b32_e32 v72, 16, v16
	v_and_b32_e32 v73, 0xffff0000, v16
	v_lshlrev_b32_e32 v74, 16, v17
	v_and_b32_e32 v75, 0xffff0000, v17
	v_lshlrev_b32_e32 v76, 16, v18
	v_and_b32_e32 v77, 0xffff0000, v18
	v_lshlrev_b32_e32 v78, 16, v19
	v_and_b32_e32 v79, 0xffff0000, v19
	v_pk_fma_f32 v[104:105], v[48:49], v[72:73], v[104:105]
	v_pk_fma_f32 v[106:107], v[50:51], v[74:75], v[106:107]
	v_pk_fma_f32 v[108:109], v[52:53], v[76:77], v[108:109]
	v_pk_fma_f32 v[110:111], v[54:55], v[78:79], v[110:111]
	v_lshlrev_b32_e32 v88, 16, v24
	v_and_b32_e32 v89, 0xffff0000, v24
	v_lshlrev_b32_e32 v90, 16, v25
	v_and_b32_e32 v91, 0xffff0000, v25
	v_lshlrev_b32_e32 v92, 16, v26
	v_and_b32_e32 v93, 0xffff0000, v26
	v_lshlrev_b32_e32 v94, 16, v27
	v_and_b32_e32 v95, 0xffff0000, v27
	v_pk_fma_f32 v[104:105], v[64:65], v[88:89], v[104:105]
	v_pk_fma_f32 v[106:107], v[66:67], v[90:91], v[106:107]
	v_pk_fma_f32 v[108:109], v[68:69], v[92:93], v[108:109]
	v_pk_fma_f32 v[110:111], v[70:71], v[94:95], v[110:111]
	v_lshlrev_b32_e32 v96, 16, v28
	v_and_b32_e32 v97, 0xffff0000, v28
	v_lshlrev_b32_e32 v98, 16, v29
	v_and_b32_e32 v99, 0xffff0000, v29
	v_lshlrev_b32_e32 v100, 16, v30
	v_and_b32_e32 v101, 0xffff0000, v30
	v_lshlrev_b32_e32 v102, 16, v31
	v_and_b32_e32 v103, 0xffff0000, v31
	v_pk_mul_f32 v[104:105], v[104:105], v[96:97]
	v_pk_mul_f32 v[106:107], v[106:107], v[98:99]
	v_pk_mul_f32 v[108:109], v[108:109], v[100:101]
	v_pk_mul_f32 v[110:111], v[110:111], v[102:103]
	v_cvt_pk_bf16_f32 v112, v104, v105
	v_cvt_pk_bf16_f32 v113, v106, v107
	v_cvt_pk_bf16_f32 v114, v108, v109
	v_cvt_pk_bf16_f32 v115, v110, v111
	global_store_dwordx4 v[118:119], v[112:115], off offset:-1024
	v_lshl_add_u64 v[118:119], v[118:119], 0, v[120:121]
	s_addk_i32 s1, 0x800
	s_cmpk_lt_u32 s0, 0x1000
	s_cselect_b32 s19, 4, 0
	s_cselect_b32 s42, 0, 0x1000
	s_lshr_b32 s19, 0xfff, s19
	s_sub_u32 s18, s0, s42
	s_and_b32 s18, s18, s19
	global_load_dwordx4 v[20:23], v[116:117], off
	s_cmp_eq_u32 s18, 0
	s_cbranch_scc1 .Lconv_f2
	global_load_dwordx4 v[16:19], v[116:117], off offset:-2048
	s_branch .Lconv_g2

.Lconv_i2:
	global_load_dwordx4 v[28:31], v[116:117], off offset:-1024 nt
	v_lshl_add_u64 v[116:117], v[116:117], 0, v[120:121]
	s_addk_i32 s0, 0x800
	s_waitcnt vmcnt(10)
	s_cmpk_lt_u32 s1, 0x1000
	s_cselect_b32 s19, 4, 0
	s_cselect_b32 s42, 0, 0x1000
	s_lshr_b32 s19, 0xfff, s19
	s_sub_u32 s18, s1, s42
	s_and_b32 s18, s18, s19
	s_cmp_lg_u32 s18, 0
	s_cbranch_scc1 .Lconv_j2
	v_mov_b32_e32 v32, 0
	v_mov_b32_e32 v33, 0
	v_mov_b32_e32 v34, 0
	v_mov_b32_e32 v35, 0
.Lconv_j2:
	s_cmp_lg_u32 s18, s19
	s_cbranch_scc1 .Lconv_k2
	v_mov_b32_e32 v40, 0
	v_mov_b32_e32 v41, 0
	v_mov_b32_e32 v42, 0
	v_mov_b32_e32 v43, 0
.Lconv_k2:
	v_lshlrev_b32_e32 v80, 16, v36
	v_and_b32_e32 v81, 0xffff0000, v36
	v_lshlrev_b32_e32 v82, 16, v37
	v_and_b32_e32 v83, 0xffff0000, v37
	v_lshlrev_b32_e32 v84, 16, v38
	v_and_b32_e32 v85, 0xffff0000, v38
	v_lshlrev_b32_e32 v86, 16, v39
	v_and_b32_e32 v87, 0xffff0000, v39
	v_pk_mul_f32 v[104:105], v[56:57], v[80:81]
	v_pk_mul_f32 v[106:107], v[58:59], v[82:83]
	v_pk_mul_f32 v[108:109], v[60:61], v[84:85]
	v_pk_mul_f32 v[110:111], v[62:63], v[86:87]
	v_lshlrev_b32_e32 v72, 16, v32
	v_and_b32_e32 v73, 0xffff0000, v32
	v_lshlrev_b32_e32 v74, 16, v33
	v_and_b32_e32 v75, 0xffff0000, v33
	v_lshlrev_b32_e32 v76, 16, v34
	v_and_b32_e32 v77, 0xffff0000, v34
	v_lshlrev_b32_e32 v78, 16, v35
	v_and_b32_e32 v79, 0xffff0000, v35
	v_pk_fma_f32 v[104:105], v[48:49], v[72:73], v[104:105]
	v_pk_fma_f32 v[106:107], v[50:51], v[74:75], v[106:107]
	v_pk_fma_f32 v[108:109], v[52:53], v[76:77], v[108:109]
	v_pk_fma_f32 v[110:111], v[54:55], v[78:79], v[110:111]
	v_lshlrev_b32_e32 v88, 16, v40
	v_and_b32_e32 v89, 0xffff0000, v40
	v_lshlrev_b32_e32 v90, 16, v41
	v_and_b32_e32 v91, 0xffff0000, v41
	v_lshlrev_b32_e32 v92, 16, v42
	v_and_b32_e32 v93, 0xffff0000, v42
	v_lshlrev_b32_e32 v94, 16, v43
	v_and_b32_e32 v95, 0xffff0000, v43
	v_pk_fma_f32 v[104:105], v[64:65], v[88:89], v[104:105]
	v_pk_fma_f32 v[106:107], v[66:67], v[90:91], v[106:107]
	v_pk_fma_f32 v[108:109], v[68:69], v[92:93], v[108:109]
	v_pk_fma_f32 v[110:111], v[70:71], v[94:95], v[110:111]
	v_lshlrev_b32_e32 v96, 16, v44
	v_and_b32_e32 v97, 0xffff0000, v44
	v_lshlrev_b32_e32 v98, 16, v45
	v_and_b32_e32 v99, 0xffff0000, v45
	v_lshlrev_b32_e32 v100, 16, v46
	v_and_b32_e32 v101, 0xffff0000, v46
	v_lshlrev_b32_e32 v102, 16, v47
	v_and_b32_e32 v103, 0xffff0000, v47
	v_pk_mul_f32 v[104:105], v[104:105], v[96:97]
	v_pk_mul_f32 v[106:107], v[106:107], v[98:99]
	v_pk_mul_f32 v[108:109], v[108:109], v[100:101]
	v_pk_mul_f32 v[110:111], v[110:111], v[102:103]
	v_cvt_pk_bf16_f32 v112, v104, v105
	v_cvt_pk_bf16_f32 v113, v106, v107
	v_cvt_pk_bf16_f32 v114, v108, v109
	v_cvt_pk_bf16_f32 v115, v110, v111
	global_store_dwordx4 v[118:119], v[112:115], off offset:-1024
	v_lshl_add_u64 v[118:119], v[118:119], 0, v[120:121]
	s_addk_i32 s1, 0x800
	s_cmpk_lt_u32 s0, 0x1000
	s_cselect_b32 s19, 4, 0
	s_cselect_b32 s42, 0, 0x1000
	s_lshr_b32 s19, 0xfff, s19
	s_sub_u32 s18, s0, s42
	s_and_b32 s18, s18, s19
	global_load_dwordx4 v[36:39], v[116:117], off
	s_cmp_eq_u32 s18, 0
	s_cbranch_scc1 .Lconv_f3
	global_load_dwordx4 v[32:35], v[116:117], off offset:-2048
	s_branch .Lconv_g3

.Lconv_k5:
	v_lshlrev_b32_e32 v80, 16, v36
	v_and_b32_e32 v81, 0xffff0000, v36
	v_lshlrev_b32_e32 v82, 16, v37
	v_and_b32_e32 v83, 0xffff0000, v37
	v_lshlrev_b32_e32 v84, 16, v38
	v_and_b32_e32 v85, 0xffff0000, v38
	v_lshlrev_b32_e32 v86, 16, v39
	v_and_b32_e32 v87, 0xffff0000, v39
	v_pk_mul_f32 v[104:105], v[56:57], v[80:81]
	v_pk_mul_f32 v[106:107], v[58:59], v[82:83]
	v_pk_mul_f32 v[108:109], v[60:61], v[84:85]
	v_pk_mul_f32 v[110:111], v[62:63], v[86:87]
	v_lshlrev_b32_e32 v72, 16, v32
	v_and_b32_e32 v73, 0xffff0000, v32
	v_lshlrev_b32_e32 v74, 16, v33
	v_and_b32_e32 v75, 0xffff0000, v33
	v_lshlrev_b32_e32 v76, 16, v34
	v_and_b32_e32 v77, 0xffff0000, v34
	v_lshlrev_b32_e32 v78, 16, v35
	v_and_b32_e32 v79, 0xffff0000, v35
	v_pk_fma_f32 v[104:105], v[48:49], v[72:73], v[104:105]
	v_pk_fma_f32 v[106:107], v[50:51], v[74:75], v[106:107]
	v_pk_fma_f32 v[108:109], v[52:53], v[76:77], v[108:109]
	v_pk_fma_f32 v[110:111], v[54:55], v[78:79], v[110:111]
	v_lshlrev_b32_e32 v88, 16, v40
	v_and_b32_e32 v89, 0xffff0000, v40
	v_lshlrev_b32_e32 v90, 16, v41
	v_and_b32_e32 v91, 0xffff0000, v41
	v_lshlrev_b32_e32 v92, 16, v42
	v_and_b32_e32 v93, 0xffff0000, v42
	v_lshlrev_b32_e32 v94, 16, v43
	v_and_b32_e32 v95, 0xffff0000, v43
	v_pk_fma_f32 v[104:105], v[64:65], v[88:89], v[104:105]
	v_pk_fma_f32 v[106:107], v[66:67], v[90:91], v[106:107]
	v_pk_fma_f32 v[108:109], v[68:69], v[92:93], v[108:109]
	v_pk_fma_f32 v[110:111], v[70:71], v[94:95], v[110:111]
	v_lshlrev_b32_e32 v96, 16, v44
	v_and_b32_e32 v97, 0xffff0000, v44
	v_lshlrev_b32_e32 v98, 16, v45
	v_and_b32_e32 v99, 0xffff0000, v45
	v_lshlrev_b32_e32 v100, 16, v46
	v_and_b32_e32 v101, 0xffff0000, v46
	v_lshlrev_b32_e32 v102, 16, v47
	v_and_b32_e32 v103, 0xffff0000, v47
	v_pk_mul_f32 v[104:105], v[104:105], v[96:97]
	v_pk_mul_f32 v[106:107], v[106:107], v[98:99]
	v_pk_mul_f32 v[108:109], v[108:109], v[100:101]
	v_pk_mul_f32 v[110:111], v[110:111], v[102:103]
	v_cvt_pk_bf16_f32 v112, v104, v105
	v_cvt_pk_bf16_f32 v113, v106, v107
	v_cvt_pk_bf16_f32 v114, v108, v109
	v_cvt_pk_bf16_f32 v115, v110, v111
	global_store_dwordx4 v[118:119], v[112:115], off offset:-1024
	v_lshl_add_u64 v[118:119], v[118:119], 0, v[120:121]
	s_addk_i32 s1, 0x800
	s_add_i32 s2, s2, 1
	s_cmp_lt_i32 s2, 3
	s_cbranch_scc1 .Lconv_loop

.LBB0_430:
	s_nop 0
	v_readlane_b32 s4, v255, 11
	v_readlane_b32 s5, v255, 12
	s_andn2_b64 vcc, exec, s[4:5]
	s_cbranch_vccnz .LBB0_439
	v_readlane_b32 s40, v255, 6
	s_nop 1
	s_cmp_lg_u32 s40, 0
	s_cbranch_scc1 .Lln1_layer1
	v_readlane_b32 s2, v254, 38
	v_lshrrev_b32_e32 v146, 6, v221
	v_and_b32_e32 v112, 63, v221
	v_mov_b32_e32 v152, 0x800000
	v_mov_b32_e32 v153, 0
	v_mov_b32_e32 v154, 0x400000
	v_mov_b32_e32 v155, 0
	v_mov_b32_e32 v156, 0x3000
	v_mov_b32_e32 v157, 0
	v_add_u32_e32 v146, s2, v146
	v_lshlrev_b32_e32 v148, 4, v112
	v_mov_b32_e32 v149, 0
	v_lshlrev_b32_e32 v150, 3, v112
	v_mov_b32_e32 v151, 0
	v_lshl_add_u32 v140, v146, 12, v148
	v_mov_b32_e32 v141, 0
	v_mov_b32_e32 v142, 0xba800000
	s_mov_b32 s0, 0
	v_add_u32_e32 v114, 0x1c000, v148
	v_mov_b32_e32 v115, 0
	v_lshl_add_u64 v[134:135], s[60:61], 0, v[114:115]
	v_and_b32_e32 v116, 1, v112
	v_cmp_eq_u32_e64 s[40:41], 1, v116
	v_lshlrev_b32_e32 v114, 3, v112
	v_mov_b32_e32 v117, 0x1f8
	v_cndmask_b32_e64 v117, 0, v117, s[40:41]
	v_add_u32_e32 v114, v114, v117
	v_lshl_add_u32 v114, v146, 11, v114
	s_add_u32 s42, s60, 0x3100000
	s_addc_u32 s43, s61, 0
	v_lshl_add_u64 v[132:133], s[42:43], 0, v[114:115]
	v_lshl_add_u64 v[128:129], s[98:99], 0, v[140:141]
	v_mov_b32_e32 v130, v128
	v_mov_b32_e32 v131, v129
	v_readlane_b32 s42, v255, 6
	s_lshl_b32 s42, s42, 12
	s_add_u32 s44, s94, s42
	s_addc_u32 s45, s95, 0
	s_add_u32 s42, s96, s42
	s_addc_u32 s43, s97, 0
	v_lshl_add_u64 v[136:137], s[44:45], 0, v[148:149]
	v_lshl_add_u64 v[138:139], s[42:43], 0, v[148:149]
	global_load_dwordx4 v[80:83], v[136:137], off
	global_load_dwordx4 v[84:87], v[136:137], off offset:1024
	global_load_dwordx4 v[88:91], v[136:137], off offset:2048
	global_load_dwordx4 v[92:95], v[136:137], off offset:3072
	global_load_dwordx4 v[96:99], v[138:139], off
	global_load_dwordx4 v[100:103], v[138:139], off offset:1024
	global_load_dwordx4 v[104:107], v[138:139], off offset:2048
	global_load_dwordx4 v[108:111], v[138:139], off offset:3072
	global_load_dwordx4 v[0:3], v[128:129], off nt
	global_load_dwordx4 v[4:7], v[128:129], off offset:1024 nt
	global_load_dwordx4 v[8:11], v[128:129], off offset:2048 nt
	global_load_dwordx4 v[12:15], v[128:129], off offset:3072 nt
	v_lshl_add_u64 v[128:129], v[128:129], 0, v[152:153]
	global_load_dword v158, v[134:135], off
	global_load_dword v158, v[134:135], off
	global_load_dword v158, v[134:135], off
	global_load_dword v158, v[134:135], off
	global_load_dword v158, v[134:135], off
	global_load_dword v158, v[134:135], off
	global_load_dwordx4 v[16:19], v[128:129], off nt
	global_load_dwordx4 v[20:23], v[128:129], off offset:1024 nt
	global_load_dwordx4 v[24:27], v[128:129], off offset:2048 nt
	global_load_dwordx4 v[28:31], v[128:129], off offset:3072 nt
	v_lshl_add_u64 v[128:129], v[128:129], 0, v[152:153]
	global_load_dword v158, v[134:135], off
	global_load_dword v158, v[134:135], off
	global_load_dword v158, v[134:135], off
	global_load_dword v158, v[134:135], off
	global_load_dword v158, v[134:135], off
	global_load_dword v158, v[134:135], off
.Lln1a_loop:
	global_load_dwordx4 v[48:51], v[134:135], off offset:-4096
	global_load_dwordx4 v[52:55], v[134:135], off offset:-3072
	global_load_dwordx4 v[56:59], v[134:135], off offset:-2048
	global_load_dwordx4 v[60:63], v[134:135], off offset:-1024
	global_load_dwordx4 v[64:67], v[134:135], off
	global_load_dwordx4 v[68:71], v[134:135], off offset:1024
	global_load_dwordx4 v[72:75], v[134:135], off offset:2048
	global_load_dwordx4 v[76:79], v[134:135], off offset:3072
	v_lshl_add_u64 v[134:135], v[134:135], 0, v[156:157]
	global_load_dwordx4 v[32:35], v[128:129], off nt
	global_load_dwordx4 v[36:39], v[128:129], off offset:1024 nt
	global_load_dwordx4 v[40:43], v[128:129], off offset:2048 nt
	global_load_dwordx4 v[44:47], v[128:129], off offset:3072 nt
	v_lshl_add_u64 v[128:129], v[128:129], 0, v[152:153]
	s_waitcnt vmcnt(28)
	v_add_f32_e32 v112, v0, v1
	v_add_f32_e32 v113, v2, v3
	v_add_f32_e32 v114, v4, v5
	v_add_f32_e32 v115, v6, v7
	v_add_f32_e32 v116, v8, v9
	v_add_f32_e32 v117, v10, v11
	v_add_f32_e32 v118, v12, v13
	v_add_f32_e32 v119, v14, v15
	v_add_f32_e32 v112, v112, v116
	v_add_f32_e32 v113, v113, v117
	v_add_f32_e32 v114, v114, v118
	v_add_f32_e32 v115, v115, v119
	v_add_f32_e32 v112, v112, v113
	v_add_f32_e32 v114, v114, v115
	v_add_f32_e32 v112, v112, v114
	s_nop 1
	v_add_f32_dpp v112, v112, v112 quad_perm:[1,0,3,2] row_mask:0xf bank_mask:0xf
	s_nop 1
	v_add_f32_dpp v112, v112, v112 quad_perm:[2,3,0,1] row_mask:0xf bank_mask:0xf
	s_nop 1
	v_add_f32_dpp v112, v112, v112 row_half_mirror row_mask:0xf bank_mask:0xf
	s_nop 1
	v_add_f32_dpp v112, v112, v112 row_mirror row_mask:0xf bank_mask:0xf
	s_nop 1
	v_add_f32_dpp v112, v112, v112 row_bcast:15 row_mask:0xa bank_mask:0xf
	s_nop 1
	v_add_f32_dpp v112, v112, v112 row_bcast:31 row_mask:0xc bank_mask:0xf
	s_nop 1
	v_readlane_b32 s2, v112, 63
	s_nop 1
	v_fmac_f32_e32 v0, s2, v142
	v_fmac_f32_e32 v1, s2, v142
	v_fmac_f32_e32 v2, s2, v142
	v_fmac_f32_e32 v3, s2, v142
	v_fmac_f32_e32 v4, s2, v142
	v_fmac_f32_e32 v5, s2, v142
	v_fmac_f32_e32 v6, s2, v142
	v_fmac_f32_e32 v7, s2, v142
	v_fmac_f32_e32 v8, s2, v142
	v_fmac_f32_e32 v9, s2, v142
	v_fmac_f32_e32 v10, s2, v142
	v_fmac_f32_e32 v11, s2, v142
	v_fmac_f32_e32 v12, s2, v142
	v_fmac_f32_e32 v13, s2, v142
	v_fmac_f32_e32 v14, s2, v142
	v_fmac_f32_e32 v15, s2, v142
	v_mul_f32_e32 v112, v0, v0
	v_mul_f32_e32 v113, v1, v1
	v_mul_f32_e32 v114, v2, v2
	v_mul_f32_e32 v115, v3, v3
	v_fmac_f32_e32 v112, v4, v4
	v_fmac_f32_e32 v113, v5, v5
	v_fmac_f32_e32 v114, v6, v6
	v_fmac_f32_e32 v115, v7, v7
	v_fmac_f32_e32 v112, v8, v8
	v_fmac_f32_e32 v113, v9, v9
	v_fmac_f32_e32 v114, v10, v10
	v_fmac_f32_e32 v115, v11, v11
	v_fmac_f32_e32 v112, v12, v12
	v_fmac_f32_e32 v113, v13, v13
	v_fmac_f32_e32 v114, v14, v14
	v_fmac_f32_e32 v115, v15, v15
	v_add_f32_e32 v112, v112, v113
	v_add_f32_e32 v114, v114, v115
	v_add_f32_e32 v112, v112, v114
	s_nop 1
	v_add_f32_dpp v112, v112, v112 quad_perm:[1,0,3,2] row_mask:0xf bank_mask:0xf
	s_nop 1
	v_add_f32_dpp v112, v112, v112 quad_perm:[2,3,0,1] row_mask:0xf bank_mask:0xf
	s_nop 1
	v_add_f32_dpp v112, v112, v112 row_half_mirror row_mask:0xf bank_mask:0xf
	s_nop 1
	v_add_f32_dpp v112, v112, v112 row_mirror row_mask:0xf bank_mask:0xf
	s_nop 1
	v_add_f32_dpp v112, v112, v112 row_bcast:15 row_mask:0xa bank_mask:0xf
	s_nop 1
	v_add_f32_dpp v112, v112, v112 row_bcast:31 row_mask:0xc bank_mask:0xf
	s_nop 1
	v_readlane_b32 s2, v112, 63
	s_nop 1
	v_mov_b32_e32 v113, 0x358637bd
	v_mov_b32_e32 v114, 0x3a800000
	v_fmac_f32_e32 v113, s2, v114
	v_rsq_f32_e32 v115, v113
	v_mul_f32_e32 v113, 0.5, v113
	v_mul_f32_e32 v116, v115, v115
	v_mov_b32_e32 v117, 0x3fc00000
	v_fma_f32 v116, -v113, v116, v117
	v_mul_f32_e32 v144, v115, v116
	v_pk_mul_f32 v[0:1], v[0:1], v[144:145] op_sel_hi:[1,0]
	v_pk_mul_f32 v[2:3], v[2:3], v[144:145] op_sel_hi:[1,0]
	v_pk_mul_f32 v[4:5], v[4:5], v[144:145] op_sel_hi:[1,0]
	v_pk_mul_f32 v[6:7], v[6:7], v[144:145] op_sel_hi:[1,0]
	v_pk_mul_f32 v[8:9], v[8:9], v[144:145] op_sel_hi:[1,0]
	v_pk_mul_f32 v[10:11], v[10:11], v[144:145] op_sel_hi:[1,0]
	v_pk_mul_f32 v[12:13], v[12:13], v[144:145] op_sel_hi:[1,0]
	v_pk_mul_f32 v[14:15], v[14:15], v[144:145] op_sel_hi:[1,0]
	v_pk_fma_f32 v[0:1], v[80:81], v[0:1], v[96:97]
	v_pk_fma_f32 v[2:3], v[82:83], v[2:3], v[98:99]
	v_pk_fma_f32 v[4:5], v[84:85], v[4:5], v[100:101]
	v_pk_fma_f32 v[6:7], v[86:87], v[6:7], v[102:103]
	v_pk_fma_f32 v[8:9], v[88:89], v[8:9], v[104:105]
	v_pk_fma_f32 v[10:11], v[90:91], v[10:11], v[106:107]
	v_pk_fma_f32 v[12:13], v[92:93], v[12:13], v[108:109]
	v_pk_fma_f32 v[14:15], v[94:95], v[14:15], v[110:111]
	global_store_dwordx4 v[130:131], v[0:3], off
	global_store_dwordx4 v[130:131], v[4:7], off offset:1024
	global_store_dwordx4 v[130:131], v[8:11], off offset:2048
	global_store_dwordx4 v[130:131], v[12:15], off offset:3072
	v_lshl_add_u64 v[130:131], v[130:131], 0, v[152:153]
	v_add_f32_e32 v112, v0, v1
	v_add_f32_e32 v113, v2, v3
	v_add_f32_e32 v114, v4, v5
	v_add_f32_e32 v115, v6, v7
	v_add_f32_e32 v116, v8, v9
	v_add_f32_e32 v117, v10, v11
	v_add_f32_e32 v118, v12, v13
	v_add_f32_e32 v119, v14, v15
	v_add_f32_e32 v112, v112, v116
	v_add_f32_e32 v113, v113, v117
	v_add_f32_e32 v114, v114, v118
	v_add_f32_e32 v115, v115, v119
	v_add_f32_e32 v112, v112, v113
	v_add_f32_e32 v114, v114, v115
	v_add_f32_e32 v112, v112, v114
	s_nop 1
	v_add_f32_dpp v112, v112, v112 quad_perm:[1,0,3,2] row_mask:0xf bank_mask:0xf
	s_nop 1
	v_add_f32_dpp v112, v112, v112 quad_perm:[2,3,0,1] row_mask:0xf bank_mask:0xf
	s_nop 1
	v_add_f32_dpp v112, v112, v112 row_half_mirror row_mask:0xf bank_mask:0xf
	s_nop 1
	v_add_f32_dpp v112, v112, v112 row_mirror row_mask:0xf bank_mask:0xf
	s_nop 1
	v_add_f32_dpp v112, v112, v112 row_bcast:15 row_mask:0xa bank_mask:0xf
	s_nop 1
	v_add_f32_dpp v112, v112, v112 row_bcast:31 row_mask:0xc bank_mask:0xf
	s_nop 1
	v_readlane_b32 s2, v112, 63
	s_nop 1
	v_fmac_f32_e32 v0, s2, v142
	v_fmac_f32_e32 v1, s2, v142
	v_fmac_f32_e32 v2, s2, v142
	v_fmac_f32_e32 v3, s2, v142
	v_fmac_f32_e32 v4, s2, v142
	v_fmac_f32_e32 v5, s2, v142
	v_fmac_f32_e32 v6, s2, v142
	v_fmac_f32_e32 v7, s2, v142
	v_fmac_f32_e32 v8, s2, v142
	v_fmac_f32_e32 v9, s2, v142
	v_fmac_f32_e32 v10, s2, v142
	v_fmac_f32_e32 v11, s2, v142
	v_fmac_f32_e32 v12, s2, v142
	v_fmac_f32_e32 v13, s2, v142
	v_fmac_f32_e32 v14, s2, v142
	v_fmac_f32_e32 v15, s2, v142
	v_mul_f32_e32 v112, v0, v0
	v_mul_f32_e32 v113, v1, v1
	v_mul_f32_e32 v114, v2, v2
	v_mul_f32_e32 v115, v3, v3
	v_fmac_f32_e32 v112, v4, v4
	v_fmac_f32_e32 v113, v5, v5
	v_fmac_f32_e32 v114, v6, v6
	v_fmac_f32_e32 v115, v7, v7
	v_fmac_f32_e32 v112, v8, v8
	v_fmac_f32_e32 v113, v9, v9
	v_fmac_f32_e32 v114, v10, v10
	v_fmac_f32_e32 v115, v11, v11
	v_fmac_f32_e32 v112, v12, v12
	v_fmac_f32_e32 v113, v13, v13
	v_fmac_f32_e32 v114, v14, v14
	v_fmac_f32_e32 v115, v15, v15
	v_add_f32_e32 v112, v112, v113
	v_add_f32_e32 v114, v114, v115
	v_add_f32_e32 v112, v112, v114
	s_nop 1
	v_add_f32_dpp v112, v112, v112 quad_perm:[1,0,3,2] row_mask:0xf bank_mask:0xf
	s_nop 1
	v_add_f32_dpp v112, v112, v112 quad_perm:[2,3,0,1] row_mask:0xf bank_mask:0xf
	s_nop 1
	v_add_f32_dpp v112, v112, v112 row_half_mirror row_mask:0xf bank_mask:0xf
	s_nop 1
	v_add_f32_dpp v112, v112, v112 row_mirror row_mask:0xf bank_mask:0xf
	s_nop 1
	v_add_f32_dpp v112, v112, v112 row_bcast:15 row_mask:0xa bank_mask:0xf
	s_nop 1
	v_add_f32_dpp v112, v112, v112 row_bcast:31 row_mask:0xc bank_mask:0xf
	s_nop 1
	v_readlane_b32 s2, v112, 63
	s_nop 1
	v_mov_b32_e32 v113, 0x358637bd
	v_mov_b32_e32 v114, 0x3a800000
	v_fmac_f32_e32 v113, s2, v114
	v_rsq_f32_e32 v115, v113
	v_mul_f32_e32 v113, 0.5, v113
	v_mul_f32_e32 v116, v115, v115
	v_mov_b32_e32 v117, 0x3fc00000
	v_fma_f32 v116, -v113, v116, v117
	v_mul_f32_e32 v144, v115, v116
	v_pk_mul_f32 v[0:1], v[0:1], v[144:145] op_sel_hi:[1,0]
	v_pk_mul_f32 v[2:3], v[2:3], v[144:145] op_sel_hi:[1,0]
	v_pk_mul_f32 v[4:5], v[4:5], v[144:145] op_sel_hi:[1,0]
	v_pk_mul_f32 v[6:7], v[6:7], v[144:145] op_sel_hi:[1,0]
	v_pk_mul_f32 v[8:9], v[8:9], v[144:145] op_sel_hi:[1,0]
	v_pk_mul_f32 v[10:11], v[10:11], v[144:145] op_sel_hi:[1,0]
	v_pk_mul_f32 v[12:13], v[12:13], v[144:145] op_sel_hi:[1,0]
	v_pk_mul_f32 v[14:15], v[14:15], v[144:145] op_sel_hi:[1,0]
	s_waitcnt vmcnt(8)
	v_pk_add_f32 v[64:65], v[64:65], 1.0 op_sel_hi:[1,0]
	v_pk_add_f32 v[66:67], v[66:67], 1.0 op_sel_hi:[1,0]
	v_pk_add_f32 v[68:69], v[68:69], 1.0 op_sel_hi:[1,0]
	v_pk_add_f32 v[70:71], v[70:71], 1.0 op_sel_hi:[1,0]
	v_pk_add_f32 v[72:73], v[72:73], 1.0 op_sel_hi:[1,0]
	v_pk_add_f32 v[74:75], v[74:75], 1.0 op_sel_hi:[1,0]
	v_pk_add_f32 v[76:77], v[76:77], 1.0 op_sel_hi:[1,0]
	v_pk_add_f32 v[78:79], v[78:79], 1.0 op_sel_hi:[1,0]
	v_pk_fma_f32 v[0:1], v[64:65], v[0:1], v[48:49]
	v_pk_fma_f32 v[2:3], v[66:67], v[2:3], v[50:51]
	v_pk_fma_f32 v[4:5], v[68:69], v[4:5], v[52:53]
	v_pk_fma_f32 v[6:7], v[70:71], v[6:7], v[54:55]
	v_pk_fma_f32 v[8:9], v[72:73], v[8:9], v[56:57]
	v_pk_fma_f32 v[10:11], v[74:75], v[10:11], v[58:59]
	v_pk_fma_f32 v[12:13], v[76:77], v[12:13], v[60:61]
	v_pk_fma_f32 v[14:15], v[78:79], v[14:15], v[62:63]
	v_cvt_pk_bf16_f32 v120, v0, v1
	v_cvt_pk_bf16_f32 v121, v2, v3
	v_cvt_pk_bf16_f32 v122, v4, v5
	v_cvt_pk_bf16_f32 v123, v6, v7
	v_cvt_pk_bf16_f32 v124, v8, v9
	v_cvt_pk_bf16_f32 v125, v10, v11
	v_cvt_pk_bf16_f32 v126, v12, v13
	v_cvt_pk_bf16_f32 v127, v14, v15
	v_cndmask_b32_e64 v112, v122, v120, s[40:41]
	v_cndmask_b32_e64 v113, v123, v121, s[40:41]
	v_cndmask_b32_e64 v114, v126, v124, s[40:41]
	v_cndmask_b32_e64 v115, v127, v125, s[40:41]
	v_mov_b32_dpp v116, v112 quad_perm:[1,0,3,2] row_mask:0xf bank_mask:0xf
	v_mov_b32_dpp v117, v113 quad_perm:[1,0,3,2] row_mask:0xf bank_mask:0xf
	v_mov_b32_dpp v118, v114 quad_perm:[1,0,3,2] row_mask:0xf bank_mask:0xf
	v_mov_b32_dpp v119, v115 quad_perm:[1,0,3,2] row_mask:0xf bank_mask:0xf
	s_nop 0
	v_cndmask_b32_e64 v160, v120, v116, s[40:41]
	v_cndmask_b32_e64 v161, v121, v117, s[40:41]
	v_cndmask_b32_e64 v162, v116, v122, s[40:41]
	v_cndmask_b32_e64 v163, v117, v123, s[40:41]
	v_cndmask_b32_e64 v164, v124, v118, s[40:41]
	v_cndmask_b32_e64 v165, v125, v119, s[40:41]
	v_cndmask_b32_e64 v166, v118, v126, s[40:41]
	v_cndmask_b32_e64 v167, v119, v127, s[40:41]
	global_store_dwordx4 v[132:133], v[160:163], off
	global_store_dwordx4 v[132:133], v[164:167], off offset:1024
	v_lshl_add_u64 v[132:133], v[132:133], 0, v[154:155]
	global_load_dwordx4 v[0:3], v[128:129], off nt
	global_load_dwordx4 v[4:7], v[128:129], off offset:1024 nt
	global_load_dwordx4 v[8:11], v[128:129], off offset:2048 nt
	global_load_dwordx4 v[12:15], v[128:129], off offset:3072 nt
	v_lshl_add_u64 v[128:129], v[128:129], 0, v[152:153]
	v_add_f32_e32 v112, v16, v17
	v_add_f32_e32 v113, v18, v19
	v_add_f32_e32 v114, v20, v21
	v_add_f32_e32 v115, v22, v23
	v_add_f32_e32 v116, v24, v25
	v_add_f32_e32 v117, v26, v27
	v_add_f32_e32 v118, v28, v29
	v_add_f32_e32 v119, v30, v31
	v_add_f32_e32 v112, v112, v116
	v_add_f32_e32 v113, v113, v117
	v_add_f32_e32 v114, v114, v118
	v_add_f32_e32 v115, v115, v119
	v_add_f32_e32 v112, v112, v113
	v_add_f32_e32 v114, v114, v115
	v_add_f32_e32 v112, v112, v114
	s_nop 1
	v_add_f32_dpp v112, v112, v112 quad_perm:[1,0,3,2] row_mask:0xf bank_mask:0xf
	s_nop 1
	v_add_f32_dpp v112, v112, v112 quad_perm:[2,3,0,1] row_mask:0xf bank_mask:0xf
	s_nop 1
	v_add_f32_dpp v112, v112, v112 row_half_mirror row_mask:0xf bank_mask:0xf
	s_nop 1
	v_add_f32_dpp v112, v112, v112 row_mirror row_mask:0xf bank_mask:0xf
	s_nop 1
	v_add_f32_dpp v112, v112, v112 row_bcast:15 row_mask:0xa bank_mask:0xf
	s_nop 1
	v_add_f32_dpp v112, v112, v112 row_bcast:31 row_mask:0xc bank_mask:0xf
	s_nop 1
	v_readlane_b32 s2, v112, 63
	s_nop 1
	v_fmac_f32_e32 v16, s2, v142
	v_fmac_f32_e32 v17, s2, v142
	v_fmac_f32_e32 v18, s2, v142
	v_fmac_f32_e32 v19, s2, v142
	v_fmac_f32_e32 v20, s2, v142
	v_fmac_f32_e32 v21, s2, v142
	v_fmac_f32_e32 v22, s2, v142
	v_fmac_f32_e32 v23, s2, v142
	v_fmac_f32_e32 v24, s2, v142
	v_fmac_f32_e32 v25, s2, v142
	v_fmac_f32_e32 v26, s2, v142
	v_fmac_f32_e32 v27, s2, v142
	v_fmac_f32_e32 v28, s2, v142
	v_fmac_f32_e32 v29, s2, v142
	v_fmac_f32_e32 v30, s2, v142
	v_fmac_f32_e32 v31, s2, v142
	v_mul_f32_e32 v112, v16, v16
	v_mul_f32_e32 v113, v17, v17
	v_mul_f32_e32 v114, v18, v18
	v_mul_f32_e32 v115, v19, v19
	v_fmac_f32_e32 v112, v20, v20
	v_fmac_f32_e32 v113, v21, v21
	v_fmac_f32_e32 v114, v22, v22
	v_fmac_f32_e32 v115, v23, v23
	v_fmac_f32_e32 v112, v24, v24
	v_fmac_f32_e32 v113, v25, v25
	v_fmac_f32_e32 v114, v26, v26
	v_fmac_f32_e32 v115, v27, v27
	v_fmac_f32_e32 v112, v28, v28
	v_fmac_f32_e32 v113, v29, v29
	v_fmac_f32_e32 v114, v30, v30
	v_fmac_f32_e32 v115, v31, v31
	v_add_f32_e32 v112, v112, v113
	v_add_f32_e32 v114, v114, v115
	v_add_f32_e32 v112, v112, v114
	s_nop 1
	v_add_f32_dpp v112, v112, v112 quad_perm:[1,0,3,2] row_mask:0xf bank_mask:0xf
	s_nop 1
	v_add_f32_dpp v112, v112, v112 quad_perm:[2,3,0,1] row_mask:0xf bank_mask:0xf
	s_nop 1
	v_add_f32_dpp v112, v112, v112 row_half_mirror row_mask:0xf bank_mask:0xf
	s_nop 1
	v_add_f32_dpp v112, v112, v112 row_mirror row_mask:0xf bank_mask:0xf
	s_nop 1
	v_add_f32_dpp v112, v112, v112 row_bcast:15 row_mask:0xa bank_mask:0xf
	s_nop 1
	v_add_f32_dpp v112, v112, v112 row_bcast:31 row_mask:0xc bank_mask:0xf
	s_nop 1
	v_readlane_b32 s2, v112, 63
	s_nop 1
	v_mov_b32_e32 v113, 0x358637bd
	v_mov_b32_e32 v114, 0x3a800000
	v_fmac_f32_e32 v113, s2, v114
	v_rsq_f32_e32 v115, v113
	v_mul_f32_e32 v113, 0.5, v113
	v_mul_f32_e32 v116, v115, v115
	v_mov_b32_e32 v117, 0x3fc00000
	v_fma_f32 v116, -v113, v116, v117
	v_mul_f32_e32 v144, v115, v116
	v_pk_mul_f32 v[16:17], v[16:17], v[144:145] op_sel_hi:[1,0]
	v_pk_mul_f32 v[18:19], v[18:19], v[144:145] op_sel_hi:[1,0]
	v_pk_mul_f32 v[20:21], v[20:21], v[144:145] op_sel_hi:[1,0]
	v_pk_mul_f32 v[22:23], v[22:23], v[144:145] op_sel_hi:[1,0]
	v_pk_mul_f32 v[24:25], v[24:25], v[144:145] op_sel_hi:[1,0]
	v_pk_mul_f32 v[26:27], v[26:27], v[144:145] op_sel_hi:[1,0]
	v_pk_mul_f32 v[28:29], v[28:29], v[144:145] op_sel_hi:[1,0]
	v_pk_mul_f32 v[30:31], v[30:31], v[144:145] op_sel_hi:[1,0]
	v_pk_fma_f32 v[16:17], v[80:81], v[16:17], v[96:97]
	v_pk_fma_f32 v[18:19], v[82:83], v[18:19], v[98:99]
	v_pk_fma_f32 v[20:21], v[84:85], v[20:21], v[100:101]
	v_pk_fma_f32 v[22:23], v[86:87], v[22:23], v[102:103]
	v_pk_fma_f32 v[24:25], v[88:89], v[24:25], v[104:105]
	v_pk_fma_f32 v[26:27], v[90:91], v[26:27], v[106:107]
	v_pk_fma_f32 v[28:29], v[92:93], v[28:29], v[108:109]
	v_pk_fma_f32 v[30:31], v[94:95], v[30:31], v[110:111]
	global_store_dwordx4 v[130:131], v[16:19], off
	global_store_dwordx4 v[130:131], v[20:23], off offset:1024
	global_store_dwordx4 v[130:131], v[24:27], off offset:2048
	global_store_dwordx4 v[130:131], v[28:31], off offset:3072
	v_lshl_add_u64 v[130:131], v[130:131], 0, v[152:153]
	v_add_f32_e32 v112, v16, v17
	v_add_f32_e32 v113, v18, v19
	v_add_f32_e32 v114, v20, v21
	v_add_f32_e32 v115, v22, v23
	v_add_f32_e32 v116, v24, v25
	v_add_f32_e32 v117, v26, v27
	v_add_f32_e32 v118, v28, v29
	v_add_f32_e32 v119, v30, v31
	v_add_f32_e32 v112, v112, v116
	v_add_f32_e32 v113, v113, v117
	v_add_f32_e32 v114, v114, v118
	v_add_f32_e32 v115, v115, v119
	v_add_f32_e32 v112, v112, v113
	v_add_f32_e32 v114, v114, v115
	v_add_f32_e32 v112, v112, v114
	s_nop 1
	v_add_f32_dpp v112, v112, v112 quad_perm:[1,0,3,2] row_mask:0xf bank_mask:0xf
	s_nop 1
	v_add_f32_dpp v112, v112, v112 quad_perm:[2,3,0,1] row_mask:0xf bank_mask:0xf
	s_nop 1
	v_add_f32_dpp v112, v112, v112 row_half_mirror row_mask:0xf bank_mask:0xf
	s_nop 1
	v_add_f32_dpp v112, v112, v112 row_mirror row_mask:0xf bank_mask:0xf
	s_nop 1
	v_add_f32_dpp v112, v112, v112 row_bcast:15 row_mask:0xa bank_mask:0xf
	s_nop 1
	v_add_f32_dpp v112, v112, v112 row_bcast:31 row_mask:0xc bank_mask:0xf
	s_nop 1
	v_readlane_b32 s2, v112, 63
	s_nop 1
	v_fmac_f32_e32 v16, s2, v142
	v_fmac_f32_e32 v17, s2, v142
	v_fmac_f32_e32 v18, s2, v142
	v_fmac_f32_e32 v19, s2, v142
	v_fmac_f32_e32 v20, s2, v142
	v_fmac_f32_e32 v21, s2, v142
	v_fmac_f32_e32 v22, s2, v142
	v_fmac_f32_e32 v23, s2, v142
	v_fmac_f32_e32 v24, s2, v142
	v_fmac_f32_e32 v25, s2, v142
	v_fmac_f32_e32 v26, s2, v142
	v_fmac_f32_e32 v27, s2, v142
	v_fmac_f32_e32 v28, s2, v142
	v_fmac_f32_e32 v29, s2, v142
	v_fmac_f32_e32 v30, s2, v142
	v_fmac_f32_e32 v31, s2, v142
	v_mul_f32_e32 v112, v16, v16
	v_mul_f32_e32 v113, v17, v17
	v_mul_f32_e32 v114, v18, v18
	v_mul_f32_e32 v115, v19, v19
	v_fmac_f32_e32 v112, v20, v20
	v_fmac_f32_e32 v113, v21, v21
	v_fmac_f32_e32 v114, v22, v22
	v_fmac_f32_e32 v115, v23, v23
	v_fmac_f32_e32 v112, v24, v24
	v_fmac_f32_e32 v113, v25, v25
	v_fmac_f32_e32 v114, v26, v26
	v_fmac_f32_e32 v115, v27, v27
	v_fmac_f32_e32 v112, v28, v28
	v_fmac_f32_e32 v113, v29, v29
	v_fmac_f32_e32 v114, v30, v30
	v_fmac_f32_e32 v115, v31, v31
	v_add_f32_e32 v112, v112, v113
	v_add_f32_e32 v114, v114, v115
	v_add_f32_e32 v112, v112, v114
	s_nop 1
	v_add_f32_dpp v112, v112, v112 quad_perm:[1,0,3,2] row_mask:0xf bank_mask:0xf
	s_nop 1
	v_add_f32_dpp v112, v112, v112 quad_perm:[2,3,0,1] row_mask:0xf bank_mask:0xf
	s_nop 1
	v_add_f32_dpp v112, v112, v112 row_half_mirror row_mask:0xf bank_mask:0xf
	s_nop 1
	v_add_f32_dpp v112, v112, v112 row_mirror row_mask:0xf bank_mask:0xf
	s_nop 1
	v_add_f32_dpp v112, v112, v112 row_bcast:15 row_mask:0xa bank_mask:0xf
	s_nop 1
	v_add_f32_dpp v112, v112, v112 row_bcast:31 row_mask:0xc bank_mask:0xf
	s_nop 1
	v_readlane_b32 s2, v112, 63
	s_nop 1
	v_mov_b32_e32 v113, 0x358637bd
	v_mov_b32_e32 v114, 0x3a800000
	v_fmac_f32_e32 v113, s2, v114
	v_rsq_f32_e32 v115, v113
	v_mul_f32_e32 v113, 0.5, v113
	v_mul_f32_e32 v116, v115, v115
	v_mov_b32_e32 v117, 0x3fc00000
	v_fma_f32 v116, -v113, v116, v117
	v_mul_f32_e32 v144, v115, v116
	v_pk_mul_f32 v[16:17], v[16:17], v[144:145] op_sel_hi:[1,0]
	v_pk_mul_f32 v[18:19], v[18:19], v[144:145] op_sel_hi:[1,0]
	v_pk_mul_f32 v[20:21], v[20:21], v[144:145] op_sel_hi:[1,0]
	v_pk_mul_f32 v[22:23], v[22:23], v[144:145] op_sel_hi:[1,0]
	v_pk_mul_f32 v[24:25], v[24:25], v[144:145] op_sel_hi:[1,0]
	v_pk_mul_f32 v[26:27], v[26:27], v[144:145] op_sel_hi:[1,0]
	v_pk_mul_f32 v[28:29], v[28:29], v[144:145] op_sel_hi:[1,0]
	v_pk_mul_f32 v[30:31], v[30:31], v[144:145] op_sel_hi:[1,0]
	v_pk_fma_f32 v[16:17], v[64:65], v[16:17], v[48:49]
	v_pk_fma_f32 v[18:19], v[66:67], v[18:19], v[50:51]
	v_pk_fma_f32 v[20:21], v[68:69], v[20:21], v[52:53]
	v_pk_fma_f32 v[22:23], v[70:71], v[22:23], v[54:55]
	v_pk_fma_f32 v[24:25], v[72:73], v[24:25], v[56:57]
	v_pk_fma_f32 v[26:27], v[74:75], v[26:27], v[58:59]
	v_pk_fma_f32 v[28:29], v[76:77], v[28:29], v[60:61]
	v_pk_fma_f32 v[30:31], v[78:79], v[30:31], v[62:63]
	v_cvt_pk_bf16_f32 v120, v16, v17
	v_cvt_pk_bf16_f32 v121, v18, v19
	v_cvt_pk_bf16_f32 v122, v20, v21
	v_cvt_pk_bf16_f32 v123, v22, v23
	v_cvt_pk_bf16_f32 v124, v24, v25
	v_cvt_pk_bf16_f32 v125, v26, v27
	v_cvt_pk_bf16_f32 v126, v28, v29
	v_cvt_pk_bf16_f32 v127, v30, v31
	v_cndmask_b32_e64 v112, v122, v120, s[40:41]
	v_cndmask_b32_e64 v113, v123, v121, s[40:41]
	v_cndmask_b32_e64 v114, v126, v124, s[40:41]
	v_cndmask_b32_e64 v115, v127, v125, s[40:41]
	v_mov_b32_dpp v116, v112 quad_perm:[1,0,3,2] row_mask:0xf bank_mask:0xf
	v_mov_b32_dpp v117, v113 quad_perm:[1,0,3,2] row_mask:0xf bank_mask:0xf
	v_mov_b32_dpp v118, v114 quad_perm:[1,0,3,2] row_mask:0xf bank_mask:0xf
	v_mov_b32_dpp v119, v115 quad_perm:[1,0,3,2] row_mask:0xf bank_mask:0xf
	s_nop 0
	v_cndmask_b32_e64 v160, v120, v116, s[40:41]
	v_cndmask_b32_e64 v161, v121, v117, s[40:41]
	v_cndmask_b32_e64 v162, v116, v122, s[40:41]
	v_cndmask_b32_e64 v163, v117, v123, s[40:41]
	v_cndmask_b32_e64 v164, v124, v118, s[40:41]
	v_cndmask_b32_e64 v165, v125, v119, s[40:41]
	v_cndmask_b32_e64 v166, v118, v126, s[40:41]
	v_cndmask_b32_e64 v167, v119, v127, s[40:41]
	global_store_dwordx4 v[132:133], v[160:163], off
	global_store_dwordx4 v[132:133], v[164:167], off offset:1024
	v_lshl_add_u64 v[132:133], v[132:133], 0, v[154:155]
	global_load_dwordx4 v[48:51], v[134:135], off offset:-4096
	global_load_dwordx4 v[52:55], v[134:135], off offset:-3072
	global_load_dwordx4 v[56:59], v[134:135], off offset:-2048
	global_load_dwordx4 v[60:63], v[134:135], off offset:-1024
	global_load_dwordx4 v[64:67], v[134:135], off
	global_load_dwordx4 v[68:71], v[134:135], off offset:1024
	global_load_dwordx4 v[72:75], v[134:135], off offset:2048
	global_load_dwordx4 v[76:79], v[134:135], off offset:3072
	v_lshl_add_u64 v[134:135], v[134:135], 0, v[156:157]
	global_load_dwordx4 v[16:19], v[128:129], off nt
	global_load_dwordx4 v[20:23], v[128:129], off offset:1024 nt
	global_load_dwordx4 v[24:27], v[128:129], off offset:2048 nt
	global_load_dwordx4 v[28:31], v[128:129], off offset:3072 nt
	v_lshl_add_u64 v[128:129], v[128:129], 0, v[152:153]
	s_waitcnt vmcnt(28)
	v_add_f32_e32 v112, v32, v33
	v_add_f32_e32 v113, v34, v35
	v_add_f32_e32 v114, v36, v37
	v_add_f32_e32 v115, v38, v39
	v_add_f32_e32 v116, v40, v41
	v_add_f32_e32 v117, v42, v43
	v_add_f32_e32 v118, v44, v45
	v_add_f32_e32 v119, v46, v47
	v_add_f32_e32 v112, v112, v116
	v_add_f32_e32 v113, v113, v117
	v_add_f32_e32 v114, v114, v118
	v_add_f32_e32 v115, v115, v119
	v_add_f32_e32 v112, v112, v113
	v_add_f32_e32 v114, v114, v115
	v_add_f32_e32 v112, v112, v114
	s_nop 1
	v_add_f32_dpp v112, v112, v112 quad_perm:[1,0,3,2] row_mask:0xf bank_mask:0xf
	s_nop 1
	v_add_f32_dpp v112, v112, v112 quad_perm:[2,3,0,1] row_mask:0xf bank_mask:0xf
	s_nop 1
	v_add_f32_dpp v112, v112, v112 row_half_mirror row_mask:0xf bank_mask:0xf
	s_nop 1
	v_add_f32_dpp v112, v112, v112 row_mirror row_mask:0xf bank_mask:0xf
	s_nop 1
	v_add_f32_dpp v112, v112, v112 row_bcast:15 row_mask:0xa bank_mask:0xf
	s_nop 1
	v_add_f32_dpp v112, v112, v112 row_bcast:31 row_mask:0xc bank_mask:0xf
	s_nop 1
	v_readlane_b32 s2, v112, 63
	s_nop 1
	v_fmac_f32_e32 v32, s2, v142
	v_fmac_f32_e32 v33, s2, v142
	v_fmac_f32_e32 v34, s2, v142
	v_fmac_f32_e32 v35, s2, v142
	v_fmac_f32_e32 v36, s2, v142
	v_fmac_f32_e32 v37, s2, v142
	v_fmac_f32_e32 v38, s2, v142
	v_fmac_f32_e32 v39, s2, v142
	v_fmac_f32_e32 v40, s2, v142
	v_fmac_f32_e32 v41, s2, v142
	v_fmac_f32_e32 v42, s2, v142
	v_fmac_f32_e32 v43, s2, v142
	v_fmac_f32_e32 v44, s2, v142
	v_fmac_f32_e32 v45, s2, v142
	v_fmac_f32_e32 v46, s2, v142
	v_fmac_f32_e32 v47, s2, v142
	v_mul_f32_e32 v112, v32, v32
	v_mul_f32_e32 v113, v33, v33
	v_mul_f32_e32 v114, v34, v34
	v_mul_f32_e32 v115, v35, v35
	v_fmac_f32_e32 v112, v36, v36
	v_fmac_f32_e32 v113, v37, v37
	v_fmac_f32_e32 v114, v38, v38
	v_fmac_f32_e32 v115, v39, v39
	v_fmac_f32_e32 v112, v40, v40
	v_fmac_f32_e32 v113, v41, v41
	v_fmac_f32_e32 v114, v42, v42
	v_fmac_f32_e32 v115, v43, v43
	v_fmac_f32_e32 v112, v44, v44
	v_fmac_f32_e32 v113, v45, v45
	v_fmac_f32_e32 v114, v46, v46
	v_fmac_f32_e32 v115, v47, v47
	v_add_f32_e32 v112, v112, v113
	v_add_f32_e32 v114, v114, v115
	v_add_f32_e32 v112, v112, v114
	s_nop 1
	v_add_f32_dpp v112, v112, v112 quad_perm:[1,0,3,2] row_mask:0xf bank_mask:0xf
	s_nop 1
	v_add_f32_dpp v112, v112, v112 quad_perm:[2,3,0,1] row_mask:0xf bank_mask:0xf
	s_nop 1
	v_add_f32_dpp v112, v112, v112 row_half_mirror row_mask:0xf bank_mask:0xf
	s_nop 1
	v_add_f32_dpp v112, v112, v112 row_mirror row_mask:0xf bank_mask:0xf
	s_nop 1
	v_add_f32_dpp v112, v112, v112 row_bcast:15 row_mask:0xa bank_mask:0xf
	s_nop 1
	v_add_f32_dpp v112, v112, v112 row_bcast:31 row_mask:0xc bank_mask:0xf
	s_nop 1
	v_readlane_b32 s2, v112, 63
	s_nop 1
	v_mov_b32_e32 v113, 0x358637bd
	v_mov_b32_e32 v114, 0x3a800000
	v_fmac_f32_e32 v113, s2, v114
	v_rsq_f32_e32 v115, v113
	v_mul_f32_e32 v113, 0.5, v113
	v_mul_f32_e32 v116, v115, v115
	v_mov_b32_e32 v117, 0x3fc00000
	v_fma_f32 v116, -v113, v116, v117
	v_mul_f32_e32 v144, v115, v116
	v_pk_mul_f32 v[32:33], v[32:33], v[144:145] op_sel_hi:[1,0]
	v_pk_mul_f32 v[34:35], v[34:35], v[144:145] op_sel_hi:[1,0]
	v_pk_mul_f32 v[36:37], v[36:37], v[144:145] op_sel_hi:[1,0]
	v_pk_mul_f32 v[38:39], v[38:39], v[144:145] op_sel_hi:[1,0]
	v_pk_mul_f32 v[40:41], v[40:41], v[144:145] op_sel_hi:[1,0]
	v_pk_mul_f32 v[42:43], v[42:43], v[144:145] op_sel_hi:[1,0]
	v_pk_mul_f32 v[44:45], v[44:45], v[144:145] op_sel_hi:[1,0]
	v_pk_mul_f32 v[46:47], v[46:47], v[144:145] op_sel_hi:[1,0]
	v_pk_fma_f32 v[32:33], v[80:81], v[32:33], v[96:97]
	v_pk_fma_f32 v[34:35], v[82:83], v[34:35], v[98:99]
	v_pk_fma_f32 v[36:37], v[84:85], v[36:37], v[100:101]
	v_pk_fma_f32 v[38:39], v[86:87], v[38:39], v[102:103]
	v_pk_fma_f32 v[40:41], v[88:89], v[40:41], v[104:105]
	v_pk_fma_f32 v[42:43], v[90:91], v[42:43], v[106:107]
	v_pk_fma_f32 v[44:45], v[92:93], v[44:45], v[108:109]
	v_pk_fma_f32 v[46:47], v[94:95], v[46:47], v[110:111]
	global_store_dwordx4 v[130:131], v[32:35], off
	global_store_dwordx4 v[130:131], v[36:39], off offset:1024
	global_store_dwordx4 v[130:131], v[40:43], off offset:2048
	global_store_dwordx4 v[130:131], v[44:47], off offset:3072
	v_lshl_add_u64 v[130:131], v[130:131], 0, v[152:153]
	v_add_f32_e32 v112, v32, v33
	v_add_f32_e32 v113, v34, v35
	v_add_f32_e32 v114, v36, v37
	v_add_f32_e32 v115, v38, v39
	v_add_f32_e32 v116, v40, v41
	v_add_f32_e32 v117, v42, v43
	v_add_f32_e32 v118, v44, v45
	v_add_f32_e32 v119, v46, v47
	v_add_f32_e32 v112, v112, v116
	v_add_f32_e32 v113, v113, v117
	v_add_f32_e32 v114, v114, v118
	v_add_f32_e32 v115, v115, v119
	v_add_f32_e32 v112, v112, v113
	v_add_f32_e32 v114, v114, v115
	v_add_f32_e32 v112, v112, v114
	s_nop 1
	v_add_f32_dpp v112, v112, v112 quad_perm:[1,0,3,2] row_mask:0xf bank_mask:0xf
	s_nop 1
	v_add_f32_dpp v112, v112, v112 quad_perm:[2,3,0,1] row_mask:0xf bank_mask:0xf
	s_nop 1
	v_add_f32_dpp v112, v112, v112 row_half_mirror row_mask:0xf bank_mask:0xf
	s_nop 1
	v_add_f32_dpp v112, v112, v112 row_mirror row_mask:0xf bank_mask:0xf
	s_nop 1
	v_add_f32_dpp v112, v112, v112 row_bcast:15 row_mask:0xa bank_mask:0xf
	s_nop 1
	v_add_f32_dpp v112, v112, v112 row_bcast:31 row_mask:0xc bank_mask:0xf
	s_nop 1
	v_readlane_b32 s2, v112, 63
	s_nop 1
	v_fmac_f32_e32 v32, s2, v142
	v_fmac_f32_e32 v33, s2, v142
	v_fmac_f32_e32 v34, s2, v142
	v_fmac_f32_e32 v35, s2, v142
	v_fmac_f32_e32 v36, s2, v142
	v_fmac_f32_e32 v37, s2, v142
	v_fmac_f32_e32 v38, s2, v142
	v_fmac_f32_e32 v39, s2, v142
	v_fmac_f32_e32 v40, s2, v142
	v_fmac_f32_e32 v41, s2, v142
	v_fmac_f32_e32 v42, s2, v142
	v_fmac_f32_e32 v43, s2, v142
	v_fmac_f32_e32 v44, s2, v142
	v_fmac_f32_e32 v45, s2, v142
	v_fmac_f32_e32 v46, s2, v142
	v_fmac_f32_e32 v47, s2, v142
	v_mul_f32_e32 v112, v32, v32
	v_mul_f32_e32 v113, v33, v33
	v_mul_f32_e32 v114, v34, v34
	v_mul_f32_e32 v115, v35, v35
	v_fmac_f32_e32 v112, v36, v36
	v_fmac_f32_e32 v113, v37, v37
	v_fmac_f32_e32 v114, v38, v38
	v_fmac_f32_e32 v115, v39, v39
	v_fmac_f32_e32 v112, v40, v40
	v_fmac_f32_e32 v113, v41, v41
	v_fmac_f32_e32 v114, v42, v42
	v_fmac_f32_e32 v115, v43, v43
	v_fmac_f32_e32 v112, v44, v44
	v_fmac_f32_e32 v113, v45, v45
	v_fmac_f32_e32 v114, v46, v46
	v_fmac_f32_e32 v115, v47, v47
	v_add_f32_e32 v112, v112, v113
	v_add_f32_e32 v114, v114, v115
	v_add_f32_e32 v112, v112, v114
	s_nop 1
	v_add_f32_dpp v112, v112, v112 quad_perm:[1,0,3,2] row_mask:0xf bank_mask:0xf
	s_nop 1
	v_add_f32_dpp v112, v112, v112 quad_perm:[2,3,0,1] row_mask:0xf bank_mask:0xf
	s_nop 1
	v_add_f32_dpp v112, v112, v112 row_half_mirror row_mask:0xf bank_mask:0xf
	s_nop 1
	v_add_f32_dpp v112, v112, v112 row_mirror row_mask:0xf bank_mask:0xf
	s_nop 1
	v_add_f32_dpp v112, v112, v112 row_bcast:15 row_mask:0xa bank_mask:0xf
	s_nop 1
	v_add_f32_dpp v112, v112, v112 row_bcast:31 row_mask:0xc bank_mask:0xf
	s_nop 1
	v_readlane_b32 s2, v112, 63
	s_nop 1
	v_mov_b32_e32 v113, 0x358637bd
	v_mov_b32_e32 v114, 0x3a800000
	v_fmac_f32_e32 v113, s2, v114
	v_rsq_f32_e32 v115, v113
	v_mul_f32_e32 v113, 0.5, v113
	v_mul_f32_e32 v116, v115, v115
	v_mov_b32_e32 v117, 0x3fc00000
	v_fma_f32 v116, -v113, v116, v117
	v_mul_f32_e32 v144, v115, v116
	v_pk_mul_f32 v[32:33], v[32:33], v[144:145] op_sel_hi:[1,0]
	v_pk_mul_f32 v[34:35], v[34:35], v[144:145] op_sel_hi:[1,0]
	v_pk_mul_f32 v[36:37], v[36:37], v[144:145] op_sel_hi:[1,0]
	v_pk_mul_f32 v[38:39], v[38:39], v[144:145] op_sel_hi:[1,0]
	v_pk_mul_f32 v[40:41], v[40:41], v[144:145] op_sel_hi:[1,0]
	v_pk_mul_f32 v[42:43], v[42:43], v[144:145] op_sel_hi:[1,0]
	v_pk_mul_f32 v[44:45], v[44:45], v[144:145] op_sel_hi:[1,0]
	v_pk_mul_f32 v[46:47], v[46:47], v[144:145] op_sel_hi:[1,0]
	s_waitcnt vmcnt(8)
	v_pk_add_f32 v[64:65], v[64:65], 1.0 op_sel_hi:[1,0]
	v_pk_add_f32 v[66:67], v[66:67], 1.0 op_sel_hi:[1,0]
	v_pk_add_f32 v[68:69], v[68:69], 1.0 op_sel_hi:[1,0]
	v_pk_add_f32 v[70:71], v[70:71], 1.0 op_sel_hi:[1,0]
	v_pk_add_f32 v[72:73], v[72:73], 1.0 op_sel_hi:[1,0]
	v_pk_add_f32 v[74:75], v[74:75], 1.0 op_sel_hi:[1,0]
	v_pk_add_f32 v[76:77], v[76:77], 1.0 op_sel_hi:[1,0]
	v_pk_add_f32 v[78:79], v[78:79], 1.0 op_sel_hi:[1,0]
	v_pk_fma_f32 v[32:33], v[64:65], v[32:33], v[48:49]
	v_pk_fma_f32 v[34:35], v[66:67], v[34:35], v[50:51]
	v_pk_fma_f32 v[36:37], v[68:69], v[36:37], v[52:53]
	v_pk_fma_f32 v[38:39], v[70:71], v[38:39], v[54:55]
	v_pk_fma_f32 v[40:41], v[72:73], v[40:41], v[56:57]
	v_pk_fma_f32 v[42:43], v[74:75], v[42:43], v[58:59]
	v_pk_fma_f32 v[44:45], v[76:77], v[44:45], v[60:61]
	v_pk_fma_f32 v[46:47], v[78:79], v[46:47], v[62:63]
	v_cvt_pk_bf16_f32 v120, v32, v33
	v_cvt_pk_bf16_f32 v121, v34, v35
	v_cvt_pk_bf16_f32 v122, v36, v37
	v_cvt_pk_bf16_f32 v123, v38, v39
	v_cvt_pk_bf16_f32 v124, v40, v41
	v_cvt_pk_bf16_f32 v125, v42, v43
	v_cvt_pk_bf16_f32 v126, v44, v45
	v_cvt_pk_bf16_f32 v127, v46, v47
	v_cndmask_b32_e64 v112, v122, v120, s[40:41]
	v_cndmask_b32_e64 v113, v123, v121, s[40:41]
	v_cndmask_b32_e64 v114, v126, v124, s[40:41]
	v_cndmask_b32_e64 v115, v127, v125, s[40:41]
	v_mov_b32_dpp v116, v112 quad_perm:[1,0,3,2] row_mask:0xf bank_mask:0xf
	v_mov_b32_dpp v117, v113 quad_perm:[1,0,3,2] row_mask:0xf bank_mask:0xf
	v_mov_b32_dpp v118, v114 quad_perm:[1,0,3,2] row_mask:0xf bank_mask:0xf
	v_mov_b32_dpp v119, v115 quad_perm:[1,0,3,2] row_mask:0xf bank_mask:0xf
	s_nop 0
	v_cndmask_b32_e64 v160, v120, v116, s[40:41]
	v_cndmask_b32_e64 v161, v121, v117, s[40:41]
	v_cndmask_b32_e64 v162, v116, v122, s[40:41]
	v_cndmask_b32_e64 v163, v117, v123, s[40:41]
	v_cndmask_b32_e64 v164, v124, v118, s[40:41]
	v_cndmask_b32_e64 v165, v125, v119, s[40:41]
	v_cndmask_b32_e64 v166, v118, v126, s[40:41]
	v_cndmask_b32_e64 v167, v119, v127, s[40:41]
	global_store_dwordx4 v[132:133], v[160:163], off
	global_store_dwordx4 v[132:133], v[164:167], off offset:1024
	v_lshl_add_u64 v[132:133], v[132:133], 0, v[154:155]
	global_load_dwordx4 v[32:35], v[128:129], off nt
	global_load_dwordx4 v[36:39], v[128:129], off offset:1024 nt
	global_load_dwordx4 v[40:43], v[128:129], off offset:2048 nt
	global_load_dwordx4 v[44:47], v[128:129], off offset:3072 nt
	v_lshl_add_u64 v[128:129], v[128:129], 0, v[152:153]
	s_cmp_lg_u32 s0, 2
	s_cbranch_scc1 .Lln1a_nopark
	v_lshl_add_u64 v[128:129], s[60:61], 0, v[148:149]
.Lln1a_nopark:
	v_add_f32_e32 v112, v0, v1
	v_add_f32_e32 v113, v2, v3
	v_add_f32_e32 v114, v4, v5
	v_add_f32_e32 v115, v6, v7
	v_add_f32_e32 v116, v8, v9
	v_add_f32_e32 v117, v10, v11
	v_add_f32_e32 v118, v12, v13
	v_add_f32_e32 v119, v14, v15
	v_add_f32_e32 v112, v112, v116
	v_add_f32_e32 v113, v113, v117
	v_add_f32_e32 v114, v114, v118
	v_add_f32_e32 v115, v115, v119
	v_add_f32_e32 v112, v112, v113
	v_add_f32_e32 v114, v114, v115
	v_add_f32_e32 v112, v112, v114
	s_nop 1
	v_add_f32_dpp v112, v112, v112 quad_perm:[1,0,3,2] row_mask:0xf bank_mask:0xf
	s_nop 1
	v_add_f32_dpp v112, v112, v112 quad_perm:[2,3,0,1] row_mask:0xf bank_mask:0xf
	s_nop 1
	v_add_f32_dpp v112, v112, v112 row_half_mirror row_mask:0xf bank_mask:0xf
	s_nop 1
	v_add_f32_dpp v112, v112, v112 row_mirror row_mask:0xf bank_mask:0xf
	s_nop 1
	v_add_f32_dpp v112, v112, v112 row_bcast:15 row_mask:0xa bank_mask:0xf
	s_nop 1
	v_add_f32_dpp v112, v112, v112 row_bcast:31 row_mask:0xc bank_mask:0xf
	s_nop 1
	v_readlane_b32 s2, v112, 63
	s_nop 1
	v_fmac_f32_e32 v0, s2, v142
	v_fmac_f32_e32 v1, s2, v142
	v_fmac_f32_e32 v2, s2, v142
	v_fmac_f32_e32 v3, s2, v142
	v_fmac_f32_e32 v4, s2, v142
	v_fmac_f32_e32 v5, s2, v142
	v_fmac_f32_e32 v6, s2, v142
	v_fmac_f32_e32 v7, s2, v142
	v_fmac_f32_e32 v8, s2, v142
	v_fmac_f32_e32 v9, s2, v142
	v_fmac_f32_e32 v10, s2, v142
	v_fmac_f32_e32 v11, s2, v142
	v_fmac_f32_e32 v12, s2, v142
	v_fmac_f32_e32 v13, s2, v142
	v_fmac_f32_e32 v14, s2, v142
	v_fmac_f32_e32 v15, s2, v142
	v_mul_f32_e32 v112, v0, v0
	v_mul_f32_e32 v113, v1, v1
	v_mul_f32_e32 v114, v2, v2
	v_mul_f32_e32 v115, v3, v3
	v_fmac_f32_e32 v112, v4, v4
	v_fmac_f32_e32 v113, v5, v5
	v_fmac_f32_e32 v114, v6, v6
	v_fmac_f32_e32 v115, v7, v7
	v_fmac_f32_e32 v112, v8, v8
	v_fmac_f32_e32 v113, v9, v9
	v_fmac_f32_e32 v114, v10, v10
	v_fmac_f32_e32 v115, v11, v11
	v_fmac_f32_e32 v112, v12, v12
	v_fmac_f32_e32 v113, v13, v13
	v_fmac_f32_e32 v114, v14, v14
	v_fmac_f32_e32 v115, v15, v15
	v_add_f32_e32 v112, v112, v113
	v_add_f32_e32 v114, v114, v115
	v_add_f32_e32 v112, v112, v114
	s_nop 1
	v_add_f32_dpp v112, v112, v112 quad_perm:[1,0,3,2] row_mask:0xf bank_mask:0xf
	s_nop 1
	v_add_f32_dpp v112, v112, v112 quad_perm:[2,3,0,1] row_mask:0xf bank_mask:0xf
	s_nop 1
	v_add_f32_dpp v112, v112, v112 row_half_mirror row_mask:0xf bank_mask:0xf
	s_nop 1
	v_add_f32_dpp v112, v112, v112 row_mirror row_mask:0xf bank_mask:0xf
	s_nop 1
	v_add_f32_dpp v112, v112, v112 row_bcast:15 row_mask:0xa bank_mask:0xf
	s_nop 1
	v_add_f32_dpp v112, v112, v112 row_bcast:31 row_mask:0xc bank_mask:0xf
	s_nop 1
	v_readlane_b32 s2, v112, 63
	s_nop 1
	v_mov_b32_e32 v113, 0x358637bd
	v_mov_b32_e32 v114, 0x3a800000
	v_fmac_f32_e32 v113, s2, v114
	v_rsq_f32_e32 v115, v113
	v_mul_f32_e32 v113, 0.5, v113
	v_mul_f32_e32 v116, v115, v115
	v_mov_b32_e32 v117, 0x3fc00000
	v_fma_f32 v116, -v113, v116, v117
	v_mul_f32_e32 v144, v115, v116
	v_pk_mul_f32 v[0:1], v[0:1], v[144:145] op_sel_hi:[1,0]
	v_pk_mul_f32 v[2:3], v[2:3], v[144:145] op_sel_hi:[1,0]
	v_pk_mul_f32 v[4:5], v[4:5], v[144:145] op_sel_hi:[1,0]
	v_pk_mul_f32 v[6:7], v[6:7], v[144:145] op_sel_hi:[1,0]
	v_pk_mul_f32 v[8:9], v[8:9], v[144:145] op_sel_hi:[1,0]
	v_pk_mul_f32 v[10:11], v[10:11], v[144:145] op_sel_hi:[1,0]
	v_pk_mul_f32 v[12:13], v[12:13], v[144:145] op_sel_hi:[1,0]
	v_pk_mul_f32 v[14:15], v[14:15], v[144:145] op_sel_hi:[1,0]
	v_pk_fma_f32 v[0:1], v[80:81], v[0:1], v[96:97]
	v_pk_fma_f32 v[2:3], v[82:83], v[2:3], v[98:99]
	v_pk_fma_f32 v[4:5], v[84:85], v[4:5], v[100:101]
	v_pk_fma_f32 v[6:7], v[86:87], v[6:7], v[102:103]
	v_pk_fma_f32 v[8:9], v[88:89], v[8:9], v[104:105]
	v_pk_fma_f32 v[10:11], v[90:91], v[10:11], v[106:107]
	v_pk_fma_f32 v[12:13], v[92:93], v[12:13], v[108:109]
	v_pk_fma_f32 v[14:15], v[94:95], v[14:15], v[110:111]
	global_store_dwordx4 v[130:131], v[0:3], off
	global_store_dwordx4 v[130:131], v[4:7], off offset:1024
	global_store_dwordx4 v[130:131], v[8:11], off offset:2048
	global_store_dwordx4 v[130:131], v[12:15], off offset:3072
	v_lshl_add_u64 v[130:131], v[130:131], 0, v[152:153]
	v_add_f32_e32 v112, v0, v1
	v_add_f32_e32 v113, v2, v3
	v_add_f32_e32 v114, v4, v5
	v_add_f32_e32 v115, v6, v7
	v_add_f32_e32 v116, v8, v9
	v_add_f32_e32 v117, v10, v11
	v_add_f32_e32 v118, v12, v13
	v_add_f32_e32 v119, v14, v15
	v_add_f32_e32 v112, v112, v116
	v_add_f32_e32 v113, v113, v117
	v_add_f32_e32 v114, v114, v118
	v_add_f32_e32 v115, v115, v119
	v_add_f32_e32 v112, v112, v113
	v_add_f32_e32 v114, v114, v115
	v_add_f32_e32 v112, v112, v114
	s_nop 1
	v_add_f32_dpp v112, v112, v112 quad_perm:[1,0,3,2] row_mask:0xf bank_mask:0xf
	s_nop 1
	v_add_f32_dpp v112, v112, v112 quad_perm:[2,3,0,1] row_mask:0xf bank_mask:0xf
	s_nop 1
	v_add_f32_dpp v112, v112, v112 row_half_mirror row_mask:0xf bank_mask:0xf
	s_nop 1
	v_add_f32_dpp v112, v112, v112 row_mirror row_mask:0xf bank_mask:0xf
	s_nop 1
	v_add_f32_dpp v112, v112, v112 row_bcast:15 row_mask:0xa bank_mask:0xf
	s_nop 1
	v_add_f32_dpp v112, v112, v112 row_bcast:31 row_mask:0xc bank_mask:0xf
	s_nop 1
	v_readlane_b32 s2, v112, 63
	s_nop 1
	v_fmac_f32_e32 v0, s2, v142
	v_fmac_f32_e32 v1, s2, v142
	v_fmac_f32_e32 v2, s2, v142
	v_fmac_f32_e32 v3, s2, v142
	v_fmac_f32_e32 v4, s2, v142
	v_fmac_f32_e32 v5, s2, v142
	v_fmac_f32_e32 v6, s2, v142
	v_fmac_f32_e32 v7, s2, v142
	v_fmac_f32_e32 v8, s2, v142
	v_fmac_f32_e32 v9, s2, v142
	v_fmac_f32_e32 v10, s2, v142
	v_fmac_f32_e32 v11, s2, v142
	v_fmac_f32_e32 v12, s2, v142
	v_fmac_f32_e32 v13, s2, v142
	v_fmac_f32_e32 v14, s2, v142
	v_fmac_f32_e32 v15, s2, v142
	v_mul_f32_e32 v112, v0, v0
	v_mul_f32_e32 v113, v1, v1
	v_mul_f32_e32 v114, v2, v2
	v_mul_f32_e32 v115, v3, v3
	v_fmac_f32_e32 v112, v4, v4
	v_fmac_f32_e32 v113, v5, v5
	v_fmac_f32_e32 v114, v6, v6
	v_fmac_f32_e32 v115, v7, v7
	v_fmac_f32_e32 v112, v8, v8
	v_fmac_f32_e32 v113, v9, v9
	v_fmac_f32_e32 v114, v10, v10
	v_fmac_f32_e32 v115, v11, v11
	v_fmac_f32_e32 v112, v12, v12
	v_fmac_f32_e32 v113, v13, v13
	v_fmac_f32_e32 v114, v14, v14
	v_fmac_f32_e32 v115, v15, v15
	v_add_f32_e32 v112, v112, v113
	v_add_f32_e32 v114, v114, v115
	v_add_f32_e32 v112, v112, v114
	s_nop 1
	v_add_f32_dpp v112, v112, v112 quad_perm:[1,0,3,2] row_mask:0xf bank_mask:0xf
	s_nop 1
	v_add_f32_dpp v112, v112, v112 quad_perm:[2,3,0,1] row_mask:0xf bank_mask:0xf
	s_nop 1
	v_add_f32_dpp v112, v112, v112 row_half_mirror row_mask:0xf bank_mask:0xf
	s_nop 1
	v_add_f32_dpp v112, v112, v112 row_mirror row_mask:0xf bank_mask:0xf
	s_nop 1
	v_add_f32_dpp v112, v112, v112 row_bcast:15 row_mask:0xa bank_mask:0xf
	s_nop 1
	v_add_f32_dpp v112, v112, v112 row_bcast:31 row_mask:0xc bank_mask:0xf
	s_nop 1
	v_readlane_b32 s2, v112, 63
	s_nop 1
	v_mov_b32_e32 v113, 0x358637bd
	v_mov_b32_e32 v114, 0x3a800000
	v_fmac_f32_e32 v113, s2, v114
	v_rsq_f32_e32 v115, v113
	v_mul_f32_e32 v113, 0.5, v113
	v_mul_f32_e32 v116, v115, v115
	v_mov_b32_e32 v117, 0x3fc00000
	v_fma_f32 v116, -v113, v116, v117
	v_mul_f32_e32 v144, v115, v116
	v_pk_mul_f32 v[0:1], v[0:1], v[144:145] op_sel_hi:[1,0]
	v_pk_mul_f32 v[2:3], v[2:3], v[144:145] op_sel_hi:[1,0]
	v_pk_mul_f32 v[4:5], v[4:5], v[144:145] op_sel_hi:[1,0]
	v_pk_mul_f32 v[6:7], v[6:7], v[144:145] op_sel_hi:[1,0]
	v_pk_mul_f32 v[8:9], v[8:9], v[144:145] op_sel_hi:[1,0]
	v_pk_mul_f32 v[10:11], v[10:11], v[144:145] op_sel_hi:[1,0]
	v_pk_mul_f32 v[12:13], v[12:13], v[144:145] op_sel_hi:[1,0]
	v_pk_mul_f32 v[14:15], v[14:15], v[144:145] op_sel_hi:[1,0]
	v_pk_fma_f32 v[0:1], v[64:65], v[0:1], v[48:49]
	v_pk_fma_f32 v[2:3], v[66:67], v[2:3], v[50:51]
	v_pk_fma_f32 v[4:5], v[68:69], v[4:5], v[52:53]
	v_pk_fma_f32 v[6:7], v[70:71], v[6:7], v[54:55]
	v_pk_fma_f32 v[8:9], v[72:73], v[8:9], v[56:57]
	v_pk_fma_f32 v[10:11], v[74:75], v[10:11], v[58:59]
	v_pk_fma_f32 v[12:13], v[76:77], v[12:13], v[60:61]
	v_pk_fma_f32 v[14:15], v[78:79], v[14:15], v[62:63]
	v_cvt_pk_bf16_f32 v120, v0, v1
	v_cvt_pk_bf16_f32 v121, v2, v3
	v_cvt_pk_bf16_f32 v122, v4, v5
	v_cvt_pk_bf16_f32 v123, v6, v7
	v_cvt_pk_bf16_f32 v124, v8, v9
	v_cvt_pk_bf16_f32 v125, v10, v11
	v_cvt_pk_bf16_f32 v126, v12, v13
	v_cvt_pk_bf16_f32 v127, v14, v15
	v_cndmask_b32_e64 v112, v122, v120, s[40:41]
	v_cndmask_b32_e64 v113, v123, v121, s[40:41]
	v_cndmask_b32_e64 v114, v126, v124, s[40:41]
	v_cndmask_b32_e64 v115, v127, v125, s[40:41]
	v_mov_b32_dpp v116, v112 quad_perm:[1,0,3,2] row_mask:0xf bank_mask:0xf
	v_mov_b32_dpp v117, v113 quad_perm:[1,0,3,2] row_mask:0xf bank_mask:0xf
	v_mov_b32_dpp v118, v114 quad_perm:[1,0,3,2] row_mask:0xf bank_mask:0xf
	v_mov_b32_dpp v119, v115 quad_perm:[1,0,3,2] row_mask:0xf bank_mask:0xf
	s_nop 0
	v_cndmask_b32_e64 v160, v120, v116, s[40:41]
	v_cndmask_b32_e64 v161, v121, v117, s[40:41]
	v_cndmask_b32_e64 v162, v116, v122, s[40:41]
	v_cndmask_b32_e64 v163, v117, v123, s[40:41]
	v_cndmask_b32_e64 v164, v124, v118, s[40:41]
	v_cndmask_b32_e64 v165, v125, v119, s[40:41]
	v_cndmask_b32_e64 v166, v118, v126, s[40:41]
	v_cndmask_b32_e64 v167, v119, v127, s[40:41]
	global_store_dwordx4 v[132:133], v[160:163], off
	global_store_dwordx4 v[132:133], v[164:167], off offset:1024
	v_lshl_add_u64 v[132:133], v[132:133], 0, v[154:155]
	global_load_dwordx4 v[48:51], v[134:135], off offset:-4096
	global_load_dwordx4 v[52:55], v[134:135], off offset:-3072
	global_load_dwordx4 v[56:59], v[134:135], off offset:-2048
	global_load_dwordx4 v[60:63], v[134:135], off offset:-1024
	global_load_dwordx4 v[64:67], v[134:135], off
	global_load_dwordx4 v[68:71], v[134:135], off offset:1024
	global_load_dwordx4 v[72:75], v[134:135], off offset:2048
	global_load_dwordx4 v[76:79], v[134:135], off offset:3072
	v_lshl_add_u64 v[134:135], v[134:135], 0, v[156:157]
	global_load_dwordx4 v[0:3], v[128:129], off nt
	global_load_dwordx4 v[4:7], v[128:129], off offset:1024 nt
	global_load_dwordx4 v[8:11], v[128:129], off offset:2048 nt
	global_load_dwordx4 v[12:15], v[128:129], off offset:3072 nt
	v_lshl_add_u64 v[128:129], v[128:129], 0, v[152:153]
	s_waitcnt vmcnt(28)
	v_add_f32_e32 v112, v16, v17
	v_add_f32_e32 v113, v18, v19
	v_add_f32_e32 v114, v20, v21
	v_add_f32_e32 v115, v22, v23
	v_add_f32_e32 v116, v24, v25
	v_add_f32_e32 v117, v26, v27
	v_add_f32_e32 v118, v28, v29
	v_add_f32_e32 v119, v30, v31
	v_add_f32_e32 v112, v112, v116
	v_add_f32_e32 v113, v113, v117
	v_add_f32_e32 v114, v114, v118
	v_add_f32_e32 v115, v115, v119
	v_add_f32_e32 v112, v112, v113
	v_add_f32_e32 v114, v114, v115
	v_add_f32_e32 v112, v112, v114
	s_nop 1
	v_add_f32_dpp v112, v112, v112 quad_perm:[1,0,3,2] row_mask:0xf bank_mask:0xf
	s_nop 1
	v_add_f32_dpp v112, v112, v112 quad_perm:[2,3,0,1] row_mask:0xf bank_mask:0xf
	s_nop 1
	v_add_f32_dpp v112, v112, v112 row_half_mirror row_mask:0xf bank_mask:0xf
	s_nop 1
	v_add_f32_dpp v112, v112, v112 row_mirror row_mask:0xf bank_mask:0xf
	s_nop 1
	v_add_f32_dpp v112, v112, v112 row_bcast:15 row_mask:0xa bank_mask:0xf
	s_nop 1
	v_add_f32_dpp v112, v112, v112 row_bcast:31 row_mask:0xc bank_mask:0xf
	s_nop 1
	v_readlane_b32 s2, v112, 63
	s_nop 1
	v_fmac_f32_e32 v16, s2, v142
	v_fmac_f32_e32 v17, s2, v142
	v_fmac_f32_e32 v18, s2, v142
	v_fmac_f32_e32 v19, s2, v142
	v_fmac_f32_e32 v20, s2, v142
	v_fmac_f32_e32 v21, s2, v142
	v_fmac_f32_e32 v22, s2, v142
	v_fmac_f32_e32 v23, s2, v142
	v_fmac_f32_e32 v24, s2, v142
	v_fmac_f32_e32 v25, s2, v142
	v_fmac_f32_e32 v26, s2, v142
	v_fmac_f32_e32 v27, s2, v142
	v_fmac_f32_e32 v28, s2, v142
	v_fmac_f32_e32 v29, s2, v142
	v_fmac_f32_e32 v30, s2, v142
	v_fmac_f32_e32 v31, s2, v142
	v_mul_f32_e32 v112, v16, v16
	v_mul_f32_e32 v113, v17, v17
	v_mul_f32_e32 v114, v18, v18
	v_mul_f32_e32 v115, v19, v19
	v_fmac_f32_e32 v112, v20, v20
	v_fmac_f32_e32 v113, v21, v21
	v_fmac_f32_e32 v114, v22, v22
	v_fmac_f32_e32 v115, v23, v23
	v_fmac_f32_e32 v112, v24, v24
	v_fmac_f32_e32 v113, v25, v25
	v_fmac_f32_e32 v114, v26, v26
	v_fmac_f32_e32 v115, v27, v27
	v_fmac_f32_e32 v112, v28, v28
	v_fmac_f32_e32 v113, v29, v29
	v_fmac_f32_e32 v114, v30, v30
	v_fmac_f32_e32 v115, v31, v31
	v_add_f32_e32 v112, v112, v113
	v_add_f32_e32 v114, v114, v115
	v_add_f32_e32 v112, v112, v114
	s_nop 1
	v_add_f32_dpp v112, v112, v112 quad_perm:[1,0,3,2] row_mask:0xf bank_mask:0xf
	s_nop 1
	v_add_f32_dpp v112, v112, v112 quad_perm:[2,3,0,1] row_mask:0xf bank_mask:0xf
	s_nop 1
	v_add_f32_dpp v112, v112, v112 row_half_mirror row_mask:0xf bank_mask:0xf
	s_nop 1
	v_add_f32_dpp v112, v112, v112 row_mirror row_mask:0xf bank_mask:0xf
	s_nop 1
	v_add_f32_dpp v112, v112, v112 row_bcast:15 row_mask:0xa bank_mask:0xf
	s_nop 1
	v_add_f32_dpp v112, v112, v112 row_bcast:31 row_mask:0xc bank_mask:0xf
	s_nop 1
	v_readlane_b32 s2, v112, 63
	s_nop 1
	v_mov_b32_e32 v113, 0x358637bd
	v_mov_b32_e32 v114, 0x3a800000
	v_fmac_f32_e32 v113, s2, v114
	v_rsq_f32_e32 v115, v113
	v_mul_f32_e32 v113, 0.5, v113
	v_mul_f32_e32 v116, v115, v115
	v_mov_b32_e32 v117, 0x3fc00000
	v_fma_f32 v116, -v113, v116, v117
	v_mul_f32_e32 v144, v115, v116
	v_pk_mul_f32 v[16:17], v[16:17], v[144:145] op_sel_hi:[1,0]
	v_pk_mul_f32 v[18:19], v[18:19], v[144:145] op_sel_hi:[1,0]
	v_pk_mul_f32 v[20:21], v[20:21], v[144:145] op_sel_hi:[1,0]
	v_pk_mul_f32 v[22:23], v[22:23], v[144:145] op_sel_hi:[1,0]
	v_pk_mul_f32 v[24:25], v[24:25], v[144:145] op_sel_hi:[1,0]
	v_pk_mul_f32 v[26:27], v[26:27], v[144:145] op_sel_hi:[1,0]
	v_pk_mul_f32 v[28:29], v[28:29], v[144:145] op_sel_hi:[1,0]
	v_pk_mul_f32 v[30:31], v[30:31], v[144:145] op_sel_hi:[1,0]
	v_pk_fma_f32 v[16:17], v[80:81], v[16:17], v[96:97]
	v_pk_fma_f32 v[18:19], v[82:83], v[18:19], v[98:99]
	v_pk_fma_f32 v[20:21], v[84:85], v[20:21], v[100:101]
	v_pk_fma_f32 v[22:23], v[86:87], v[22:23], v[102:103]
	v_pk_fma_f32 v[24:25], v[88:89], v[24:25], v[104:105]
	v_pk_fma_f32 v[26:27], v[90:91], v[26:27], v[106:107]
	v_pk_fma_f32 v[28:29], v[92:93], v[28:29], v[108:109]
	v_pk_fma_f32 v[30:31], v[94:95], v[30:31], v[110:111]
	global_store_dwordx4 v[130:131], v[16:19], off
	global_store_dwordx4 v[130:131], v[20:23], off offset:1024
	global_store_dwordx4 v[130:131], v[24:27], off offset:2048
	global_store_dwordx4 v[130:131], v[28:31], off offset:3072
	v_lshl_add_u64 v[130:131], v[130:131], 0, v[152:153]
	v_add_f32_e32 v112, v16, v17
	v_add_f32_e32 v113, v18, v19
	v_add_f32_e32 v114, v20, v21
	v_add_f32_e32 v115, v22, v23
	v_add_f32_e32 v116, v24, v25
	v_add_f32_e32 v117, v26, v27
	v_add_f32_e32 v118, v28, v29
	v_add_f32_e32 v119, v30, v31
	v_add_f32_e32 v112, v112, v116
	v_add_f32_e32 v113, v113, v117
	v_add_f32_e32 v114, v114, v118
	v_add_f32_e32 v115, v115, v119
	v_add_f32_e32 v112, v112, v113
	v_add_f32_e32 v114, v114, v115
	v_add_f32_e32 v112, v112, v114
	s_nop 1
	v_add_f32_dpp v112, v112, v112 quad_perm:[1,0,3,2] row_mask:0xf bank_mask:0xf
	s_nop 1
	v_add_f32_dpp v112, v112, v112 quad_perm:[2,3,0,1] row_mask:0xf bank_mask:0xf
	s_nop 1
	v_add_f32_dpp v112, v112, v112 row_half_mirror row_mask:0xf bank_mask:0xf
	s_nop 1
	v_add_f32_dpp v112, v112, v112 row_mirror row_mask:0xf bank_mask:0xf
	s_nop 1
	v_add_f32_dpp v112, v112, v112 row_bcast:15 row_mask:0xa bank_mask:0xf
	s_nop 1
	v_add_f32_dpp v112, v112, v112 row_bcast:31 row_mask:0xc bank_mask:0xf
	s_nop 1
	v_readlane_b32 s2, v112, 63
	s_nop 1
	v_fmac_f32_e32 v16, s2, v142
	v_fmac_f32_e32 v17, s2, v142
	v_fmac_f32_e32 v18, s2, v142
	v_fmac_f32_e32 v19, s2, v142
	v_fmac_f32_e32 v20, s2, v142
	v_fmac_f32_e32 v21, s2, v142
	v_fmac_f32_e32 v22, s2, v142
	v_fmac_f32_e32 v23, s2, v142
	v_fmac_f32_e32 v24, s2, v142
	v_fmac_f32_e32 v25, s2, v142
	v_fmac_f32_e32 v26, s2, v142
	v_fmac_f32_e32 v27, s2, v142
	v_fmac_f32_e32 v28, s2, v142
	v_fmac_f32_e32 v29, s2, v142
	v_fmac_f32_e32 v30, s2, v142
	v_fmac_f32_e32 v31, s2, v142
	v_mul_f32_e32 v112, v16, v16
	v_mul_f32_e32 v113, v17, v17
	v_mul_f32_e32 v114, v18, v18
	v_mul_f32_e32 v115, v19, v19
	v_fmac_f32_e32 v112, v20, v20
	v_fmac_f32_e32 v113, v21, v21
	v_fmac_f32_e32 v114, v22, v22
	v_fmac_f32_e32 v115, v23, v23
	v_fmac_f32_e32 v112, v24, v24
	v_fmac_f32_e32 v113, v25, v25
	v_fmac_f32_e32 v114, v26, v26
	v_fmac_f32_e32 v115, v27, v27
	v_fmac_f32_e32 v112, v28, v28
	v_fmac_f32_e32 v113, v29, v29
	v_fmac_f32_e32 v114, v30, v30
	v_fmac_f32_e32 v115, v31, v31
	v_add_f32_e32 v112, v112, v113
	v_add_f32_e32 v114, v114, v115
	v_add_f32_e32 v112, v112, v114
	s_nop 1
	v_add_f32_dpp v112, v112, v112 quad_perm:[1,0,3,2] row_mask:0xf bank_mask:0xf
	s_nop 1
	v_add_f32_dpp v112, v112, v112 quad_perm:[2,3,0,1] row_mask:0xf bank_mask:0xf
	s_nop 1
	v_add_f32_dpp v112, v112, v112 row_half_mirror row_mask:0xf bank_mask:0xf
	s_nop 1
	v_add_f32_dpp v112, v112, v112 row_mirror row_mask:0xf bank_mask:0xf
	s_nop 1
	v_add_f32_dpp v112, v112, v112 row_bcast:15 row_mask:0xa bank_mask:0xf
	s_nop 1
	v_add_f32_dpp v112, v112, v112 row_bcast:31 row_mask:0xc bank_mask:0xf
	s_nop 1
	v_readlane_b32 s2, v112, 63
	s_nop 1
	v_mov_b32_e32 v113, 0x358637bd
	v_mov_b32_e32 v114, 0x3a800000
	v_fmac_f32_e32 v113, s2, v114
	v_rsq_f32_e32 v115, v113
	v_mul_f32_e32 v113, 0.5, v113
	v_mul_f32_e32 v116, v115, v115
	v_mov_b32_e32 v117, 0x3fc00000
	v_fma_f32 v116, -v113, v116, v117
	v_mul_f32_e32 v144, v115, v116
	v_pk_mul_f32 v[16:17], v[16:17], v[144:145] op_sel_hi:[1,0]
	v_pk_mul_f32 v[18:19], v[18:19], v[144:145] op_sel_hi:[1,0]
	v_pk_mul_f32 v[20:21], v[20:21], v[144:145] op_sel_hi:[1,0]
	v_pk_mul_f32 v[22:23], v[22:23], v[144:145] op_sel_hi:[1,0]
	v_pk_mul_f32 v[24:25], v[24:25], v[144:145] op_sel_hi:[1,0]
	v_pk_mul_f32 v[26:27], v[26:27], v[144:145] op_sel_hi:[1,0]
	v_pk_mul_f32 v[28:29], v[28:29], v[144:145] op_sel_hi:[1,0]
	v_pk_mul_f32 v[30:31], v[30:31], v[144:145] op_sel_hi:[1,0]
	s_waitcnt vmcnt(8)
	v_pk_add_f32 v[64:65], v[64:65], 1.0 op_sel_hi:[1,0]
	v_pk_add_f32 v[66:67], v[66:67], 1.0 op_sel_hi:[1,0]
	v_pk_add_f32 v[68:69], v[68:69], 1.0 op_sel_hi:[1,0]
	v_pk_add_f32 v[70:71], v[70:71], 1.0 op_sel_hi:[1,0]
	v_pk_add_f32 v[72:73], v[72:73], 1.0 op_sel_hi:[1,0]
	v_pk_add_f32 v[74:75], v[74:75], 1.0 op_sel_hi:[1,0]
	v_pk_add_f32 v[76:77], v[76:77], 1.0 op_sel_hi:[1,0]
	v_pk_add_f32 v[78:79], v[78:79], 1.0 op_sel_hi:[1,0]
	v_pk_fma_f32 v[16:17], v[64:65], v[16:17], v[48:49]
	v_pk_fma_f32 v[18:19], v[66:67], v[18:19], v[50:51]
	v_pk_fma_f32 v[20:21], v[68:69], v[20:21], v[52:53]
	v_pk_fma_f32 v[22:23], v[70:71], v[22:23], v[54:55]
	v_pk_fma_f32 v[24:25], v[72:73], v[24:25], v[56:57]
	v_pk_fma_f32 v[26:27], v[74:75], v[26:27], v[58:59]
	v_pk_fma_f32 v[28:29], v[76:77], v[28:29], v[60:61]
	v_pk_fma_f32 v[30:31], v[78:79], v[30:31], v[62:63]
	v_cvt_pk_bf16_f32 v120, v16, v17
	v_cvt_pk_bf16_f32 v121, v18, v19
	v_cvt_pk_bf16_f32 v122, v20, v21
	v_cvt_pk_bf16_f32 v123, v22, v23
	v_cvt_pk_bf16_f32 v124, v24, v25
	v_cvt_pk_bf16_f32 v125, v26, v27
	v_cvt_pk_bf16_f32 v126, v28, v29
	v_cvt_pk_bf16_f32 v127, v30, v31
	v_cndmask_b32_e64 v112, v122, v120, s[40:41]
	v_cndmask_b32_e64 v113, v123, v121, s[40:41]
	v_cndmask_b32_e64 v114, v126, v124, s[40:41]
	v_cndmask_b32_e64 v115, v127, v125, s[40:41]
	v_mov_b32_dpp v116, v112 quad_perm:[1,0,3,2] row_mask:0xf bank_mask:0xf
	v_mov_b32_dpp v117, v113 quad_perm:[1,0,3,2] row_mask:0xf bank_mask:0xf
	v_mov_b32_dpp v118, v114 quad_perm:[1,0,3,2] row_mask:0xf bank_mask:0xf
	v_mov_b32_dpp v119, v115 quad_perm:[1,0,3,2] row_mask:0xf bank_mask:0xf
	s_nop 0
	v_cndmask_b32_e64 v160, v120, v116, s[40:41]
	v_cndmask_b32_e64 v161, v121, v117, s[40:41]
	v_cndmask_b32_e64 v162, v116, v122, s[40:41]
	v_cndmask_b32_e64 v163, v117, v123, s[40:41]
	v_cndmask_b32_e64 v164, v124, v118, s[40:41]
	v_cndmask_b32_e64 v165, v125, v119, s[40:41]
	v_cndmask_b32_e64 v166, v118, v126, s[40:41]
	v_cndmask_b32_e64 v167, v119, v127, s[40:41]
	global_store_dwordx4 v[132:133], v[160:163], off
	global_store_dwordx4 v[132:133], v[164:167], off offset:1024
	v_lshl_add_u64 v[132:133], v[132:133], 0, v[154:155]
	global_load_dwordx4 v[16:19], v[128:129], off nt
	global_load_dwordx4 v[20:23], v[128:129], off offset:1024 nt
	global_load_dwordx4 v[24:27], v[128:129], off offset:2048 nt
	global_load_dwordx4 v[28:31], v[128:129], off offset:3072 nt
	v_lshl_add_u64 v[128:129], v[128:129], 0, v[152:153]
	v_add_f32_e32 v112, v32, v33
	v_add_f32_e32 v113, v34, v35
	v_add_f32_e32 v114, v36, v37
	v_add_f32_e32 v115, v38, v39
	v_add_f32_e32 v116, v40, v41
	v_add_f32_e32 v117, v42, v43
	v_add_f32_e32 v118, v44, v45
	v_add_f32_e32 v119, v46, v47
	v_add_f32_e32 v112, v112, v116
	v_add_f32_e32 v113, v113, v117
	v_add_f32_e32 v114, v114, v118
	v_add_f32_e32 v115, v115, v119
	v_add_f32_e32 v112, v112, v113
	v_add_f32_e32 v114, v114, v115
	v_add_f32_e32 v112, v112, v114
	s_nop 1
	v_add_f32_dpp v112, v112, v112 quad_perm:[1,0,3,2] row_mask:0xf bank_mask:0xf
	s_nop 1
	v_add_f32_dpp v112, v112, v112 quad_perm:[2,3,0,1] row_mask:0xf bank_mask:0xf
	s_nop 1
	v_add_f32_dpp v112, v112, v112 row_half_mirror row_mask:0xf bank_mask:0xf
	s_nop 1
	v_add_f32_dpp v112, v112, v112 row_mirror row_mask:0xf bank_mask:0xf
	s_nop 1
	v_add_f32_dpp v112, v112, v112 row_bcast:15 row_mask:0xa bank_mask:0xf
	s_nop 1
	v_add_f32_dpp v112, v112, v112 row_bcast:31 row_mask:0xc bank_mask:0xf
	s_nop 1
	v_readlane_b32 s2, v112, 63
	s_nop 1
	v_fmac_f32_e32 v32, s2, v142
	v_fmac_f32_e32 v33, s2, v142
	v_fmac_f32_e32 v34, s2, v142
	v_fmac_f32_e32 v35, s2, v142
	v_fmac_f32_e32 v36, s2, v142
	v_fmac_f32_e32 v37, s2, v142
	v_fmac_f32_e32 v38, s2, v142
	v_fmac_f32_e32 v39, s2, v142
	v_fmac_f32_e32 v40, s2, v142
	v_fmac_f32_e32 v41, s2, v142
	v_fmac_f32_e32 v42, s2, v142
	v_fmac_f32_e32 v43, s2, v142
	v_fmac_f32_e32 v44, s2, v142
	v_fmac_f32_e32 v45, s2, v142
	v_fmac_f32_e32 v46, s2, v142
	v_fmac_f32_e32 v47, s2, v142
	v_mul_f32_e32 v112, v32, v32
	v_mul_f32_e32 v113, v33, v33
	v_mul_f32_e32 v114, v34, v34
	v_mul_f32_e32 v115, v35, v35
	v_fmac_f32_e32 v112, v36, v36
	v_fmac_f32_e32 v113, v37, v37
	v_fmac_f32_e32 v114, v38, v38
	v_fmac_f32_e32 v115, v39, v39
	v_fmac_f32_e32 v112, v40, v40
	v_fmac_f32_e32 v113, v41, v41
	v_fmac_f32_e32 v114, v42, v42
	v_fmac_f32_e32 v115, v43, v43
	v_fmac_f32_e32 v112, v44, v44
	v_fmac_f32_e32 v113, v45, v45
	v_fmac_f32_e32 v114, v46, v46
	v_fmac_f32_e32 v115, v47, v47
	v_add_f32_e32 v112, v112, v113
	v_add_f32_e32 v114, v114, v115
	v_add_f32_e32 v112, v112, v114
	s_nop 1
	v_add_f32_dpp v112, v112, v112 quad_perm:[1,0,3,2] row_mask:0xf bank_mask:0xf
	s_nop 1
	v_add_f32_dpp v112, v112, v112 quad_perm:[2,3,0,1] row_mask:0xf bank_mask:0xf
	s_nop 1
	v_add_f32_dpp v112, v112, v112 row_half_mirror row_mask:0xf bank_mask:0xf
	s_nop 1
	v_add_f32_dpp v112, v112, v112 row_mirror row_mask:0xf bank_mask:0xf
	s_nop 1
	v_add_f32_dpp v112, v112, v112 row_bcast:15 row_mask:0xa bank_mask:0xf
	s_nop 1
	v_add_f32_dpp v112, v112, v112 row_bcast:31 row_mask:0xc bank_mask:0xf
	s_nop 1
	v_readlane_b32 s2, v112, 63
	s_nop 1
	v_mov_b32_e32 v113, 0x358637bd
	v_mov_b32_e32 v114, 0x3a800000
	v_fmac_f32_e32 v113, s2, v114
	v_rsq_f32_e32 v115, v113
	v_mul_f32_e32 v113, 0.5, v113
	v_mul_f32_e32 v116, v115, v115
	v_mov_b32_e32 v117, 0x3fc00000
	v_fma_f32 v116, -v113, v116, v117
	v_mul_f32_e32 v144, v115, v116
	v_pk_mul_f32 v[32:33], v[32:33], v[144:145] op_sel_hi:[1,0]
	v_pk_mul_f32 v[34:35], v[34:35], v[144:145] op_sel_hi:[1,0]
	v_pk_mul_f32 v[36:37], v[36:37], v[144:145] op_sel_hi:[1,0]
	v_pk_mul_f32 v[38:39], v[38:39], v[144:145] op_sel_hi:[1,0]
	v_pk_mul_f32 v[40:41], v[40:41], v[144:145] op_sel_hi:[1,0]
	v_pk_mul_f32 v[42:43], v[42:43], v[144:145] op_sel_hi:[1,0]
	v_pk_mul_f32 v[44:45], v[44:45], v[144:145] op_sel_hi:[1,0]
	v_pk_mul_f32 v[46:47], v[46:47], v[144:145] op_sel_hi:[1,0]
	v_pk_fma_f32 v[32:33], v[80:81], v[32:33], v[96:97]
	v_pk_fma_f32 v[34:35], v[82:83], v[34:35], v[98:99]
	v_pk_fma_f32 v[36:37], v[84:85], v[36:37], v[100:101]
	v_pk_fma_f32 v[38:39], v[86:87], v[38:39], v[102:103]
	v_pk_fma_f32 v[40:41], v[88:89], v[40:41], v[104:105]
	v_pk_fma_f32 v[42:43], v[90:91], v[42:43], v[106:107]
	v_pk_fma_f32 v[44:45], v[92:93], v[44:45], v[108:109]
	v_pk_fma_f32 v[46:47], v[94:95], v[46:47], v[110:111]
	global_store_dwordx4 v[130:131], v[32:35], off
	global_store_dwordx4 v[130:131], v[36:39], off offset:1024
	global_store_dwordx4 v[130:131], v[40:43], off offset:2048
	global_store_dwordx4 v[130:131], v[44:47], off offset:3072
	v_lshl_add_u64 v[130:131], v[130:131], 0, v[152:153]
	v_add_f32_e32 v112, v32, v33
	v_add_f32_e32 v113, v34, v35
	v_add_f32_e32 v114, v36, v37
	v_add_f32_e32 v115, v38, v39
	v_add_f32_e32 v116, v40, v41
	v_add_f32_e32 v117, v42, v43
	v_add_f32_e32 v118, v44, v45
	v_add_f32_e32 v119, v46, v47
	v_add_f32_e32 v112, v112, v116
	v_add_f32_e32 v113, v113, v117
	v_add_f32_e32 v114, v114, v118
	v_add_f32_e32 v115, v115, v119
	v_add_f32_e32 v112, v112, v113
	v_add_f32_e32 v114, v114, v115
	v_add_f32_e32 v112, v112, v114
	s_nop 1
	v_add_f32_dpp v112, v112, v112 quad_perm:[1,0,3,2] row_mask:0xf bank_mask:0xf
	s_nop 1
	v_add_f32_dpp v112, v112, v112 quad_perm:[2,3,0,1] row_mask:0xf bank_mask:0xf
	s_nop 1
	v_add_f32_dpp v112, v112, v112 row_half_mirror row_mask:0xf bank_mask:0xf
	s_nop 1
	v_add_f32_dpp v112, v112, v112 row_mirror row_mask:0xf bank_mask:0xf
	s_nop 1
	v_add_f32_dpp v112, v112, v112 row_bcast:15 row_mask:0xa bank_mask:0xf
	s_nop 1
	v_add_f32_dpp v112, v112, v112 row_bcast:31 row_mask:0xc bank_mask:0xf
	s_nop 1
	v_readlane_b32 s2, v112, 63
	s_nop 1
	v_fmac_f32_e32 v32, s2, v142
	v_fmac_f32_e32 v33, s2, v142
	v_fmac_f32_e32 v34, s2, v142
	v_fmac_f32_e32 v35, s2, v142
	v_fmac_f32_e32 v36, s2, v142
	v_fmac_f32_e32 v37, s2, v142
	v_fmac_f32_e32 v38, s2, v142
	v_fmac_f32_e32 v39, s2, v142
	v_fmac_f32_e32 v40, s2, v142
	v_fmac_f32_e32 v41, s2, v142
	v_fmac_f32_e32 v42, s2, v142
	v_fmac_f32_e32 v43, s2, v142
	v_fmac_f32_e32 v44, s2, v142
	v_fmac_f32_e32 v45, s2, v142
	v_fmac_f32_e32 v46, s2, v142
	v_fmac_f32_e32 v47, s2, v142
	v_mul_f32_e32 v112, v32, v32
	v_mul_f32_e32 v113, v33, v33
	v_mul_f32_e32 v114, v34, v34
	v_mul_f32_e32 v115, v35, v35
	v_fmac_f32_e32 v112, v36, v36
	v_fmac_f32_e32 v113, v37, v37
	v_fmac_f32_e32 v114, v38, v38
	v_fmac_f32_e32 v115, v39, v39
	v_fmac_f32_e32 v112, v40, v40
	v_fmac_f32_e32 v113, v41, v41
	v_fmac_f32_e32 v114, v42, v42
	v_fmac_f32_e32 v115, v43, v43
	v_fmac_f32_e32 v112, v44, v44
	v_fmac_f32_e32 v113, v45, v45
	v_fmac_f32_e32 v114, v46, v46
	v_fmac_f32_e32 v115, v47, v47
	v_add_f32_e32 v112, v112, v113
	v_add_f32_e32 v114, v114, v115
	v_add_f32_e32 v112, v112, v114
	s_nop 1
	v_add_f32_dpp v112, v112, v112 quad_perm:[1,0,3,2] row_mask:0xf bank_mask:0xf
	s_nop 1
	v_add_f32_dpp v112, v112, v112 quad_perm:[2,3,0,1] row_mask:0xf bank_mask:0xf
	s_nop 1
	v_add_f32_dpp v112, v112, v112 row_half_mirror row_mask:0xf bank_mask:0xf
	s_nop 1
	v_add_f32_dpp v112, v112, v112 row_mirror row_mask:0xf bank_mask:0xf
	s_nop 1
	v_add_f32_dpp v112, v112, v112 row_bcast:15 row_mask:0xa bank_mask:0xf
	s_nop 1
	v_add_f32_dpp v112, v112, v112 row_bcast:31 row_mask:0xc bank_mask:0xf
	s_nop 1
	v_readlane_b32 s2, v112, 63
	s_nop 1
	v_mov_b32_e32 v113, 0x358637bd
	v_mov_b32_e32 v114, 0x3a800000
	v_fmac_f32_e32 v113, s2, v114
	v_rsq_f32_e32 v115, v113
	v_mul_f32_e32 v113, 0.5, v113
	v_mul_f32_e32 v116, v115, v115
	v_mov_b32_e32 v117, 0x3fc00000
	v_fma_f32 v116, -v113, v116, v117
	v_mul_f32_e32 v144, v115, v116
	v_pk_mul_f32 v[32:33], v[32:33], v[144:145] op_sel_hi:[1,0]
	v_pk_mul_f32 v[34:35], v[34:35], v[144:145] op_sel_hi:[1,0]
	v_pk_mul_f32 v[36:37], v[36:37], v[144:145] op_sel_hi:[1,0]
	v_pk_mul_f32 v[38:39], v[38:39], v[144:145] op_sel_hi:[1,0]
	v_pk_mul_f32 v[40:41], v[40:41], v[144:145] op_sel_hi:[1,0]
	v_pk_mul_f32 v[42:43], v[42:43], v[144:145] op_sel_hi:[1,0]
	v_pk_mul_f32 v[44:45], v[44:45], v[144:145] op_sel_hi:[1,0]
	v_pk_mul_f32 v[46:47], v[46:47], v[144:145] op_sel_hi:[1,0]
	v_pk_fma_f32 v[32:33], v[64:65], v[32:33], v[48:49]
	v_pk_fma_f32 v[34:35], v[66:67], v[34:35], v[50:51]
	v_pk_fma_f32 v[36:37], v[68:69], v[36:37], v[52:53]
	v_pk_fma_f32 v[38:39], v[70:71], v[38:39], v[54:55]
	v_pk_fma_f32 v[40:41], v[72:73], v[40:41], v[56:57]
	v_pk_fma_f32 v[42:43], v[74:75], v[42:43], v[58:59]
	v_pk_fma_f32 v[44:45], v[76:77], v[44:45], v[60:61]
	v_pk_fma_f32 v[46:47], v[78:79], v[46:47], v[62:63]
	v_cvt_pk_bf16_f32 v120, v32, v33
	v_cvt_pk_bf16_f32 v121, v34, v35
	v_cvt_pk_bf16_f32 v122, v36, v37
	v_cvt_pk_bf16_f32 v123, v38, v39
	v_cvt_pk_bf16_f32 v124, v40, v41
	v_cvt_pk_bf16_f32 v125, v42, v43
	v_cvt_pk_bf16_f32 v126, v44, v45
	v_cvt_pk_bf16_f32 v127, v46, v47
	v_cndmask_b32_e64 v112, v122, v120, s[40:41]
	v_cndmask_b32_e64 v113, v123, v121, s[40:41]
	v_cndmask_b32_e64 v114, v126, v124, s[40:41]
	v_cndmask_b32_e64 v115, v127, v125, s[40:41]
	v_mov_b32_dpp v116, v112 quad_perm:[1,0,3,2] row_mask:0xf bank_mask:0xf
	v_mov_b32_dpp v117, v113 quad_perm:[1,0,3,2] row_mask:0xf bank_mask:0xf
	v_mov_b32_dpp v118, v114 quad_perm:[1,0,3,2] row_mask:0xf bank_mask:0xf
	v_mov_b32_dpp v119, v115 quad_perm:[1,0,3,2] row_mask:0xf bank_mask:0xf
	s_nop 0
	v_cndmask_b32_e64 v160, v120, v116, s[40:41]
	v_cndmask_b32_e64 v161, v121, v117, s[40:41]
	v_cndmask_b32_e64 v162, v116, v122, s[40:41]
	v_cndmask_b32_e64 v163, v117, v123, s[40:41]
	v_cndmask_b32_e64 v164, v124, v118, s[40:41]
	v_cndmask_b32_e64 v165, v125, v119, s[40:41]
	v_cndmask_b32_e64 v166, v118, v126, s[40:41]
	v_cndmask_b32_e64 v167, v119, v127, s[40:41]
	global_store_dwordx4 v[132:133], v[160:163], off
	global_store_dwordx4 v[132:133], v[164:167], off offset:1024
	v_lshl_add_u64 v[132:133], v[132:133], 0, v[154:155]
	s_add_i32 s0, s0, 1
	s_cmp_lt_i32 s0, 3
	s_cbranch_scc1 .Lln1a_loop
	s_branch .LBB0_438
.Lln1_layer1:
	v_readlane_b32 s2, v254, 38
	v_lshrrev_b32_e32 v146, 6, v221
	v_and_b32_e32 v112, 63, v221
	v_mov_b32_e32 v152, 0x800000
	v_mov_b32_e32 v153, 0
	v_mov_b32_e32 v154, 0x400000
	v_mov_b32_e32 v155, 0
	v_mov_b32_e32 v156, 0x3000
	v_mov_b32_e32 v157, 0
	v_add_u32_e32 v146, s2, v146
	v_lshlrev_b32_e32 v148, 4, v112
	v_mov_b32_e32 v149, 0
	v_lshlrev_b32_e32 v150, 3, v112
	v_mov_b32_e32 v151, 0
	v_lshl_add_u32 v140, v146, 12, v148
	v_mov_b32_e32 v141, 0
	v_mov_b32_e32 v142, 0xba800000
	s_mov_b32 s0, 0
	v_add_u32_e32 v114, 0x1c000, v148
	v_mov_b32_e32 v115, 0
	v_lshl_add_u64 v[134:135], s[60:61], 0, v[114:115]
	v_lshl_add_u64 v[128:129], s[98:99], 0, v[140:141]
	v_mov_b32_e32 v130, v128
	v_mov_b32_e32 v131, v129
	v_readlane_b32 s42, v255, 6
	s_lshl_b32 s42, s42, 12
	s_add_u32 s44, s94, s42
	s_addc_u32 s45, s95, 0
	s_add_u32 s42, s96, s42
	s_addc_u32 s43, s97, 0
	v_lshl_add_u64 v[136:137], s[44:45], 0, v[148:149]
	v_lshl_add_u64 v[138:139], s[42:43], 0, v[148:149]
	global_load_dwordx4 v[80:83], v[136:137], off
	global_load_dwordx4 v[84:87], v[136:137], off offset:1024
	global_load_dwordx4 v[88:91], v[136:137], off offset:2048
	global_load_dwordx4 v[92:95], v[136:137], off offset:3072
	global_load_dwordx4 v[96:99], v[138:139], off
	global_load_dwordx4 v[100:103], v[138:139], off offset:1024
	global_load_dwordx4 v[104:107], v[138:139], off offset:2048
	global_load_dwordx4 v[108:111], v[138:139], off offset:3072
	global_load_dwordx4 v[0:3], v[128:129], off nt
	global_load_dwordx4 v[4:7], v[128:129], off offset:1024 nt
	global_load_dwordx4 v[8:11], v[128:129], off offset:2048 nt
	global_load_dwordx4 v[12:15], v[128:129], off offset:3072 nt
	v_lshl_add_u64 v[128:129], v[128:129], 0, v[152:153]
	global_load_dword v158, v[134:135], off
	global_load_dword v158, v[134:135], off
	global_load_dword v158, v[134:135], off
	global_load_dword v158, v[134:135], off
	global_load_dwordx4 v[16:19], v[128:129], off nt
	global_load_dwordx4 v[20:23], v[128:129], off offset:1024 nt
	global_load_dwordx4 v[24:27], v[128:129], off offset:2048 nt
	global_load_dwordx4 v[28:31], v[128:129], off offset:3072 nt
	v_lshl_add_u64 v[128:129], v[128:129], 0, v[152:153]
	global_load_dword v158, v[134:135], off
	global_load_dword v158, v[134:135], off
	global_load_dword v158, v[134:135], off
	global_load_dword v158, v[134:135], off
.Lln1b_loop:
	global_load_dwordx4 v[32:35], v[128:129], off nt
	global_load_dwordx4 v[36:39], v[128:129], off offset:1024 nt
	global_load_dwordx4 v[40:43], v[128:129], off offset:2048 nt
	global_load_dwordx4 v[44:47], v[128:129], off offset:3072 nt
	v_lshl_add_u64 v[128:129], v[128:129], 0, v[152:153]
	s_waitcnt vmcnt(16)
	v_add_f32_e32 v112, v0, v1
	v_add_f32_e32 v113, v2, v3
	v_add_f32_e32 v114, v4, v5
	v_add_f32_e32 v115, v6, v7
	v_add_f32_e32 v116, v8, v9
	v_add_f32_e32 v117, v10, v11
	v_add_f32_e32 v118, v12, v13
	v_add_f32_e32 v119, v14, v15
	v_add_f32_e32 v112, v112, v116
	v_add_f32_e32 v113, v113, v117
	v_add_f32_e32 v114, v114, v118
	v_add_f32_e32 v115, v115, v119
	v_add_f32_e32 v112, v112, v113
	v_add_f32_e32 v114, v114, v115
	v_add_f32_e32 v112, v112, v114
	s_nop 1
	v_add_f32_dpp v112, v112, v112 quad_perm:[1,0,3,2] row_mask:0xf bank_mask:0xf
	s_nop 1
	v_add_f32_dpp v112, v112, v112 quad_perm:[2,3,0,1] row_mask:0xf bank_mask:0xf
	s_nop 1
	v_add_f32_dpp v112, v112, v112 row_half_mirror row_mask:0xf bank_mask:0xf
	s_nop 1
	v_add_f32_dpp v112, v112, v112 row_mirror row_mask:0xf bank_mask:0xf
	s_nop 1
	v_add_f32_dpp v112, v112, v112 row_bcast:15 row_mask:0xa bank_mask:0xf
	s_nop 1
	v_add_f32_dpp v112, v112, v112 row_bcast:31 row_mask:0xc bank_mask:0xf
	s_nop 1
	v_readlane_b32 s2, v112, 63
	s_nop 1
	v_fmac_f32_e32 v0, s2, v142
	v_fmac_f32_e32 v1, s2, v142
	v_fmac_f32_e32 v2, s2, v142
	v_fmac_f32_e32 v3, s2, v142
	v_fmac_f32_e32 v4, s2, v142
	v_fmac_f32_e32 v5, s2, v142
	v_fmac_f32_e32 v6, s2, v142
	v_fmac_f32_e32 v7, s2, v142
	v_fmac_f32_e32 v8, s2, v142
	v_fmac_f32_e32 v9, s2, v142
	v_fmac_f32_e32 v10, s2, v142
	v_fmac_f32_e32 v11, s2, v142
	v_fmac_f32_e32 v12, s2, v142
	v_fmac_f32_e32 v13, s2, v142
	v_fmac_f32_e32 v14, s2, v142
	v_fmac_f32_e32 v15, s2, v142
	v_mul_f32_e32 v112, v0, v0
	v_mul_f32_e32 v113, v1, v1
	v_mul_f32_e32 v114, v2, v2
	v_mul_f32_e32 v115, v3, v3
	v_fmac_f32_e32 v112, v4, v4
	v_fmac_f32_e32 v113, v5, v5
	v_fmac_f32_e32 v114, v6, v6
	v_fmac_f32_e32 v115, v7, v7
	v_fmac_f32_e32 v112, v8, v8
	v_fmac_f32_e32 v113, v9, v9
	v_fmac_f32_e32 v114, v10, v10
	v_fmac_f32_e32 v115, v11, v11
	v_fmac_f32_e32 v112, v12, v12
	v_fmac_f32_e32 v113, v13, v13
	v_fmac_f32_e32 v114, v14, v14
	v_fmac_f32_e32 v115, v15, v15
	v_add_f32_e32 v112, v112, v113
	v_add_f32_e32 v114, v114, v115
	v_add_f32_e32 v112, v112, v114
	s_nop 1
	v_add_f32_dpp v112, v112, v112 quad_perm:[1,0,3,2] row_mask:0xf bank_mask:0xf
	s_nop 1
	v_add_f32_dpp v112, v112, v112 quad_perm:[2,3,0,1] row_mask:0xf bank_mask:0xf
	s_nop 1
	v_add_f32_dpp v112, v112, v112 row_half_mirror row_mask:0xf bank_mask:0xf
	s_nop 1
	v_add_f32_dpp v112, v112, v112 row_mirror row_mask:0xf bank_mask:0xf
	s_nop 1
	v_add_f32_dpp v112, v112, v112 row_bcast:15 row_mask:0xa bank_mask:0xf
	s_nop 1
	v_add_f32_dpp v112, v112, v112 row_bcast:31 row_mask:0xc bank_mask:0xf
	s_nop 1
	v_readlane_b32 s2, v112, 63
	s_nop 1
	v_mov_b32_e32 v113, 0x358637bd
	v_mov_b32_e32 v114, 0x3a800000
	v_fmac_f32_e32 v113, s2, v114
	v_rsq_f32_e32 v115, v113
	v_mul_f32_e32 v113, 0.5, v113
	v_mul_f32_e32 v116, v115, v115
	v_mov_b32_e32 v117, 0x3fc00000
	v_fma_f32 v116, -v113, v116, v117
	v_mul_f32_e32 v144, v115, v116
	v_pk_mul_f32 v[0:1], v[0:1], v[144:145] op_sel_hi:[1,0]
	v_pk_mul_f32 v[2:3], v[2:3], v[144:145] op_sel_hi:[1,0]
	v_pk_mul_f32 v[4:5], v[4:5], v[144:145] op_sel_hi:[1,0]
	v_pk_mul_f32 v[6:7], v[6:7], v[144:145] op_sel_hi:[1,0]
	v_pk_mul_f32 v[8:9], v[8:9], v[144:145] op_sel_hi:[1,0]
	v_pk_mul_f32 v[10:11], v[10:11], v[144:145] op_sel_hi:[1,0]
	v_pk_mul_f32 v[12:13], v[12:13], v[144:145] op_sel_hi:[1,0]
	v_pk_mul_f32 v[14:15], v[14:15], v[144:145] op_sel_hi:[1,0]
	v_pk_fma_f32 v[0:1], v[80:81], v[0:1], v[96:97]
	v_pk_fma_f32 v[2:3], v[82:83], v[2:3], v[98:99]
	v_pk_fma_f32 v[4:5], v[84:85], v[4:5], v[100:101]
	v_pk_fma_f32 v[6:7], v[86:87], v[6:7], v[102:103]
	v_pk_fma_f32 v[8:9], v[88:89], v[8:9], v[104:105]
	v_pk_fma_f32 v[10:11], v[90:91], v[10:11], v[106:107]
	v_pk_fma_f32 v[12:13], v[92:93], v[12:13], v[108:109]
	v_pk_fma_f32 v[14:15], v[94:95], v[14:15], v[110:111]
	global_store_dwordx4 v[130:131], v[0:3], off
	global_store_dwordx4 v[130:131], v[4:7], off offset:1024
	global_store_dwordx4 v[130:131], v[8:11], off offset:2048
	global_store_dwordx4 v[130:131], v[12:15], off offset:3072
	v_lshl_add_u64 v[130:131], v[130:131], 0, v[152:153]
	global_load_dwordx4 v[0:3], v[128:129], off nt
	global_load_dwordx4 v[4:7], v[128:129], off offset:1024 nt
	global_load_dwordx4 v[8:11], v[128:129], off offset:2048 nt
	global_load_dwordx4 v[12:15], v[128:129], off offset:3072 nt
	v_lshl_add_u64 v[128:129], v[128:129], 0, v[152:153]
	s_waitcnt vmcnt(16)
	v_add_f32_e32 v112, v16, v17
	v_add_f32_e32 v113, v18, v19
	v_add_f32_e32 v114, v20, v21
	v_add_f32_e32 v115, v22, v23
	v_add_f32_e32 v116, v24, v25
	v_add_f32_e32 v117, v26, v27
	v_add_f32_e32 v118, v28, v29
	v_add_f32_e32 v119, v30, v31
	v_add_f32_e32 v112, v112, v116
	v_add_f32_e32 v113, v113, v117
	v_add_f32_e32 v114, v114, v118
	v_add_f32_e32 v115, v115, v119
	v_add_f32_e32 v112, v112, v113
	v_add_f32_e32 v114, v114, v115
	v_add_f32_e32 v112, v112, v114
	s_nop 1
	v_add_f32_dpp v112, v112, v112 quad_perm:[1,0,3,2] row_mask:0xf bank_mask:0xf
	s_nop 1
	v_add_f32_dpp v112, v112, v112 quad_perm:[2,3,0,1] row_mask:0xf bank_mask:0xf
	s_nop 1
	v_add_f32_dpp v112, v112, v112 row_half_mirror row_mask:0xf bank_mask:0xf
	s_nop 1
	v_add_f32_dpp v112, v112, v112 row_mirror row_mask:0xf bank_mask:0xf
	s_nop 1
	v_add_f32_dpp v112, v112, v112 row_bcast:15 row_mask:0xa bank_mask:0xf
	s_nop 1
	v_add_f32_dpp v112, v112, v112 row_bcast:31 row_mask:0xc bank_mask:0xf
	s_nop 1
	v_readlane_b32 s2, v112, 63
	s_nop 1
	v_fmac_f32_e32 v16, s2, v142
	v_fmac_f32_e32 v17, s2, v142
	v_fmac_f32_e32 v18, s2, v142
	v_fmac_f32_e32 v19, s2, v142
	v_fmac_f32_e32 v20, s2, v142
	v_fmac_f32_e32 v21, s2, v142
	v_fmac_f32_e32 v22, s2, v142
	v_fmac_f32_e32 v23, s2, v142
	v_fmac_f32_e32 v24, s2, v142
	v_fmac_f32_e32 v25, s2, v142
	v_fmac_f32_e32 v26, s2, v142
	v_fmac_f32_e32 v27, s2, v142
	v_fmac_f32_e32 v28, s2, v142
	v_fmac_f32_e32 v29, s2, v142
	v_fmac_f32_e32 v30, s2, v142
	v_fmac_f32_e32 v31, s2, v142
	v_mul_f32_e32 v112, v16, v16
	v_mul_f32_e32 v113, v17, v17
	v_mul_f32_e32 v114, v18, v18
	v_mul_f32_e32 v115, v19, v19
	v_fmac_f32_e32 v112, v20, v20
	v_fmac_f32_e32 v113, v21, v21
	v_fmac_f32_e32 v114, v22, v22
	v_fmac_f32_e32 v115, v23, v23
	v_fmac_f32_e32 v112, v24, v24
	v_fmac_f32_e32 v113, v25, v25
	v_fmac_f32_e32 v114, v26, v26
	v_fmac_f32_e32 v115, v27, v27
	v_fmac_f32_e32 v112, v28, v28
	v_fmac_f32_e32 v113, v29, v29
	v_fmac_f32_e32 v114, v30, v30
	v_fmac_f32_e32 v115, v31, v31
	v_add_f32_e32 v112, v112, v113
	v_add_f32_e32 v114, v114, v115
	v_add_f32_e32 v112, v112, v114
	s_nop 1
	v_add_f32_dpp v112, v112, v112 quad_perm:[1,0,3,2] row_mask:0xf bank_mask:0xf
	s_nop 1
	v_add_f32_dpp v112, v112, v112 quad_perm:[2,3,0,1] row_mask:0xf bank_mask:0xf
	s_nop 1
	v_add_f32_dpp v112, v112, v112 row_half_mirror row_mask:0xf bank_mask:0xf
	s_nop 1
	v_add_f32_dpp v112, v112, v112 row_mirror row_mask:0xf bank_mask:0xf
	s_nop 1
	v_add_f32_dpp v112, v112, v112 row_bcast:15 row_mask:0xa bank_mask:0xf
	s_nop 1
	v_add_f32_dpp v112, v112, v112 row_bcast:31 row_mask:0xc bank_mask:0xf
	s_nop 1
	v_readlane_b32 s2, v112, 63
	s_nop 1
	v_mov_b32_e32 v113, 0x358637bd
	v_mov_b32_e32 v114, 0x3a800000
	v_fmac_f32_e32 v113, s2, v114
	v_rsq_f32_e32 v115, v113
	v_mul_f32_e32 v113, 0.5, v113
	v_mul_f32_e32 v116, v115, v115
	v_mov_b32_e32 v117, 0x3fc00000
	v_fma_f32 v116, -v113, v116, v117
	v_mul_f32_e32 v144, v115, v116
	v_pk_mul_f32 v[16:17], v[16:17], v[144:145] op_sel_hi:[1,0]
	v_pk_mul_f32 v[18:19], v[18:19], v[144:145] op_sel_hi:[1,0]
	v_pk_mul_f32 v[20:21], v[20:21], v[144:145] op_sel_hi:[1,0]
	v_pk_mul_f32 v[22:23], v[22:23], v[144:145] op_sel_hi:[1,0]
	v_pk_mul_f32 v[24:25], v[24:25], v[144:145] op_sel_hi:[1,0]
	v_pk_mul_f32 v[26:27], v[26:27], v[144:145] op_sel_hi:[1,0]
	v_pk_mul_f32 v[28:29], v[28:29], v[144:145] op_sel_hi:[1,0]
	v_pk_mul_f32 v[30:31], v[30:31], v[144:145] op_sel_hi:[1,0]
	v_pk_fma_f32 v[16:17], v[80:81], v[16:17], v[96:97]
	v_pk_fma_f32 v[18:19], v[82:83], v[18:19], v[98:99]
	v_pk_fma_f32 v[20:21], v[84:85], v[20:21], v[100:101]
	v_pk_fma_f32 v[22:23], v[86:87], v[22:23], v[102:103]
	v_pk_fma_f32 v[24:25], v[88:89], v[24:25], v[104:105]
	v_pk_fma_f32 v[26:27], v[90:91], v[26:27], v[106:107]
	v_pk_fma_f32 v[28:29], v[92:93], v[28:29], v[108:109]
	v_pk_fma_f32 v[30:31], v[94:95], v[30:31], v[110:111]
	global_store_dwordx4 v[130:131], v[16:19], off
	global_store_dwordx4 v[130:131], v[20:23], off offset:1024
	global_store_dwordx4 v[130:131], v[24:27], off offset:2048
	global_store_dwordx4 v[130:131], v[28:31], off offset:3072
	v_lshl_add_u64 v[130:131], v[130:131], 0, v[152:153]
	global_load_dwordx4 v[16:19], v[128:129], off nt
	global_load_dwordx4 v[20:23], v[128:129], off offset:1024 nt
	global_load_dwordx4 v[24:27], v[128:129], off offset:2048 nt
	global_load_dwordx4 v[28:31], v[128:129], off offset:3072 nt
	v_lshl_add_u64 v[128:129], v[128:129], 0, v[152:153]
	s_waitcnt vmcnt(16)
	v_add_f32_e32 v112, v32, v33
	v_add_f32_e32 v113, v34, v35
	v_add_f32_e32 v114, v36, v37
	v_add_f32_e32 v115, v38, v39
	v_add_f32_e32 v116, v40, v41
	v_add_f32_e32 v117, v42, v43
	v_add_f32_e32 v118, v44, v45
	v_add_f32_e32 v119, v46, v47
	v_add_f32_e32 v112, v112, v116
	v_add_f32_e32 v113, v113, v117
	v_add_f32_e32 v114, v114, v118
	v_add_f32_e32 v115, v115, v119
	v_add_f32_e32 v112, v112, v113
	v_add_f32_e32 v114, v114, v115
	v_add_f32_e32 v112, v112, v114
	s_nop 1
	v_add_f32_dpp v112, v112, v112 quad_perm:[1,0,3,2] row_mask:0xf bank_mask:0xf
	s_nop 1
	v_add_f32_dpp v112, v112, v112 quad_perm:[2,3,0,1] row_mask:0xf bank_mask:0xf
	s_nop 1
	v_add_f32_dpp v112, v112, v112 row_half_mirror row_mask:0xf bank_mask:0xf
	s_nop 1
	v_add_f32_dpp v112, v112, v112 row_mirror row_mask:0xf bank_mask:0xf
	s_nop 1
	v_add_f32_dpp v112, v112, v112 row_bcast:15 row_mask:0xa bank_mask:0xf
	s_nop 1
	v_add_f32_dpp v112, v112, v112 row_bcast:31 row_mask:0xc bank_mask:0xf
	s_nop 1
	v_readlane_b32 s2, v112, 63
	s_nop 1
	v_fmac_f32_e32 v32, s2, v142
	v_fmac_f32_e32 v33, s2, v142
	v_fmac_f32_e32 v34, s2, v142
	v_fmac_f32_e32 v35, s2, v142
	v_fmac_f32_e32 v36, s2, v142
	v_fmac_f32_e32 v37, s2, v142
	v_fmac_f32_e32 v38, s2, v142
	v_fmac_f32_e32 v39, s2, v142
	v_fmac_f32_e32 v40, s2, v142
	v_fmac_f32_e32 v41, s2, v142
	v_fmac_f32_e32 v42, s2, v142
	v_fmac_f32_e32 v43, s2, v142
	v_fmac_f32_e32 v44, s2, v142
	v_fmac_f32_e32 v45, s2, v142
	v_fmac_f32_e32 v46, s2, v142
	v_fmac_f32_e32 v47, s2, v142
	v_mul_f32_e32 v112, v32, v32
	v_mul_f32_e32 v113, v33, v33
	v_mul_f32_e32 v114, v34, v34
	v_mul_f32_e32 v115, v35, v35
	v_fmac_f32_e32 v112, v36, v36
	v_fmac_f32_e32 v113, v37, v37
	v_fmac_f32_e32 v114, v38, v38
	v_fmac_f32_e32 v115, v39, v39
	v_fmac_f32_e32 v112, v40, v40
	v_fmac_f32_e32 v113, v41, v41
	v_fmac_f32_e32 v114, v42, v42
	v_fmac_f32_e32 v115, v43, v43
	v_fmac_f32_e32 v112, v44, v44
	v_fmac_f32_e32 v113, v45, v45
	v_fmac_f32_e32 v114, v46, v46
	v_fmac_f32_e32 v115, v47, v47
	v_add_f32_e32 v112, v112, v113
	v_add_f32_e32 v114, v114, v115
	v_add_f32_e32 v112, v112, v114
	s_nop 1
	v_add_f32_dpp v112, v112, v112 quad_perm:[1,0,3,2] row_mask:0xf bank_mask:0xf
	s_nop 1
	v_add_f32_dpp v112, v112, v112 quad_perm:[2,3,0,1] row_mask:0xf bank_mask:0xf
	s_nop 1
	v_add_f32_dpp v112, v112, v112 row_half_mirror row_mask:0xf bank_mask:0xf
	s_nop 1
	v_add_f32_dpp v112, v112, v112 row_mirror row_mask:0xf bank_mask:0xf
	s_nop 1
	v_add_f32_dpp v112, v112, v112 row_bcast:15 row_mask:0xa bank_mask:0xf
	s_nop 1
	v_add_f32_dpp v112, v112, v112 row_bcast:31 row_mask:0xc bank_mask:0xf
	s_nop 1
	v_readlane_b32 s2, v112, 63
	s_nop 1
	v_mov_b32_e32 v113, 0x358637bd
	v_mov_b32_e32 v114, 0x3a800000
	v_fmac_f32_e32 v113, s2, v114
	v_rsq_f32_e32 v115, v113
	v_mul_f32_e32 v113, 0.5, v113
	v_mul_f32_e32 v116, v115, v115
	v_mov_b32_e32 v117, 0x3fc00000
	v_fma_f32 v116, -v113, v116, v117
	v_mul_f32_e32 v144, v115, v116
	v_pk_mul_f32 v[32:33], v[32:33], v[144:145] op_sel_hi:[1,0]
	v_pk_mul_f32 v[34:35], v[34:35], v[144:145] op_sel_hi:[1,0]
	v_pk_mul_f32 v[36:37], v[36:37], v[144:145] op_sel_hi:[1,0]
	v_pk_mul_f32 v[38:39], v[38:39], v[144:145] op_sel_hi:[1,0]
	v_pk_mul_f32 v[40:41], v[40:41], v[144:145] op_sel_hi:[1,0]
	v_pk_mul_f32 v[42:43], v[42:43], v[144:145] op_sel_hi:[1,0]
	v_pk_mul_f32 v[44:45], v[44:45], v[144:145] op_sel_hi:[1,0]
	v_pk_mul_f32 v[46:47], v[46:47], v[144:145] op_sel_hi:[1,0]
	v_pk_fma_f32 v[32:33], v[80:81], v[32:33], v[96:97]
	v_pk_fma_f32 v[34:35], v[82:83], v[34:35], v[98:99]
	v_pk_fma_f32 v[36:37], v[84:85], v[36:37], v[100:101]
	v_pk_fma_f32 v[38:39], v[86:87], v[38:39], v[102:103]
	v_pk_fma_f32 v[40:41], v[88:89], v[40:41], v[104:105]
	v_pk_fma_f32 v[42:43], v[90:91], v[42:43], v[106:107]
	v_pk_fma_f32 v[44:45], v[92:93], v[44:45], v[108:109]
	v_pk_fma_f32 v[46:47], v[94:95], v[46:47], v[110:111]
	global_store_dwordx4 v[130:131], v[32:35], off
	global_store_dwordx4 v[130:131], v[36:39], off offset:1024
	global_store_dwordx4 v[130:131], v[40:43], off offset:2048
	global_store_dwordx4 v[130:131], v[44:47], off offset:3072
	v_lshl_add_u64 v[130:131], v[130:131], 0, v[152:153]
	global_load_dwordx4 v[32:35], v[128:129], off nt
	global_load_dwordx4 v[36:39], v[128:129], off offset:1024 nt
	global_load_dwordx4 v[40:43], v[128:129], off offset:2048 nt
	global_load_dwordx4 v[44:47], v[128:129], off offset:3072 nt
	v_lshl_add_u64 v[128:129], v[128:129], 0, v[152:153]
	s_cmp_lg_u32 s0, 2
	s_cbranch_scc1 .Lln1b_nopark
	v_lshl_add_u64 v[128:129], s[60:61], 0, v[148:149]
.Lln1b_nopark:
	s_waitcnt vmcnt(16)
	v_add_f32_e32 v112, v0, v1
	v_add_f32_e32 v113, v2, v3
	v_add_f32_e32 v114, v4, v5
	v_add_f32_e32 v115, v6, v7
	v_add_f32_e32 v116, v8, v9
	v_add_f32_e32 v117, v10, v11
	v_add_f32_e32 v118, v12, v13
	v_add_f32_e32 v119, v14, v15
	v_add_f32_e32 v112, v112, v116
	v_add_f32_e32 v113, v113, v117
	v_add_f32_e32 v114, v114, v118
	v_add_f32_e32 v115, v115, v119
	v_add_f32_e32 v112, v112, v113
	v_add_f32_e32 v114, v114, v115
	v_add_f32_e32 v112, v112, v114
	s_nop 1
	v_add_f32_dpp v112, v112, v112 quad_perm:[1,0,3,2] row_mask:0xf bank_mask:0xf
	s_nop 1
	v_add_f32_dpp v112, v112, v112 quad_perm:[2,3,0,1] row_mask:0xf bank_mask:0xf
	s_nop 1
	v_add_f32_dpp v112, v112, v112 row_half_mirror row_mask:0xf bank_mask:0xf
	s_nop 1
	v_add_f32_dpp v112, v112, v112 row_mirror row_mask:0xf bank_mask:0xf
	s_nop 1
	v_add_f32_dpp v112, v112, v112 row_bcast:15 row_mask:0xa bank_mask:0xf
	s_nop 1
	v_add_f32_dpp v112, v112, v112 row_bcast:31 row_mask:0xc bank_mask:0xf
	s_nop 1
	v_readlane_b32 s2, v112, 63
	s_nop 1
	v_fmac_f32_e32 v0, s2, v142
	v_fmac_f32_e32 v1, s2, v142
	v_fmac_f32_e32 v2, s2, v142
	v_fmac_f32_e32 v3, s2, v142
	v_fmac_f32_e32 v4, s2, v142
	v_fmac_f32_e32 v5, s2, v142
	v_fmac_f32_e32 v6, s2, v142
	v_fmac_f32_e32 v7, s2, v142
	v_fmac_f32_e32 v8, s2, v142
	v_fmac_f32_e32 v9, s2, v142
	v_fmac_f32_e32 v10, s2, v142
	v_fmac_f32_e32 v11, s2, v142
	v_fmac_f32_e32 v12, s2, v142
	v_fmac_f32_e32 v13, s2, v142
	v_fmac_f32_e32 v14, s2, v142
	v_fmac_f32_e32 v15, s2, v142
	v_mul_f32_e32 v112, v0, v0
	v_mul_f32_e32 v113, v1, v1
	v_mul_f32_e32 v114, v2, v2
	v_mul_f32_e32 v115, v3, v3
	v_fmac_f32_e32 v112, v4, v4
	v_fmac_f32_e32 v113, v5, v5
	v_fmac_f32_e32 v114, v6, v6
	v_fmac_f32_e32 v115, v7, v7
	v_fmac_f32_e32 v112, v8, v8
	v_fmac_f32_e32 v113, v9, v9
	v_fmac_f32_e32 v114, v10, v10
	v_fmac_f32_e32 v115, v11, v11
	v_fmac_f32_e32 v112, v12, v12
	v_fmac_f32_e32 v113, v13, v13
	v_fmac_f32_e32 v114, v14, v14
	v_fmac_f32_e32 v115, v15, v15
	v_add_f32_e32 v112, v112, v113
	v_add_f32_e32 v114, v114, v115
	v_add_f32_e32 v112, v112, v114
	s_nop 1
	v_add_f32_dpp v112, v112, v112 quad_perm:[1,0,3,2] row_mask:0xf bank_mask:0xf
	s_nop 1
	v_add_f32_dpp v112, v112, v112 quad_perm:[2,3,0,1] row_mask:0xf bank_mask:0xf
	s_nop 1
	v_add_f32_dpp v112, v112, v112 row_half_mirror row_mask:0xf bank_mask:0xf
	s_nop 1
	v_add_f32_dpp v112, v112, v112 row_mirror row_mask:0xf bank_mask:0xf
	s_nop 1
	v_add_f32_dpp v112, v112, v112 row_bcast:15 row_mask:0xa bank_mask:0xf
	s_nop 1
	v_add_f32_dpp v112, v112, v112 row_bcast:31 row_mask:0xc bank_mask:0xf
	s_nop 1
	v_readlane_b32 s2, v112, 63
	s_nop 1
	v_mov_b32_e32 v113, 0x358637bd
	v_mov_b32_e32 v114, 0x3a800000
	v_fmac_f32_e32 v113, s2, v114
	v_rsq_f32_e32 v115, v113
	v_mul_f32_e32 v113, 0.5, v113
	v_mul_f32_e32 v116, v115, v115
	v_mov_b32_e32 v117, 0x3fc00000
	v_fma_f32 v116, -v113, v116, v117
	v_mul_f32_e32 v144, v115, v116
	v_pk_mul_f32 v[0:1], v[0:1], v[144:145] op_sel_hi:[1,0]
	v_pk_mul_f32 v[2:3], v[2:3], v[144:145] op_sel_hi:[1,0]
	v_pk_mul_f32 v[4:5], v[4:5], v[144:145] op_sel_hi:[1,0]
	v_pk_mul_f32 v[6:7], v[6:7], v[144:145] op_sel_hi:[1,0]
	v_pk_mul_f32 v[8:9], v[8:9], v[144:145] op_sel_hi:[1,0]
	v_pk_mul_f32 v[10:11], v[10:11], v[144:145] op_sel_hi:[1,0]
	v_pk_mul_f32 v[12:13], v[12:13], v[144:145] op_sel_hi:[1,0]
	v_pk_mul_f32 v[14:15], v[14:15], v[144:145] op_sel_hi:[1,0]
	v_pk_fma_f32 v[0:1], v[80:81], v[0:1], v[96:97]
	v_pk_fma_f32 v[2:3], v[82:83], v[2:3], v[98:99]
	v_pk_fma_f32 v[4:5], v[84:85], v[4:5], v[100:101]
	v_pk_fma_f32 v[6:7], v[86:87], v[6:7], v[102:103]
	v_pk_fma_f32 v[8:9], v[88:89], v[8:9], v[104:105]
	v_pk_fma_f32 v[10:11], v[90:91], v[10:11], v[106:107]
	v_pk_fma_f32 v[12:13], v[92:93], v[12:13], v[108:109]
	v_pk_fma_f32 v[14:15], v[94:95], v[14:15], v[110:111]
	global_store_dwordx4 v[130:131], v[0:3], off
	global_store_dwordx4 v[130:131], v[4:7], off offset:1024
	global_store_dwordx4 v[130:131], v[8:11], off offset:2048
	global_store_dwordx4 v[130:131], v[12:15], off offset:3072
	v_lshl_add_u64 v[130:131], v[130:131], 0, v[152:153]
	global_load_dwordx4 v[0:3], v[128:129], off nt
	global_load_dwordx4 v[4:7], v[128:129], off offset:1024 nt
	global_load_dwordx4 v[8:11], v[128:129], off offset:2048 nt
	global_load_dwordx4 v[12:15], v[128:129], off offset:3072 nt
	v_lshl_add_u64 v[128:129], v[128:129], 0, v[152:153]
	s_waitcnt vmcnt(16)
	v_add_f32_e32 v112, v16, v17
	v_add_f32_e32 v113, v18, v19
	v_add_f32_e32 v114, v20, v21
	v_add_f32_e32 v115, v22, v23
	v_add_f32_e32 v116, v24, v25
	v_add_f32_e32 v117, v26, v27
	v_add_f32_e32 v118, v28, v29
	v_add_f32_e32 v119, v30, v31
	v_add_f32_e32 v112, v112, v116
	v_add_f32_e32 v113, v113, v117
	v_add_f32_e32 v114, v114, v118
	v_add_f32_e32 v115, v115, v119
	v_add_f32_e32 v112, v112, v113
	v_add_f32_e32 v114, v114, v115
	v_add_f32_e32 v112, v112, v114
	s_nop 1
	v_add_f32_dpp v112, v112, v112 quad_perm:[1,0,3,2] row_mask:0xf bank_mask:0xf
	s_nop 1
	v_add_f32_dpp v112, v112, v112 quad_perm:[2,3,0,1] row_mask:0xf bank_mask:0xf
	s_nop 1
	v_add_f32_dpp v112, v112, v112 row_half_mirror row_mask:0xf bank_mask:0xf
	s_nop 1
	v_add_f32_dpp v112, v112, v112 row_mirror row_mask:0xf bank_mask:0xf
	s_nop 1
	v_add_f32_dpp v112, v112, v112 row_bcast:15 row_mask:0xa bank_mask:0xf
	s_nop 1
	v_add_f32_dpp v112, v112, v112 row_bcast:31 row_mask:0xc bank_mask:0xf
	s_nop 1
	v_readlane_b32 s2, v112, 63
	s_nop 1
	v_fmac_f32_e32 v16, s2, v142
	v_fmac_f32_e32 v17, s2, v142
	v_fmac_f32_e32 v18, s2, v142
	v_fmac_f32_e32 v19, s2, v142
	v_fmac_f32_e32 v20, s2, v142
	v_fmac_f32_e32 v21, s2, v142
	v_fmac_f32_e32 v22, s2, v142
	v_fmac_f32_e32 v23, s2, v142
	v_fmac_f32_e32 v24, s2, v142
	v_fmac_f32_e32 v25, s2, v142
	v_fmac_f32_e32 v26, s2, v142
	v_fmac_f32_e32 v27, s2, v142
	v_fmac_f32_e32 v28, s2, v142
	v_fmac_f32_e32 v29, s2, v142
	v_fmac_f32_e32 v30, s2, v142
	v_fmac_f32_e32 v31, s2, v142
	v_mul_f32_e32 v112, v16, v16
	v_mul_f32_e32 v113, v17, v17
	v_mul_f32_e32 v114, v18, v18
	v_mul_f32_e32 v115, v19, v19
	v_fmac_f32_e32 v112, v20, v20
	v_fmac_f32_e32 v113, v21, v21
	v_fmac_f32_e32 v114, v22, v22
	v_fmac_f32_e32 v115, v23, v23
	v_fmac_f32_e32 v112, v24, v24
	v_fmac_f32_e32 v113, v25, v25
	v_fmac_f32_e32 v114, v26, v26
	v_fmac_f32_e32 v115, v27, v27
	v_fmac_f32_e32 v112, v28, v28
	v_fmac_f32_e32 v113, v29, v29
	v_fmac_f32_e32 v114, v30, v30
	v_fmac_f32_e32 v115, v31, v31
	v_add_f32_e32 v112, v112, v113
	v_add_f32_e32 v114, v114, v115
	v_add_f32_e32 v112, v112, v114
	s_nop 1
	v_add_f32_dpp v112, v112, v112 quad_perm:[1,0,3,2] row_mask:0xf bank_mask:0xf
	s_nop 1
	v_add_f32_dpp v112, v112, v112 quad_perm:[2,3,0,1] row_mask:0xf bank_mask:0xf
	s_nop 1
	v_add_f32_dpp v112, v112, v112 row_half_mirror row_mask:0xf bank_mask:0xf
	s_nop 1
	v_add_f32_dpp v112, v112, v112 row_mirror row_mask:0xf bank_mask:0xf
	s_nop 1
	v_add_f32_dpp v112, v112, v112 row_bcast:15 row_mask:0xa bank_mask:0xf
	s_nop 1
	v_add_f32_dpp v112, v112, v112 row_bcast:31 row_mask:0xc bank_mask:0xf
	s_nop 1
	v_readlane_b32 s2, v112, 63
	s_nop 1
	v_mov_b32_e32 v113, 0x358637bd
	v_mov_b32_e32 v114, 0x3a800000
	v_fmac_f32_e32 v113, s2, v114
	v_rsq_f32_e32 v115, v113
	v_mul_f32_e32 v113, 0.5, v113
	v_mul_f32_e32 v116, v115, v115
	v_mov_b32_e32 v117, 0x3fc00000
	v_fma_f32 v116, -v113, v116, v117
	v_mul_f32_e32 v144, v115, v116
	v_pk_mul_f32 v[16:17], v[16:17], v[144:145] op_sel_hi:[1,0]
	v_pk_mul_f32 v[18:19], v[18:19], v[144:145] op_sel_hi:[1,0]
	v_pk_mul_f32 v[20:21], v[20:21], v[144:145] op_sel_hi:[1,0]
	v_pk_mul_f32 v[22:23], v[22:23], v[144:145] op_sel_hi:[1,0]
	v_pk_mul_f32 v[24:25], v[24:25], v[144:145] op_sel_hi:[1,0]
	v_pk_mul_f32 v[26:27], v[26:27], v[144:145] op_sel_hi:[1,0]
	v_pk_mul_f32 v[28:29], v[28:29], v[144:145] op_sel_hi:[1,0]
	v_pk_mul_f32 v[30:31], v[30:31], v[144:145] op_sel_hi:[1,0]
	v_pk_fma_f32 v[16:17], v[80:81], v[16:17], v[96:97]
	v_pk_fma_f32 v[18:19], v[82:83], v[18:19], v[98:99]
	v_pk_fma_f32 v[20:21], v[84:85], v[20:21], v[100:101]
	v_pk_fma_f32 v[22:23], v[86:87], v[22:23], v[102:103]
	v_pk_fma_f32 v[24:25], v[88:89], v[24:25], v[104:105]
	v_pk_fma_f32 v[26:27], v[90:91], v[26:27], v[106:107]
	v_pk_fma_f32 v[28:29], v[92:93], v[28:29], v[108:109]
	v_pk_fma_f32 v[30:31], v[94:95], v[30:31], v[110:111]
	global_store_dwordx4 v[130:131], v[16:19], off
	global_store_dwordx4 v[130:131], v[20:23], off offset:1024
	global_store_dwordx4 v[130:131], v[24:27], off offset:2048
	global_store_dwordx4 v[130:131], v[28:31], off offset:3072
	v_lshl_add_u64 v[130:131], v[130:131], 0, v[152:153]
	global_load_dwordx4 v[16:19], v[128:129], off nt
	global_load_dwordx4 v[20:23], v[128:129], off offset:1024 nt
	global_load_dwordx4 v[24:27], v[128:129], off offset:2048 nt
	global_load_dwordx4 v[28:31], v[128:129], off offset:3072 nt
	v_lshl_add_u64 v[128:129], v[128:129], 0, v[152:153]
	s_waitcnt vmcnt(16)
	v_add_f32_e32 v112, v32, v33
	v_add_f32_e32 v113, v34, v35
	v_add_f32_e32 v114, v36, v37
	v_add_f32_e32 v115, v38, v39
	v_add_f32_e32 v116, v40, v41
	v_add_f32_e32 v117, v42, v43
	v_add_f32_e32 v118, v44, v45
	v_add_f32_e32 v119, v46, v47
	v_add_f32_e32 v112, v112, v116
	v_add_f32_e32 v113, v113, v117
	v_add_f32_e32 v114, v114, v118
	v_add_f32_e32 v115, v115, v119
	v_add_f32_e32 v112, v112, v113
	v_add_f32_e32 v114, v114, v115
	v_add_f32_e32 v112, v112, v114
	s_nop 1
	v_add_f32_dpp v112, v112, v112 quad_perm:[1,0,3,2] row_mask:0xf bank_mask:0xf
	s_nop 1
	v_add_f32_dpp v112, v112, v112 quad_perm:[2,3,0,1] row_mask:0xf bank_mask:0xf
	s_nop 1
	v_add_f32_dpp v112, v112, v112 row_half_mirror row_mask:0xf bank_mask:0xf
	s_nop 1
	v_add_f32_dpp v112, v112, v112 row_mirror row_mask:0xf bank_mask:0xf
	s_nop 1
	v_add_f32_dpp v112, v112, v112 row_bcast:15 row_mask:0xa bank_mask:0xf
	s_nop 1
	v_add_f32_dpp v112, v112, v112 row_bcast:31 row_mask:0xc bank_mask:0xf
	s_nop 1
	v_readlane_b32 s2, v112, 63
	s_nop 1
	v_fmac_f32_e32 v32, s2, v142
	v_fmac_f32_e32 v33, s2, v142
	v_fmac_f32_e32 v34, s2, v142
	v_fmac_f32_e32 v35, s2, v142
	v_fmac_f32_e32 v36, s2, v142
	v_fmac_f32_e32 v37, s2, v142
	v_fmac_f32_e32 v38, s2, v142
	v_fmac_f32_e32 v39, s2, v142
	v_fmac_f32_e32 v40, s2, v142
	v_fmac_f32_e32 v41, s2, v142
	v_fmac_f32_e32 v42, s2, v142
	v_fmac_f32_e32 v43, s2, v142
	v_fmac_f32_e32 v44, s2, v142
	v_fmac_f32_e32 v45, s2, v142
	v_fmac_f32_e32 v46, s2, v142
	v_fmac_f32_e32 v47, s2, v142
	v_mul_f32_e32 v112, v32, v32
	v_mul_f32_e32 v113, v33, v33
	v_mul_f32_e32 v114, v34, v34
	v_mul_f32_e32 v115, v35, v35
	v_fmac_f32_e32 v112, v36, v36
	v_fmac_f32_e32 v113, v37, v37
	v_fmac_f32_e32 v114, v38, v38
	v_fmac_f32_e32 v115, v39, v39
	v_fmac_f32_e32 v112, v40, v40
	v_fmac_f32_e32 v113, v41, v41
	v_fmac_f32_e32 v114, v42, v42
	v_fmac_f32_e32 v115, v43, v43
	v_fmac_f32_e32 v112, v44, v44
	v_fmac_f32_e32 v113, v45, v45
	v_fmac_f32_e32 v114, v46, v46
	v_fmac_f32_e32 v115, v47, v47
	v_add_f32_e32 v112, v112, v113
	v_add_f32_e32 v114, v114, v115
	v_add_f32_e32 v112, v112, v114
	s_nop 1
	v_add_f32_dpp v112, v112, v112 quad_perm:[1,0,3,2] row_mask:0xf bank_mask:0xf
	s_nop 1
	v_add_f32_dpp v112, v112, v112 quad_perm:[2,3,0,1] row_mask:0xf bank_mask:0xf
	s_nop 1
	v_add_f32_dpp v112, v112, v112 row_half_mirror row_mask:0xf bank_mask:0xf
	s_nop 1
	v_add_f32_dpp v112, v112, v112 row_mirror row_mask:0xf bank_mask:0xf
	s_nop 1
	v_add_f32_dpp v112, v112, v112 row_bcast:15 row_mask:0xa bank_mask:0xf
	s_nop 1
	v_add_f32_dpp v112, v112, v112 row_bcast:31 row_mask:0xc bank_mask:0xf
	s_nop 1
	v_readlane_b32 s2, v112, 63
	s_nop 1
	v_mov_b32_e32 v113, 0x358637bd
	v_mov_b32_e32 v114, 0x3a800000
	v_fmac_f32_e32 v113, s2, v114
	v_rsq_f32_e32 v115, v113
	v_mul_f32_e32 v113, 0.5, v113
	v_mul_f32_e32 v116, v115, v115
	v_mov_b32_e32 v117, 0x3fc00000
	v_fma_f32 v116, -v113, v116, v117
	v_mul_f32_e32 v144, v115, v116
	v_pk_mul_f32 v[32:33], v[32:33], v[144:145] op_sel_hi:[1,0]
	v_pk_mul_f32 v[34:35], v[34:35], v[144:145] op_sel_hi:[1,0]
	v_pk_mul_f32 v[36:37], v[36:37], v[144:145] op_sel_hi:[1,0]
	v_pk_mul_f32 v[38:39], v[38:39], v[144:145] op_sel_hi:[1,0]
	v_pk_mul_f32 v[40:41], v[40:41], v[144:145] op_sel_hi:[1,0]
	v_pk_mul_f32 v[42:43], v[42:43], v[144:145] op_sel_hi:[1,0]
	v_pk_mul_f32 v[44:45], v[44:45], v[144:145] op_sel_hi:[1,0]
	v_pk_mul_f32 v[46:47], v[46:47], v[144:145] op_sel_hi:[1,0]
	v_pk_fma_f32 v[32:33], v[80:81], v[32:33], v[96:97]
	v_pk_fma_f32 v[34:35], v[82:83], v[34:35], v[98:99]
	v_pk_fma_f32 v[36:37], v[84:85], v[36:37], v[100:101]
	v_pk_fma_f32 v[38:39], v[86:87], v[38:39], v[102:103]
	v_pk_fma_f32 v[40:41], v[88:89], v[40:41], v[104:105]
	v_pk_fma_f32 v[42:43], v[90:91], v[42:43], v[106:107]
	v_pk_fma_f32 v[44:45], v[92:93], v[44:45], v[108:109]
	v_pk_fma_f32 v[46:47], v[94:95], v[46:47], v[110:111]
	global_store_dwordx4 v[130:131], v[32:35], off
	global_store_dwordx4 v[130:131], v[36:39], off offset:1024
	global_store_dwordx4 v[130:131], v[40:43], off offset:2048
	global_store_dwordx4 v[130:131], v[44:47], off offset:3072
	v_lshl_add_u64 v[130:131], v[130:131], 0, v[152:153]
	s_add_i32 s0, s0, 1
	s_cmp_lt_i32 s0, 3
	s_cbranch_scc1 .Lln1b_loop
